# prep row phase: one 64-lane log-sigmoid pass after the last row instead of an 8-lane pass per row
# speedup vs baseline: 1.0091x; 1.0018x over previous
.LBB0_54:
	s_or_b64 exec, exec, s[0:1]
	s_movk_i32 s2, 0x4000
	v_cmp_gt_i32_e32 vcc, s2, v66
	v_mbcnt_lo_u32_b32 v1, -1, 0
	s_waitcnt lgkmcnt(0)
	s_barrier
	s_and_saveexec_b64 s[8:9], vcc
	s_cbranch_execz .LBB0_61
	v_mov_b32_e32 v250, v66
	v_mov_b32_e32 v251, v69
	v_lshlrev_b32_e32 v206, 4, v251
	v_add_u32_e32 v207, 0x1000, v206
	global_load_dwordx4 v[2:5], v206, s[14:15]
	global_load_dwordx4 v[6:9], v206, s[14:15] offset:1024
	global_load_dwordx4 v[10:13], v206, s[14:15] offset:2048
	global_load_dwordx4 v[14:17], v206, s[14:15] offset:3072
	global_load_dwordx4 v[18:21], v207, s[14:15]
	global_load_dwordx4 v[22:25], v207, s[14:15] offset:1024
	global_load_dwordx4 v[26:29], v207, s[14:15] offset:2048
	global_load_dwordx4 v[30:33], v207, s[14:15] offset:3072
	v_and_b32_e32 v222, 7, v251
	v_lshlrev_b32_e32 v222, 2, v222
	global_load_dword v196, v222, s[18:19]
	v_lshlrev_b32_e32 v193, 13, v250
	v_add_u32_e32 v193, v193, v206
	v_add_u32_e32 v193, 0x1000, v193
	v_lshlrev_b32_e32 v194, 12, v250
	v_lshl_add_u32 v194, v251, 3, v194
	v_lshlrev_b32_e32 v195, 2, v250
	v_lshl_add_u32 v195, v251, 15, v195
	v_add_u32_e32 v192, 16, v206
	v_xor_b32_e32 v186, 32, v251
	v_lshlrev_b32_e32 v186, 2, v186
	v_xor_b32_e32 v187, 16, v251
	v_lshlrev_b32_e32 v187, 2, v187
	v_xor_b32_e32 v188, 8, v251
	v_lshlrev_b32_e32 v188, 2, v188
	v_xor_b32_e32 v189, 4, v251
	v_lshlrev_b32_e32 v189, 2, v189
	v_xor_b32_e32 v190, 2, v251
	v_lshlrev_b32_e32 v190, 2, v190
	v_xor_b32_e32 v191, 1, v251
	v_lshlrev_b32_e32 v191, 2, v191
	v_mov_b32_e32 v241, 0x358637bd
	v_mov_b32_e32 v242, 0x3ecc95a3
	v_mov_b32_e32 v243, 0x7f800000
	v_mov_b32_e32 v244, 0x7fc00000
	v_mov_b32_e32 v245, 0xff800000
	s_mov_b32 s17, 0x800000
	s_mov_b32 s24, 0xbfb8aa3b
	s_mov_b32 s25, 0x3f2aaaab
	s_mov_b32 s28, 0x3f317218
	s_mov_b32 s29, 0x7f800000
	s_mov_b32 s30, 0x33800000
	s_mov_b32 s0, 0x1000000
	global_load_dwordx4 v[34:37], v193, s[12:13] offset:-4096 nt
	global_load_dwordx4 v[38:41], v193, s[12:13] offset:-3072 nt
	global_load_dwordx4 v[42:45], v193, s[12:13] offset:-2048 nt
	global_load_dwordx4 v[46:49], v193, s[12:13] offset:-1024 nt
	global_load_dwordx4 v[50:53], v193, s[12:13] offset:0 nt
	global_load_dwordx4 v[54:57], v193, s[12:13] offset:1024 nt
	global_load_dwordx4 v[58:61], v193, s[12:13] offset:2048 nt
	global_load_dwordx4 v[62:65], v193, s[12:13] offset:3072 nt
	v_add_u32_e32 v193, s0, v193
	global_load_dwordx4 v[66:69], v193, s[12:13] offset:-4096 nt
	global_load_dwordx4 v[70:73], v193, s[12:13] offset:-3072 nt
	global_load_dwordx4 v[74:77], v193, s[12:13] offset:-2048 nt
	global_load_dwordx4 v[78:81], v193, s[12:13] offset:-1024 nt
	global_load_dwordx4 v[82:85], v193, s[12:13] offset:0 nt
	global_load_dwordx4 v[86:89], v193, s[12:13] offset:1024 nt
	global_load_dwordx4 v[90:93], v193, s[12:13] offset:2048 nt
	global_load_dwordx4 v[94:97], v193, s[12:13] offset:3072 nt
	v_add_u32_e32 v193, s0, v193
	s_waitcnt vmcnt(8)
	v_pk_mul_f32 v[198:199], v[34:35], v[34:35]
	v_pk_mul_f32 v[200:201], v[36:37], v[36:37]
	v_pk_fma_f32 v[198:199], v[38:39], v[38:39], v[198:199]
	v_pk_fma_f32 v[200:201], v[40:41], v[40:41], v[200:201]
	v_pk_fma_f32 v[198:199], v[42:43], v[42:43], v[198:199]
	v_pk_fma_f32 v[200:201], v[44:45], v[44:45], v[200:201]
	v_pk_fma_f32 v[198:199], v[46:47], v[46:47], v[198:199]
	v_pk_fma_f32 v[200:201], v[48:49], v[48:49], v[200:201]
	v_pk_fma_f32 v[198:199], v[50:51], v[50:51], v[198:199]
	v_pk_fma_f32 v[200:201], v[52:53], v[52:53], v[200:201]
	v_pk_fma_f32 v[198:199], v[54:55], v[54:55], v[198:199]
	v_pk_fma_f32 v[200:201], v[56:57], v[56:57], v[200:201]
	v_pk_fma_f32 v[198:199], v[58:59], v[58:59], v[198:199]
	v_pk_fma_f32 v[200:201], v[60:61], v[60:61], v[200:201]
	v_pk_fma_f32 v[198:199], v[62:63], v[62:63], v[198:199]
	v_pk_fma_f32 v[200:201], v[64:65], v[64:65], v[200:201]
	v_pk_add_f32 v[198:199], v[198:199], v[200:201]
	v_add_f32_e32 v198, v198, v199
	s_nop 1
	v_add_f32_dpp v198, v198, v198 quad_perm:[1,0,3,2] row_mask:0xf bank_mask:0xf
	s_nop 1
	v_add_f32_dpp v198, v198, v198 quad_perm:[2,3,0,1] row_mask:0xf bank_mask:0xf
	s_nop 1
	v_add_f32_dpp v198, v198, v198 row_half_mirror row_mask:0xf bank_mask:0xf
	s_nop 1
	v_add_f32_dpp v198, v198, v198 row_mirror row_mask:0xf bank_mask:0xf
	v_mov_b32_e32 v199, v198
	s_nop 1
	v_permlane16_swap_b32 v199, v198
	v_add_f32_e32 v198, v198, v199
	v_mov_b32_e32 v199, v198
	s_nop 1
	v_permlane32_swap_b32 v199, v198
	v_add_f32_e32 v198, v198, v199
	ds_read_b128 v[130:133], v192
	ds_read_b128 v[134:137], v192 offset:1024
	ds_read_b128 v[138:141], v192 offset:2048
	ds_read_b128 v[142:145], v192 offset:3072
	ds_read_b128 v[146:149], v192 offset:4096
	ds_read_b128 v[150:153], v192 offset:5120
	ds_read_b128 v[154:157], v192 offset:6144
	ds_read_b128 v[158:161], v192 offset:7168
	v_fmamk_f32 v198, v198, 0x3a000000, v241
	v_mul_f32_e32 v199, 0x4b800000, v198
	v_cmp_gt_f32_e32 vcc, s17, v198
	s_nop 1
	v_cndmask_b32_e32 v198, v198, v199, vcc
	v_rsq_f32_e32 v198, v198
	s_nop 0
	v_mul_f32_e32 v199, 0x45800000, v198
	v_cndmask_b32_e32 v202, v198, v199, vcc
	v_pk_mul_f32 v[98:99], v[34:35], v[202:203] op_sel_hi:[1,0]
	v_pk_mul_f32 v[98:99], v[2:3], v[98:99]
	v_pk_mul_f32 v[100:101], v[36:37], v[202:203] op_sel_hi:[1,0]
	v_pk_mul_f32 v[100:101], v[4:5], v[100:101]
	v_cvt_pk_bf16_f32 v206, v98, v99
	v_cvt_pk_bf16_f32 v207, v100, v101
	global_store_dwordx2 v194, v[206:207], s[52:53]
	v_pk_mul_f32 v[102:103], v[38:39], v[202:203] op_sel_hi:[1,0]
	v_pk_mul_f32 v[102:103], v[6:7], v[102:103]
	v_pk_mul_f32 v[104:105], v[40:41], v[202:203] op_sel_hi:[1,0]
	v_pk_mul_f32 v[104:105], v[8:9], v[104:105]
	v_cvt_pk_bf16_f32 v206, v102, v103
	v_cvt_pk_bf16_f32 v207, v104, v105
	global_store_dwordx2 v194, v[206:207], s[52:53] offset:512
	v_pk_mul_f32 v[106:107], v[42:43], v[202:203] op_sel_hi:[1,0]
	v_pk_mul_f32 v[106:107], v[10:11], v[106:107]
	v_pk_mul_f32 v[108:109], v[44:45], v[202:203] op_sel_hi:[1,0]
	v_pk_mul_f32 v[108:109], v[12:13], v[108:109]
	v_cvt_pk_bf16_f32 v206, v106, v107
	v_cvt_pk_bf16_f32 v207, v108, v109
	global_store_dwordx2 v194, v[206:207], s[52:53] offset:1024
	v_pk_mul_f32 v[110:111], v[46:47], v[202:203] op_sel_hi:[1,0]
	v_pk_mul_f32 v[110:111], v[14:15], v[110:111]
	v_pk_mul_f32 v[112:113], v[48:49], v[202:203] op_sel_hi:[1,0]
	v_pk_mul_f32 v[112:113], v[16:17], v[112:113]
	v_cvt_pk_bf16_f32 v206, v110, v111
	v_cvt_pk_bf16_f32 v207, v112, v113
	global_store_dwordx2 v194, v[206:207], s[52:53] offset:1536
	v_pk_mul_f32 v[114:115], v[50:51], v[202:203] op_sel_hi:[1,0]
	v_pk_mul_f32 v[114:115], v[18:19], v[114:115]
	v_pk_mul_f32 v[116:117], v[52:53], v[202:203] op_sel_hi:[1,0]
	v_pk_mul_f32 v[116:117], v[20:21], v[116:117]
	v_cvt_pk_bf16_f32 v206, v114, v115
	v_cvt_pk_bf16_f32 v207, v116, v117
	global_store_dwordx2 v194, v[206:207], s[52:53] offset:2048
	v_pk_mul_f32 v[118:119], v[54:55], v[202:203] op_sel_hi:[1,0]
	v_pk_mul_f32 v[118:119], v[22:23], v[118:119]
	v_pk_mul_f32 v[120:121], v[56:57], v[202:203] op_sel_hi:[1,0]
	v_pk_mul_f32 v[120:121], v[24:25], v[120:121]
	v_cvt_pk_bf16_f32 v206, v118, v119
	v_cvt_pk_bf16_f32 v207, v120, v121
	global_store_dwordx2 v194, v[206:207], s[52:53] offset:2560
	v_pk_mul_f32 v[122:123], v[58:59], v[202:203] op_sel_hi:[1,0]
	v_pk_mul_f32 v[122:123], v[26:27], v[122:123]
	v_pk_mul_f32 v[124:125], v[60:61], v[202:203] op_sel_hi:[1,0]
	v_pk_mul_f32 v[124:125], v[28:29], v[124:125]
	v_cvt_pk_bf16_f32 v206, v122, v123
	v_cvt_pk_bf16_f32 v207, v124, v125
	global_store_dwordx2 v194, v[206:207], s[52:53] offset:3072
	v_pk_mul_f32 v[126:127], v[62:63], v[202:203] op_sel_hi:[1,0]
	v_pk_mul_f32 v[126:127], v[30:31], v[126:127]
	v_pk_mul_f32 v[128:129], v[64:65], v[202:203] op_sel_hi:[1,0]
	v_pk_mul_f32 v[128:129], v[32:33], v[128:129]
	v_cvt_pk_bf16_f32 v206, v126, v127
	v_cvt_pk_bf16_f32 v207, v128, v129
	global_store_dwordx2 v194, v[206:207], s[52:53] offset:3584
	v_add_u32_e32 v194, 0x800000, v194
	global_load_dwordx4 v[34:37], v193, s[12:13] offset:-4096 nt
	global_load_dwordx4 v[38:41], v193, s[12:13] offset:-3072 nt
	global_load_dwordx4 v[42:45], v193, s[12:13] offset:-2048 nt
	global_load_dwordx4 v[46:49], v193, s[12:13] offset:-1024 nt
	global_load_dwordx4 v[50:53], v193, s[12:13] offset:0 nt
	global_load_dwordx4 v[54:57], v193, s[12:13] offset:1024 nt
	global_load_dwordx4 v[58:61], v193, s[12:13] offset:2048 nt
	global_load_dwordx4 v[62:65], v193, s[12:13] offset:3072 nt
	v_add_u32_e32 v193, s0, v193
	s_waitcnt lgkmcnt(6)
	v_pk_mul_f32 v[162:163], v[130:131], v[98:99] op_sel_hi:[1,0]
	v_pk_mul_f32 v[164:165], v[132:133], v[98:99] op_sel_hi:[1,0]
	v_pk_mul_f32 v[166:167], v[134:135], v[98:99] op_sel_hi:[1,0]
	v_pk_mul_f32 v[168:169], v[136:137], v[98:99] op_sel_hi:[1,0]
	ds_read_b128 v[130:133], v192 offset:8192
	ds_read_b128 v[134:137], v192 offset:9216
	s_waitcnt lgkmcnt(6)
	v_pk_fma_f32 v[162:163], v[138:139], v[98:99], v[162:163] op_sel:[0,1,0] op_sel_hi:[1,1,1]
	v_pk_fma_f32 v[164:165], v[140:141], v[98:99], v[164:165] op_sel:[0,1,0] op_sel_hi:[1,1,1]
	v_pk_fma_f32 v[166:167], v[142:143], v[98:99], v[166:167] op_sel:[0,1,0] op_sel_hi:[1,1,1]
	v_pk_fma_f32 v[168:169], v[144:145], v[98:99], v[168:169] op_sel:[0,1,0] op_sel_hi:[1,1,1]
	ds_read_b128 v[138:141], v192 offset:10240
	ds_read_b128 v[142:145], v192 offset:11264
	s_waitcnt lgkmcnt(6)
	v_pk_fma_f32 v[162:163], v[146:147], v[100:101], v[162:163] op_sel_hi:[1,0,1]
	v_pk_fma_f32 v[164:165], v[148:149], v[100:101], v[164:165] op_sel_hi:[1,0,1]
	v_pk_fma_f32 v[166:167], v[150:151], v[100:101], v[166:167] op_sel_hi:[1,0,1]
	v_pk_fma_f32 v[168:169], v[152:153], v[100:101], v[168:169] op_sel_hi:[1,0,1]
	ds_read_b128 v[146:149], v192 offset:12288
	ds_read_b128 v[150:153], v192 offset:13312
	s_waitcnt lgkmcnt(6)
	v_pk_fma_f32 v[162:163], v[154:155], v[100:101], v[162:163] op_sel:[0,1,0] op_sel_hi:[1,1,1]
	v_pk_fma_f32 v[164:165], v[156:157], v[100:101], v[164:165] op_sel:[0,1,0] op_sel_hi:[1,1,1]
	v_pk_fma_f32 v[166:167], v[158:159], v[100:101], v[166:167] op_sel:[0,1,0] op_sel_hi:[1,1,1]
	v_pk_fma_f32 v[168:169], v[160:161], v[100:101], v[168:169] op_sel:[0,1,0] op_sel_hi:[1,1,1]
	ds_read_b128 v[154:157], v192 offset:14336
	ds_read_b128 v[158:161], v192 offset:15360
	s_waitcnt lgkmcnt(6)
	v_pk_fma_f32 v[162:163], v[130:131], v[102:103], v[162:163] op_sel_hi:[1,0,1]
	v_pk_fma_f32 v[164:165], v[132:133], v[102:103], v[164:165] op_sel_hi:[1,0,1]
	v_pk_fma_f32 v[166:167], v[134:135], v[102:103], v[166:167] op_sel_hi:[1,0,1]
	v_pk_fma_f32 v[168:169], v[136:137], v[102:103], v[168:169] op_sel_hi:[1,0,1]
	ds_read_b128 v[130:133], v192 offset:16384
	ds_read_b128 v[134:137], v192 offset:17408
	s_waitcnt lgkmcnt(6)
	v_pk_fma_f32 v[162:163], v[138:139], v[102:103], v[162:163] op_sel:[0,1,0] op_sel_hi:[1,1,1]
	v_pk_fma_f32 v[164:165], v[140:141], v[102:103], v[164:165] op_sel:[0,1,0] op_sel_hi:[1,1,1]
	v_pk_fma_f32 v[166:167], v[142:143], v[102:103], v[166:167] op_sel:[0,1,0] op_sel_hi:[1,1,1]
	v_pk_fma_f32 v[168:169], v[144:145], v[102:103], v[168:169] op_sel:[0,1,0] op_sel_hi:[1,1,1]
	ds_read_b128 v[138:141], v192 offset:18432
	ds_read_b128 v[142:145], v192 offset:19456
	s_waitcnt lgkmcnt(6)
	v_pk_fma_f32 v[162:163], v[146:147], v[104:105], v[162:163] op_sel_hi:[1,0,1]
	v_pk_fma_f32 v[164:165], v[148:149], v[104:105], v[164:165] op_sel_hi:[1,0,1]
	v_pk_fma_f32 v[166:167], v[150:151], v[104:105], v[166:167] op_sel_hi:[1,0,1]
	v_pk_fma_f32 v[168:169], v[152:153], v[104:105], v[168:169] op_sel_hi:[1,0,1]
	ds_read_b128 v[146:149], v192 offset:20480
	ds_read_b128 v[150:153], v192 offset:21504
	s_waitcnt lgkmcnt(6)
	v_pk_fma_f32 v[162:163], v[154:155], v[104:105], v[162:163] op_sel:[0,1,0] op_sel_hi:[1,1,1]
	v_pk_fma_f32 v[164:165], v[156:157], v[104:105], v[164:165] op_sel:[0,1,0] op_sel_hi:[1,1,1]
	v_pk_fma_f32 v[166:167], v[158:159], v[104:105], v[166:167] op_sel:[0,1,0] op_sel_hi:[1,1,1]
	v_pk_fma_f32 v[168:169], v[160:161], v[104:105], v[168:169] op_sel:[0,1,0] op_sel_hi:[1,1,1]
	ds_read_b128 v[154:157], v192 offset:22528
	ds_read_b128 v[158:161], v192 offset:23552
	s_waitcnt lgkmcnt(6)
	v_pk_fma_f32 v[162:163], v[130:131], v[106:107], v[162:163] op_sel_hi:[1,0,1]
	v_pk_fma_f32 v[164:165], v[132:133], v[106:107], v[164:165] op_sel_hi:[1,0,1]
	v_pk_fma_f32 v[166:167], v[134:135], v[106:107], v[166:167] op_sel_hi:[1,0,1]
	v_pk_fma_f32 v[168:169], v[136:137], v[106:107], v[168:169] op_sel_hi:[1,0,1]
	ds_read_b128 v[130:133], v192 offset:24576
	ds_read_b128 v[134:137], v192 offset:25600
	s_waitcnt lgkmcnt(6)
	v_pk_fma_f32 v[162:163], v[138:139], v[106:107], v[162:163] op_sel:[0,1,0] op_sel_hi:[1,1,1]
	v_pk_fma_f32 v[164:165], v[140:141], v[106:107], v[164:165] op_sel:[0,1,0] op_sel_hi:[1,1,1]
	v_pk_fma_f32 v[166:167], v[142:143], v[106:107], v[166:167] op_sel:[0,1,0] op_sel_hi:[1,1,1]
	v_pk_fma_f32 v[168:169], v[144:145], v[106:107], v[168:169] op_sel:[0,1,0] op_sel_hi:[1,1,1]
	ds_read_b128 v[138:141], v192 offset:26624
	ds_read_b128 v[142:145], v192 offset:27648
	s_waitcnt lgkmcnt(6)
	v_pk_fma_f32 v[162:163], v[146:147], v[108:109], v[162:163] op_sel_hi:[1,0,1]
	v_pk_fma_f32 v[164:165], v[148:149], v[108:109], v[164:165] op_sel_hi:[1,0,1]
	v_pk_fma_f32 v[166:167], v[150:151], v[108:109], v[166:167] op_sel_hi:[1,0,1]
	v_pk_fma_f32 v[168:169], v[152:153], v[108:109], v[168:169] op_sel_hi:[1,0,1]
	ds_read_b128 v[146:149], v192 offset:28672
	ds_read_b128 v[150:153], v192 offset:29696
	s_waitcnt lgkmcnt(6)
	v_pk_fma_f32 v[162:163], v[154:155], v[108:109], v[162:163] op_sel:[0,1,0] op_sel_hi:[1,1,1]
	v_pk_fma_f32 v[164:165], v[156:157], v[108:109], v[164:165] op_sel:[0,1,0] op_sel_hi:[1,1,1]
	v_pk_fma_f32 v[166:167], v[158:159], v[108:109], v[166:167] op_sel:[0,1,0] op_sel_hi:[1,1,1]
	v_pk_fma_f32 v[168:169], v[160:161], v[108:109], v[168:169] op_sel:[0,1,0] op_sel_hi:[1,1,1]
	ds_read_b128 v[154:157], v192 offset:30720
	ds_read_b128 v[158:161], v192 offset:31744
	s_waitcnt lgkmcnt(6)
	v_pk_fma_f32 v[162:163], v[130:131], v[110:111], v[162:163] op_sel_hi:[1,0,1]
	v_pk_fma_f32 v[164:165], v[132:133], v[110:111], v[164:165] op_sel_hi:[1,0,1]
	v_pk_fma_f32 v[166:167], v[134:135], v[110:111], v[166:167] op_sel_hi:[1,0,1]
	v_pk_fma_f32 v[168:169], v[136:137], v[110:111], v[168:169] op_sel_hi:[1,0,1]
	ds_read_b128 v[130:133], v192 offset:32768
	ds_read_b128 v[134:137], v192 offset:33792
	s_waitcnt lgkmcnt(6)
	v_pk_fma_f32 v[162:163], v[138:139], v[110:111], v[162:163] op_sel:[0,1,0] op_sel_hi:[1,1,1]
	v_pk_fma_f32 v[164:165], v[140:141], v[110:111], v[164:165] op_sel:[0,1,0] op_sel_hi:[1,1,1]
	v_pk_fma_f32 v[166:167], v[142:143], v[110:111], v[166:167] op_sel:[0,1,0] op_sel_hi:[1,1,1]
	v_pk_fma_f32 v[168:169], v[144:145], v[110:111], v[168:169] op_sel:[0,1,0] op_sel_hi:[1,1,1]
	ds_read_b128 v[138:141], v192 offset:34816
	ds_read_b128 v[142:145], v192 offset:35840
	s_waitcnt lgkmcnt(6)
	v_pk_fma_f32 v[162:163], v[146:147], v[112:113], v[162:163] op_sel_hi:[1,0,1]
	v_pk_fma_f32 v[164:165], v[148:149], v[112:113], v[164:165] op_sel_hi:[1,0,1]
	v_pk_fma_f32 v[166:167], v[150:151], v[112:113], v[166:167] op_sel_hi:[1,0,1]
	v_pk_fma_f32 v[168:169], v[152:153], v[112:113], v[168:169] op_sel_hi:[1,0,1]
	ds_read_b128 v[146:149], v192 offset:36864
	ds_read_b128 v[150:153], v192 offset:37888
	s_waitcnt lgkmcnt(6)
	v_pk_fma_f32 v[162:163], v[154:155], v[112:113], v[162:163] op_sel:[0,1,0] op_sel_hi:[1,1,1]
	v_pk_fma_f32 v[164:165], v[156:157], v[112:113], v[164:165] op_sel:[0,1,0] op_sel_hi:[1,1,1]
	v_pk_fma_f32 v[166:167], v[158:159], v[112:113], v[166:167] op_sel:[0,1,0] op_sel_hi:[1,1,1]
	v_pk_fma_f32 v[168:169], v[160:161], v[112:113], v[168:169] op_sel:[0,1,0] op_sel_hi:[1,1,1]
	ds_read_b128 v[154:157], v192 offset:38912
	ds_read_b128 v[158:161], v192 offset:39936
	s_waitcnt lgkmcnt(6)
	v_pk_fma_f32 v[162:163], v[130:131], v[114:115], v[162:163] op_sel_hi:[1,0,1]
	v_pk_fma_f32 v[164:165], v[132:133], v[114:115], v[164:165] op_sel_hi:[1,0,1]
	v_pk_fma_f32 v[166:167], v[134:135], v[114:115], v[166:167] op_sel_hi:[1,0,1]
	v_pk_fma_f32 v[168:169], v[136:137], v[114:115], v[168:169] op_sel_hi:[1,0,1]
	ds_read_b128 v[130:133], v192 offset:40960
	ds_read_b128 v[134:137], v192 offset:41984
	s_waitcnt lgkmcnt(6)
	v_pk_fma_f32 v[162:163], v[138:139], v[114:115], v[162:163] op_sel:[0,1,0] op_sel_hi:[1,1,1]
	v_pk_fma_f32 v[164:165], v[140:141], v[114:115], v[164:165] op_sel:[0,1,0] op_sel_hi:[1,1,1]
	v_pk_fma_f32 v[166:167], v[142:143], v[114:115], v[166:167] op_sel:[0,1,0] op_sel_hi:[1,1,1]
	v_pk_fma_f32 v[168:169], v[144:145], v[114:115], v[168:169] op_sel:[0,1,0] op_sel_hi:[1,1,1]
	ds_read_b128 v[138:141], v192 offset:43008
	ds_read_b128 v[142:145], v192 offset:44032
	s_waitcnt lgkmcnt(6)
	v_pk_fma_f32 v[162:163], v[146:147], v[116:117], v[162:163] op_sel_hi:[1,0,1]
	v_pk_fma_f32 v[164:165], v[148:149], v[116:117], v[164:165] op_sel_hi:[1,0,1]
	v_pk_fma_f32 v[166:167], v[150:151], v[116:117], v[166:167] op_sel_hi:[1,0,1]
	v_pk_fma_f32 v[168:169], v[152:153], v[116:117], v[168:169] op_sel_hi:[1,0,1]
	ds_read_b128 v[146:149], v192 offset:45056
	ds_read_b128 v[150:153], v192 offset:46080
	s_waitcnt lgkmcnt(6)
	v_pk_fma_f32 v[162:163], v[154:155], v[116:117], v[162:163] op_sel:[0,1,0] op_sel_hi:[1,1,1]
	v_pk_fma_f32 v[164:165], v[156:157], v[116:117], v[164:165] op_sel:[0,1,0] op_sel_hi:[1,1,1]
	v_pk_fma_f32 v[166:167], v[158:159], v[116:117], v[166:167] op_sel:[0,1,0] op_sel_hi:[1,1,1]
	v_pk_fma_f32 v[168:169], v[160:161], v[116:117], v[168:169] op_sel:[0,1,0] op_sel_hi:[1,1,1]
	ds_read_b128 v[154:157], v192 offset:47104
	ds_read_b128 v[158:161], v192 offset:48128
	s_waitcnt lgkmcnt(6)
	v_pk_fma_f32 v[162:163], v[130:131], v[118:119], v[162:163] op_sel_hi:[1,0,1]
	v_pk_fma_f32 v[164:165], v[132:133], v[118:119], v[164:165] op_sel_hi:[1,0,1]
	v_pk_fma_f32 v[166:167], v[134:135], v[118:119], v[166:167] op_sel_hi:[1,0,1]
	v_pk_fma_f32 v[168:169], v[136:137], v[118:119], v[168:169] op_sel_hi:[1,0,1]
	ds_read_b128 v[130:133], v192 offset:49152
	ds_read_b128 v[134:137], v192 offset:50176
	s_waitcnt lgkmcnt(6)
	v_pk_fma_f32 v[162:163], v[138:139], v[118:119], v[162:163] op_sel:[0,1,0] op_sel_hi:[1,1,1]
	v_pk_fma_f32 v[164:165], v[140:141], v[118:119], v[164:165] op_sel:[0,1,0] op_sel_hi:[1,1,1]
	v_pk_fma_f32 v[166:167], v[142:143], v[118:119], v[166:167] op_sel:[0,1,0] op_sel_hi:[1,1,1]
	v_pk_fma_f32 v[168:169], v[144:145], v[118:119], v[168:169] op_sel:[0,1,0] op_sel_hi:[1,1,1]
	ds_read_b128 v[138:141], v192 offset:51200
	ds_read_b128 v[142:145], v192 offset:52224
	s_waitcnt lgkmcnt(6)
	v_pk_fma_f32 v[162:163], v[146:147], v[120:121], v[162:163] op_sel_hi:[1,0,1]
	v_pk_fma_f32 v[164:165], v[148:149], v[120:121], v[164:165] op_sel_hi:[1,0,1]
	v_pk_fma_f32 v[166:167], v[150:151], v[120:121], v[166:167] op_sel_hi:[1,0,1]
	v_pk_fma_f32 v[168:169], v[152:153], v[120:121], v[168:169] op_sel_hi:[1,0,1]
	ds_read_b128 v[146:149], v192 offset:53248
	ds_read_b128 v[150:153], v192 offset:54272
	s_waitcnt lgkmcnt(6)
	v_pk_fma_f32 v[162:163], v[154:155], v[120:121], v[162:163] op_sel:[0,1,0] op_sel_hi:[1,1,1]
	v_pk_fma_f32 v[164:165], v[156:157], v[120:121], v[164:165] op_sel:[0,1,0] op_sel_hi:[1,1,1]
	v_pk_fma_f32 v[166:167], v[158:159], v[120:121], v[166:167] op_sel:[0,1,0] op_sel_hi:[1,1,1]
	v_pk_fma_f32 v[168:169], v[160:161], v[120:121], v[168:169] op_sel:[0,1,0] op_sel_hi:[1,1,1]
	ds_read_b128 v[154:157], v192 offset:55296
	ds_read_b128 v[158:161], v192 offset:56320
	s_waitcnt lgkmcnt(6)
	v_pk_fma_f32 v[162:163], v[130:131], v[122:123], v[162:163] op_sel_hi:[1,0,1]
	v_pk_fma_f32 v[164:165], v[132:133], v[122:123], v[164:165] op_sel_hi:[1,0,1]
	v_pk_fma_f32 v[166:167], v[134:135], v[122:123], v[166:167] op_sel_hi:[1,0,1]
	v_pk_fma_f32 v[168:169], v[136:137], v[122:123], v[168:169] op_sel_hi:[1,0,1]
	ds_read_b128 v[130:133], v192 offset:57344
	ds_read_b128 v[134:137], v192 offset:58368
	s_waitcnt lgkmcnt(6)
	v_pk_fma_f32 v[162:163], v[138:139], v[122:123], v[162:163] op_sel:[0,1,0] op_sel_hi:[1,1,1]
	v_pk_fma_f32 v[164:165], v[140:141], v[122:123], v[164:165] op_sel:[0,1,0] op_sel_hi:[1,1,1]
	v_pk_fma_f32 v[166:167], v[142:143], v[122:123], v[166:167] op_sel:[0,1,0] op_sel_hi:[1,1,1]
	v_pk_fma_f32 v[168:169], v[144:145], v[122:123], v[168:169] op_sel:[0,1,0] op_sel_hi:[1,1,1]
	ds_read_b128 v[138:141], v192 offset:59392
	ds_read_b128 v[142:145], v192 offset:60416
	s_waitcnt lgkmcnt(6)
	v_pk_fma_f32 v[162:163], v[146:147], v[124:125], v[162:163] op_sel_hi:[1,0,1]
	v_pk_fma_f32 v[164:165], v[148:149], v[124:125], v[164:165] op_sel_hi:[1,0,1]
	v_pk_fma_f32 v[166:167], v[150:151], v[124:125], v[166:167] op_sel_hi:[1,0,1]
	v_pk_fma_f32 v[168:169], v[152:153], v[124:125], v[168:169] op_sel_hi:[1,0,1]
	ds_read_b128 v[146:149], v192 offset:61440
	ds_read_b128 v[150:153], v192 offset:62464
	s_waitcnt lgkmcnt(6)
	v_pk_fma_f32 v[162:163], v[154:155], v[124:125], v[162:163] op_sel:[0,1,0] op_sel_hi:[1,1,1]
	v_pk_fma_f32 v[164:165], v[156:157], v[124:125], v[164:165] op_sel:[0,1,0] op_sel_hi:[1,1,1]
	v_pk_fma_f32 v[166:167], v[158:159], v[124:125], v[166:167] op_sel:[0,1,0] op_sel_hi:[1,1,1]
	v_pk_fma_f32 v[168:169], v[160:161], v[124:125], v[168:169] op_sel:[0,1,0] op_sel_hi:[1,1,1]
	ds_read_b128 v[154:157], v192 offset:63488
	ds_read_b128 v[158:161], v192 offset:64512
	s_waitcnt lgkmcnt(6)
	v_pk_fma_f32 v[162:163], v[130:131], v[126:127], v[162:163] op_sel_hi:[1,0,1]
	v_pk_fma_f32 v[164:165], v[132:133], v[126:127], v[164:165] op_sel_hi:[1,0,1]
	v_pk_fma_f32 v[166:167], v[134:135], v[126:127], v[166:167] op_sel_hi:[1,0,1]
	v_pk_fma_f32 v[168:169], v[136:137], v[126:127], v[168:169] op_sel_hi:[1,0,1]
	s_waitcnt lgkmcnt(4)
	v_pk_fma_f32 v[162:163], v[138:139], v[126:127], v[162:163] op_sel:[0,1,0] op_sel_hi:[1,1,1]
	v_pk_fma_f32 v[164:165], v[140:141], v[126:127], v[164:165] op_sel:[0,1,0] op_sel_hi:[1,1,1]
	v_pk_fma_f32 v[166:167], v[142:143], v[126:127], v[166:167] op_sel:[0,1,0] op_sel_hi:[1,1,1]
	v_pk_fma_f32 v[168:169], v[144:145], v[126:127], v[168:169] op_sel:[0,1,0] op_sel_hi:[1,1,1]
	s_waitcnt lgkmcnt(2)
	v_pk_fma_f32 v[162:163], v[146:147], v[128:129], v[162:163] op_sel_hi:[1,0,1]
	v_pk_fma_f32 v[164:165], v[148:149], v[128:129], v[164:165] op_sel_hi:[1,0,1]
	v_pk_fma_f32 v[166:167], v[150:151], v[128:129], v[166:167] op_sel_hi:[1,0,1]
	v_pk_fma_f32 v[168:169], v[152:153], v[128:129], v[168:169] op_sel_hi:[1,0,1]
	s_waitcnt lgkmcnt(0)
	v_pk_fma_f32 v[162:163], v[154:155], v[128:129], v[162:163] op_sel:[0,1,0] op_sel_hi:[1,1,1]
	v_pk_fma_f32 v[164:165], v[156:157], v[128:129], v[164:165] op_sel:[0,1,0] op_sel_hi:[1,1,1]
	v_pk_fma_f32 v[166:167], v[158:159], v[128:129], v[166:167] op_sel:[0,1,0] op_sel_hi:[1,1,1]
	v_pk_fma_f32 v[168:169], v[160:161], v[128:129], v[168:169] op_sel:[0,1,0] op_sel_hi:[1,1,1]
	s_nop 1
	v_add_f32_dpp v162, v162, v162 quad_perm:[1,0,3,2] row_mask:0xf bank_mask:0xf
	v_add_f32_dpp v163, v163, v163 quad_perm:[1,0,3,2] row_mask:0xf bank_mask:0xf
	v_add_f32_dpp v164, v164, v164 quad_perm:[1,0,3,2] row_mask:0xf bank_mask:0xf
	v_add_f32_dpp v165, v165, v165 quad_perm:[1,0,3,2] row_mask:0xf bank_mask:0xf
	v_add_f32_dpp v166, v166, v166 quad_perm:[1,0,3,2] row_mask:0xf bank_mask:0xf
	v_add_f32_dpp v167, v167, v167 quad_perm:[1,0,3,2] row_mask:0xf bank_mask:0xf
	v_add_f32_dpp v168, v168, v168 quad_perm:[1,0,3,2] row_mask:0xf bank_mask:0xf
	v_add_f32_dpp v169, v169, v169 quad_perm:[1,0,3,2] row_mask:0xf bank_mask:0xf
	v_add_f32_dpp v162, v162, v162 quad_perm:[2,3,0,1] row_mask:0xf bank_mask:0xf
	v_add_f32_dpp v163, v163, v163 quad_perm:[2,3,0,1] row_mask:0xf bank_mask:0xf
	v_add_f32_dpp v164, v164, v164 quad_perm:[2,3,0,1] row_mask:0xf bank_mask:0xf
	v_add_f32_dpp v165, v165, v165 quad_perm:[2,3,0,1] row_mask:0xf bank_mask:0xf
	v_add_f32_dpp v166, v166, v166 quad_perm:[2,3,0,1] row_mask:0xf bank_mask:0xf
	v_add_f32_dpp v167, v167, v167 quad_perm:[2,3,0,1] row_mask:0xf bank_mask:0xf
	v_add_f32_dpp v168, v168, v168 quad_perm:[2,3,0,1] row_mask:0xf bank_mask:0xf
	v_add_f32_dpp v169, v169, v169 quad_perm:[2,3,0,1] row_mask:0xf bank_mask:0xf
	v_add_f32_dpp v162, v162, v162 row_half_mirror row_mask:0xf bank_mask:0xf
	v_add_f32_dpp v163, v163, v163 row_half_mirror row_mask:0xf bank_mask:0xf
	v_add_f32_dpp v164, v164, v164 row_half_mirror row_mask:0xf bank_mask:0xf
	v_add_f32_dpp v165, v165, v165 row_half_mirror row_mask:0xf bank_mask:0xf
	v_add_f32_dpp v166, v166, v166 row_half_mirror row_mask:0xf bank_mask:0xf
	v_add_f32_dpp v167, v167, v167 row_half_mirror row_mask:0xf bank_mask:0xf
	v_add_f32_dpp v168, v168, v168 row_half_mirror row_mask:0xf bank_mask:0xf
	v_add_f32_dpp v169, v169, v169 row_half_mirror row_mask:0xf bank_mask:0xf
	v_add_f32_dpp v162, v162, v162 row_mirror row_mask:0xf bank_mask:0xf
	v_add_f32_dpp v163, v163, v163 row_mirror row_mask:0xf bank_mask:0xf
	v_add_f32_dpp v164, v164, v164 row_mirror row_mask:0xf bank_mask:0xf
	v_add_f32_dpp v165, v165, v165 row_mirror row_mask:0xf bank_mask:0xf
	v_add_f32_dpp v166, v166, v166 row_mirror row_mask:0xf bank_mask:0xf
	v_add_f32_dpp v167, v167, v167 row_mirror row_mask:0xf bank_mask:0xf
	v_add_f32_dpp v168, v168, v168 row_mirror row_mask:0xf bank_mask:0xf
	v_add_f32_dpp v169, v169, v169 row_mirror row_mask:0xf bank_mask:0xf
	v_mov_b32_e32 v170, v162
	v_mov_b32_e32 v171, v163
	v_mov_b32_e32 v172, v164
	v_mov_b32_e32 v173, v165
	v_mov_b32_e32 v174, v166
	v_mov_b32_e32 v175, v167
	v_mov_b32_e32 v176, v168
	v_mov_b32_e32 v177, v169
	v_permlane16_swap_b32 v170, v162
	v_permlane16_swap_b32 v171, v163
	v_permlane16_swap_b32 v172, v164
	v_permlane16_swap_b32 v173, v165
	v_permlane16_swap_b32 v174, v166
	v_permlane16_swap_b32 v175, v167
	v_permlane16_swap_b32 v176, v168
	v_permlane16_swap_b32 v177, v169
	v_add_f32_e32 v162, v162, v170
	v_add_f32_e32 v163, v163, v171
	v_add_f32_e32 v164, v164, v172
	v_add_f32_e32 v165, v165, v173
	v_add_f32_e32 v166, v166, v174
	v_add_f32_e32 v167, v167, v175
	v_add_f32_e32 v168, v168, v176
	v_add_f32_e32 v169, v169, v177
	v_mov_b32_e32 v170, v162
	v_mov_b32_e32 v171, v163
	v_mov_b32_e32 v172, v164
	v_mov_b32_e32 v173, v165
	v_mov_b32_e32 v174, v166
	v_mov_b32_e32 v175, v167
	v_mov_b32_e32 v176, v168
	v_mov_b32_e32 v177, v169
	v_permlane32_swap_b32 v170, v162
	v_permlane32_swap_b32 v171, v163
	v_permlane32_swap_b32 v172, v164
	v_permlane32_swap_b32 v173, v165
	v_permlane32_swap_b32 v174, v166
	v_permlane32_swap_b32 v175, v167
	v_permlane32_swap_b32 v176, v168
	v_permlane32_swap_b32 v177, v169
	v_add_f32_e32 v162, v162, v170
	v_add_f32_e32 v163, v163, v171
	v_add_f32_e32 v164, v164, v172
	v_add_f32_e32 v165, v165, v173
	v_add_f32_e32 v166, v166, v174
	v_add_f32_e32 v167, v167, v175
	v_add_f32_e32 v168, v168, v176
	v_add_f32_e32 v169, v169, v177
	v_readfirstlane_b32 s98, v162
	v_readfirstlane_b32 s99, v163
	v_readfirstlane_b32 s100, v164
	v_readfirstlane_b32 s101, v165
	v_writelane_b32 v230, s98, 0
	v_writelane_b32 v230, s99, 1
	v_writelane_b32 v230, s100, 2
	v_writelane_b32 v230, s101, 3
	v_readfirstlane_b32 s98, v166
	v_readfirstlane_b32 s99, v167
	v_readfirstlane_b32 s100, v168
	v_readfirstlane_b32 s101, v169
	v_writelane_b32 v230, s98, 4
	v_writelane_b32 v230, s99, 5
	v_writelane_b32 v230, s100, 6
	v_writelane_b32 v230, s101, 7
	s_waitcnt vmcnt(16)
	v_pk_mul_f32 v[198:199], v[66:67], v[66:67]
	v_pk_mul_f32 v[200:201], v[68:69], v[68:69]
	v_pk_fma_f32 v[198:199], v[70:71], v[70:71], v[198:199]
	v_pk_fma_f32 v[200:201], v[72:73], v[72:73], v[200:201]
	v_pk_fma_f32 v[198:199], v[74:75], v[74:75], v[198:199]
	v_pk_fma_f32 v[200:201], v[76:77], v[76:77], v[200:201]
	v_pk_fma_f32 v[198:199], v[78:79], v[78:79], v[198:199]
	v_pk_fma_f32 v[200:201], v[80:81], v[80:81], v[200:201]
	v_pk_fma_f32 v[198:199], v[82:83], v[82:83], v[198:199]
	v_pk_fma_f32 v[200:201], v[84:85], v[84:85], v[200:201]
	v_pk_fma_f32 v[198:199], v[86:87], v[86:87], v[198:199]
	v_pk_fma_f32 v[200:201], v[88:89], v[88:89], v[200:201]
	v_pk_fma_f32 v[198:199], v[90:91], v[90:91], v[198:199]
	v_pk_fma_f32 v[200:201], v[92:93], v[92:93], v[200:201]
	v_pk_fma_f32 v[198:199], v[94:95], v[94:95], v[198:199]
	v_pk_fma_f32 v[200:201], v[96:97], v[96:97], v[200:201]
	v_pk_add_f32 v[198:199], v[198:199], v[200:201]
	v_add_f32_e32 v198, v198, v199
	s_nop 1
	v_add_f32_dpp v198, v198, v198 quad_perm:[1,0,3,2] row_mask:0xf bank_mask:0xf
	s_nop 1
	v_add_f32_dpp v198, v198, v198 quad_perm:[2,3,0,1] row_mask:0xf bank_mask:0xf
	s_nop 1
	v_add_f32_dpp v198, v198, v198 row_half_mirror row_mask:0xf bank_mask:0xf
	s_nop 1
	v_add_f32_dpp v198, v198, v198 row_mirror row_mask:0xf bank_mask:0xf
	v_mov_b32_e32 v199, v198
	s_nop 1
	v_permlane16_swap_b32 v199, v198
	v_add_f32_e32 v198, v198, v199
	v_mov_b32_e32 v199, v198
	s_nop 1
	v_permlane32_swap_b32 v199, v198
	v_add_f32_e32 v198, v198, v199
	ds_read_b128 v[130:133], v192
	ds_read_b128 v[134:137], v192 offset:1024
	ds_read_b128 v[138:141], v192 offset:2048
	ds_read_b128 v[142:145], v192 offset:3072
	ds_read_b128 v[146:149], v192 offset:4096
	ds_read_b128 v[150:153], v192 offset:5120
	ds_read_b128 v[154:157], v192 offset:6144
	ds_read_b128 v[158:161], v192 offset:7168
	v_fmamk_f32 v198, v198, 0x3a000000, v241
	v_mul_f32_e32 v199, 0x4b800000, v198
	v_cmp_gt_f32_e32 vcc, s17, v198
	s_nop 1
	v_cndmask_b32_e32 v198, v198, v199, vcc
	v_rsq_f32_e32 v198, v198
	s_nop 0
	v_mul_f32_e32 v199, 0x45800000, v198
	v_cndmask_b32_e32 v202, v198, v199, vcc
	v_pk_mul_f32 v[98:99], v[66:67], v[202:203] op_sel_hi:[1,0]
	v_pk_mul_f32 v[98:99], v[2:3], v[98:99]
	v_pk_mul_f32 v[100:101], v[68:69], v[202:203] op_sel_hi:[1,0]
	v_pk_mul_f32 v[100:101], v[4:5], v[100:101]
	v_cvt_pk_bf16_f32 v206, v98, v99
	v_cvt_pk_bf16_f32 v207, v100, v101
	global_store_dwordx2 v194, v[206:207], s[52:53]
	v_pk_mul_f32 v[102:103], v[70:71], v[202:203] op_sel_hi:[1,0]
	v_pk_mul_f32 v[102:103], v[6:7], v[102:103]
	v_pk_mul_f32 v[104:105], v[72:73], v[202:203] op_sel_hi:[1,0]
	v_pk_mul_f32 v[104:105], v[8:9], v[104:105]
	v_cvt_pk_bf16_f32 v206, v102, v103
	v_cvt_pk_bf16_f32 v207, v104, v105
	global_store_dwordx2 v194, v[206:207], s[52:53] offset:512
	v_pk_mul_f32 v[106:107], v[74:75], v[202:203] op_sel_hi:[1,0]
	v_pk_mul_f32 v[106:107], v[10:11], v[106:107]
	v_pk_mul_f32 v[108:109], v[76:77], v[202:203] op_sel_hi:[1,0]
	v_pk_mul_f32 v[108:109], v[12:13], v[108:109]
	v_cvt_pk_bf16_f32 v206, v106, v107
	v_cvt_pk_bf16_f32 v207, v108, v109
	global_store_dwordx2 v194, v[206:207], s[52:53] offset:1024
	v_pk_mul_f32 v[110:111], v[78:79], v[202:203] op_sel_hi:[1,0]
	v_pk_mul_f32 v[110:111], v[14:15], v[110:111]
	v_pk_mul_f32 v[112:113], v[80:81], v[202:203] op_sel_hi:[1,0]
	v_pk_mul_f32 v[112:113], v[16:17], v[112:113]
	v_cvt_pk_bf16_f32 v206, v110, v111
	v_cvt_pk_bf16_f32 v207, v112, v113
	global_store_dwordx2 v194, v[206:207], s[52:53] offset:1536
	v_pk_mul_f32 v[114:115], v[82:83], v[202:203] op_sel_hi:[1,0]
	v_pk_mul_f32 v[114:115], v[18:19], v[114:115]
	v_pk_mul_f32 v[116:117], v[84:85], v[202:203] op_sel_hi:[1,0]
	v_pk_mul_f32 v[116:117], v[20:21], v[116:117]
	v_cvt_pk_bf16_f32 v206, v114, v115
	v_cvt_pk_bf16_f32 v207, v116, v117
	global_store_dwordx2 v194, v[206:207], s[52:53] offset:2048
	v_pk_mul_f32 v[118:119], v[86:87], v[202:203] op_sel_hi:[1,0]
	v_pk_mul_f32 v[118:119], v[22:23], v[118:119]
	v_pk_mul_f32 v[120:121], v[88:89], v[202:203] op_sel_hi:[1,0]
	v_pk_mul_f32 v[120:121], v[24:25], v[120:121]
	v_cvt_pk_bf16_f32 v206, v118, v119
	v_cvt_pk_bf16_f32 v207, v120, v121
	global_store_dwordx2 v194, v[206:207], s[52:53] offset:2560
	v_pk_mul_f32 v[122:123], v[90:91], v[202:203] op_sel_hi:[1,0]
	v_pk_mul_f32 v[122:123], v[26:27], v[122:123]
	v_pk_mul_f32 v[124:125], v[92:93], v[202:203] op_sel_hi:[1,0]
	v_pk_mul_f32 v[124:125], v[28:29], v[124:125]
	v_cvt_pk_bf16_f32 v206, v122, v123
	v_cvt_pk_bf16_f32 v207, v124, v125
	global_store_dwordx2 v194, v[206:207], s[52:53] offset:3072
	v_pk_mul_f32 v[126:127], v[94:95], v[202:203] op_sel_hi:[1,0]
	v_pk_mul_f32 v[126:127], v[30:31], v[126:127]
	v_pk_mul_f32 v[128:129], v[96:97], v[202:203] op_sel_hi:[1,0]
	v_pk_mul_f32 v[128:129], v[32:33], v[128:129]
	v_cvt_pk_bf16_f32 v206, v126, v127
	v_cvt_pk_bf16_f32 v207, v128, v129
	global_store_dwordx2 v194, v[206:207], s[52:53] offset:3584
	v_add_u32_e32 v194, 0x800000, v194
	global_load_dwordx4 v[66:69], v193, s[12:13] offset:-4096 nt
	global_load_dwordx4 v[70:73], v193, s[12:13] offset:-3072 nt
	global_load_dwordx4 v[74:77], v193, s[12:13] offset:-2048 nt
	global_load_dwordx4 v[78:81], v193, s[12:13] offset:-1024 nt
	global_load_dwordx4 v[82:85], v193, s[12:13] offset:0 nt
	global_load_dwordx4 v[86:89], v193, s[12:13] offset:1024 nt
	global_load_dwordx4 v[90:93], v193, s[12:13] offset:2048 nt
	global_load_dwordx4 v[94:97], v193, s[12:13] offset:3072 nt
	v_add_u32_e32 v193, s0, v193
	s_waitcnt lgkmcnt(6)
	v_pk_mul_f32 v[162:163], v[130:131], v[98:99] op_sel_hi:[1,0]
	v_pk_mul_f32 v[164:165], v[132:133], v[98:99] op_sel_hi:[1,0]
	v_pk_mul_f32 v[166:167], v[134:135], v[98:99] op_sel_hi:[1,0]
	v_pk_mul_f32 v[168:169], v[136:137], v[98:99] op_sel_hi:[1,0]
	ds_read_b128 v[130:133], v192 offset:8192
	ds_read_b128 v[134:137], v192 offset:9216
	s_waitcnt lgkmcnt(6)
	v_pk_fma_f32 v[162:163], v[138:139], v[98:99], v[162:163] op_sel:[0,1,0] op_sel_hi:[1,1,1]
	v_pk_fma_f32 v[164:165], v[140:141], v[98:99], v[164:165] op_sel:[0,1,0] op_sel_hi:[1,1,1]
	v_pk_fma_f32 v[166:167], v[142:143], v[98:99], v[166:167] op_sel:[0,1,0] op_sel_hi:[1,1,1]
	v_pk_fma_f32 v[168:169], v[144:145], v[98:99], v[168:169] op_sel:[0,1,0] op_sel_hi:[1,1,1]
	ds_read_b128 v[138:141], v192 offset:10240
	ds_read_b128 v[142:145], v192 offset:11264
	s_waitcnt lgkmcnt(6)
	v_pk_fma_f32 v[162:163], v[146:147], v[100:101], v[162:163] op_sel_hi:[1,0,1]
	v_pk_fma_f32 v[164:165], v[148:149], v[100:101], v[164:165] op_sel_hi:[1,0,1]
	v_pk_fma_f32 v[166:167], v[150:151], v[100:101], v[166:167] op_sel_hi:[1,0,1]
	v_pk_fma_f32 v[168:169], v[152:153], v[100:101], v[168:169] op_sel_hi:[1,0,1]
	ds_read_b128 v[146:149], v192 offset:12288
	ds_read_b128 v[150:153], v192 offset:13312
	s_waitcnt lgkmcnt(6)
	v_pk_fma_f32 v[162:163], v[154:155], v[100:101], v[162:163] op_sel:[0,1,0] op_sel_hi:[1,1,1]
	v_pk_fma_f32 v[164:165], v[156:157], v[100:101], v[164:165] op_sel:[0,1,0] op_sel_hi:[1,1,1]
	v_pk_fma_f32 v[166:167], v[158:159], v[100:101], v[166:167] op_sel:[0,1,0] op_sel_hi:[1,1,1]
	v_pk_fma_f32 v[168:169], v[160:161], v[100:101], v[168:169] op_sel:[0,1,0] op_sel_hi:[1,1,1]
	ds_read_b128 v[154:157], v192 offset:14336
	ds_read_b128 v[158:161], v192 offset:15360
	s_waitcnt lgkmcnt(6)
	v_pk_fma_f32 v[162:163], v[130:131], v[102:103], v[162:163] op_sel_hi:[1,0,1]
	v_pk_fma_f32 v[164:165], v[132:133], v[102:103], v[164:165] op_sel_hi:[1,0,1]
	v_pk_fma_f32 v[166:167], v[134:135], v[102:103], v[166:167] op_sel_hi:[1,0,1]
	v_pk_fma_f32 v[168:169], v[136:137], v[102:103], v[168:169] op_sel_hi:[1,0,1]
	ds_read_b128 v[130:133], v192 offset:16384
	ds_read_b128 v[134:137], v192 offset:17408
	s_waitcnt lgkmcnt(6)
	v_pk_fma_f32 v[162:163], v[138:139], v[102:103], v[162:163] op_sel:[0,1,0] op_sel_hi:[1,1,1]
	v_pk_fma_f32 v[164:165], v[140:141], v[102:103], v[164:165] op_sel:[0,1,0] op_sel_hi:[1,1,1]
	v_pk_fma_f32 v[166:167], v[142:143], v[102:103], v[166:167] op_sel:[0,1,0] op_sel_hi:[1,1,1]
	v_pk_fma_f32 v[168:169], v[144:145], v[102:103], v[168:169] op_sel:[0,1,0] op_sel_hi:[1,1,1]
	ds_read_b128 v[138:141], v192 offset:18432
	ds_read_b128 v[142:145], v192 offset:19456
	s_waitcnt lgkmcnt(6)
	v_pk_fma_f32 v[162:163], v[146:147], v[104:105], v[162:163] op_sel_hi:[1,0,1]
	v_pk_fma_f32 v[164:165], v[148:149], v[104:105], v[164:165] op_sel_hi:[1,0,1]
	v_pk_fma_f32 v[166:167], v[150:151], v[104:105], v[166:167] op_sel_hi:[1,0,1]
	v_pk_fma_f32 v[168:169], v[152:153], v[104:105], v[168:169] op_sel_hi:[1,0,1]
	ds_read_b128 v[146:149], v192 offset:20480
	ds_read_b128 v[150:153], v192 offset:21504
	s_waitcnt lgkmcnt(6)
	v_pk_fma_f32 v[162:163], v[154:155], v[104:105], v[162:163] op_sel:[0,1,0] op_sel_hi:[1,1,1]
	v_pk_fma_f32 v[164:165], v[156:157], v[104:105], v[164:165] op_sel:[0,1,0] op_sel_hi:[1,1,1]
	v_pk_fma_f32 v[166:167], v[158:159], v[104:105], v[166:167] op_sel:[0,1,0] op_sel_hi:[1,1,1]
	v_pk_fma_f32 v[168:169], v[160:161], v[104:105], v[168:169] op_sel:[0,1,0] op_sel_hi:[1,1,1]
	ds_read_b128 v[154:157], v192 offset:22528
	ds_read_b128 v[158:161], v192 offset:23552
	s_waitcnt lgkmcnt(6)
	v_pk_fma_f32 v[162:163], v[130:131], v[106:107], v[162:163] op_sel_hi:[1,0,1]
	v_pk_fma_f32 v[164:165], v[132:133], v[106:107], v[164:165] op_sel_hi:[1,0,1]
	v_pk_fma_f32 v[166:167], v[134:135], v[106:107], v[166:167] op_sel_hi:[1,0,1]
	v_pk_fma_f32 v[168:169], v[136:137], v[106:107], v[168:169] op_sel_hi:[1,0,1]
	ds_read_b128 v[130:133], v192 offset:24576
	ds_read_b128 v[134:137], v192 offset:25600
	s_waitcnt lgkmcnt(6)
	v_pk_fma_f32 v[162:163], v[138:139], v[106:107], v[162:163] op_sel:[0,1,0] op_sel_hi:[1,1,1]
	v_pk_fma_f32 v[164:165], v[140:141], v[106:107], v[164:165] op_sel:[0,1,0] op_sel_hi:[1,1,1]
	v_pk_fma_f32 v[166:167], v[142:143], v[106:107], v[166:167] op_sel:[0,1,0] op_sel_hi:[1,1,1]
	v_pk_fma_f32 v[168:169], v[144:145], v[106:107], v[168:169] op_sel:[0,1,0] op_sel_hi:[1,1,1]
	ds_read_b128 v[138:141], v192 offset:26624
	ds_read_b128 v[142:145], v192 offset:27648
	s_waitcnt lgkmcnt(6)
	v_pk_fma_f32 v[162:163], v[146:147], v[108:109], v[162:163] op_sel_hi:[1,0,1]
	v_pk_fma_f32 v[164:165], v[148:149], v[108:109], v[164:165] op_sel_hi:[1,0,1]
	v_pk_fma_f32 v[166:167], v[150:151], v[108:109], v[166:167] op_sel_hi:[1,0,1]
	v_pk_fma_f32 v[168:169], v[152:153], v[108:109], v[168:169] op_sel_hi:[1,0,1]
	ds_read_b128 v[146:149], v192 offset:28672
	ds_read_b128 v[150:153], v192 offset:29696
	s_waitcnt lgkmcnt(6)
	v_pk_fma_f32 v[162:163], v[154:155], v[108:109], v[162:163] op_sel:[0,1,0] op_sel_hi:[1,1,1]
	v_pk_fma_f32 v[164:165], v[156:157], v[108:109], v[164:165] op_sel:[0,1,0] op_sel_hi:[1,1,1]
	v_pk_fma_f32 v[166:167], v[158:159], v[108:109], v[166:167] op_sel:[0,1,0] op_sel_hi:[1,1,1]
	v_pk_fma_f32 v[168:169], v[160:161], v[108:109], v[168:169] op_sel:[0,1,0] op_sel_hi:[1,1,1]
	ds_read_b128 v[154:157], v192 offset:30720
	ds_read_b128 v[158:161], v192 offset:31744
	s_waitcnt lgkmcnt(6)
	v_pk_fma_f32 v[162:163], v[130:131], v[110:111], v[162:163] op_sel_hi:[1,0,1]
	v_pk_fma_f32 v[164:165], v[132:133], v[110:111], v[164:165] op_sel_hi:[1,0,1]
	v_pk_fma_f32 v[166:167], v[134:135], v[110:111], v[166:167] op_sel_hi:[1,0,1]
	v_pk_fma_f32 v[168:169], v[136:137], v[110:111], v[168:169] op_sel_hi:[1,0,1]
	ds_read_b128 v[130:133], v192 offset:32768
	ds_read_b128 v[134:137], v192 offset:33792
	s_waitcnt lgkmcnt(6)
	v_pk_fma_f32 v[162:163], v[138:139], v[110:111], v[162:163] op_sel:[0,1,0] op_sel_hi:[1,1,1]
	v_pk_fma_f32 v[164:165], v[140:141], v[110:111], v[164:165] op_sel:[0,1,0] op_sel_hi:[1,1,1]
	v_pk_fma_f32 v[166:167], v[142:143], v[110:111], v[166:167] op_sel:[0,1,0] op_sel_hi:[1,1,1]
	v_pk_fma_f32 v[168:169], v[144:145], v[110:111], v[168:169] op_sel:[0,1,0] op_sel_hi:[1,1,1]
	ds_read_b128 v[138:141], v192 offset:34816
	ds_read_b128 v[142:145], v192 offset:35840
	s_waitcnt lgkmcnt(6)
	v_pk_fma_f32 v[162:163], v[146:147], v[112:113], v[162:163] op_sel_hi:[1,0,1]
	v_pk_fma_f32 v[164:165], v[148:149], v[112:113], v[164:165] op_sel_hi:[1,0,1]
	v_pk_fma_f32 v[166:167], v[150:151], v[112:113], v[166:167] op_sel_hi:[1,0,1]
	v_pk_fma_f32 v[168:169], v[152:153], v[112:113], v[168:169] op_sel_hi:[1,0,1]
	ds_read_b128 v[146:149], v192 offset:36864
	ds_read_b128 v[150:153], v192 offset:37888
	s_waitcnt lgkmcnt(6)
	v_pk_fma_f32 v[162:163], v[154:155], v[112:113], v[162:163] op_sel:[0,1,0] op_sel_hi:[1,1,1]
	v_pk_fma_f32 v[164:165], v[156:157], v[112:113], v[164:165] op_sel:[0,1,0] op_sel_hi:[1,1,1]
	v_pk_fma_f32 v[166:167], v[158:159], v[112:113], v[166:167] op_sel:[0,1,0] op_sel_hi:[1,1,1]
	v_pk_fma_f32 v[168:169], v[160:161], v[112:113], v[168:169] op_sel:[0,1,0] op_sel_hi:[1,1,1]
	ds_read_b128 v[154:157], v192 offset:38912
	ds_read_b128 v[158:161], v192 offset:39936
	s_waitcnt lgkmcnt(6)
	v_pk_fma_f32 v[162:163], v[130:131], v[114:115], v[162:163] op_sel_hi:[1,0,1]
	v_pk_fma_f32 v[164:165], v[132:133], v[114:115], v[164:165] op_sel_hi:[1,0,1]
	v_pk_fma_f32 v[166:167], v[134:135], v[114:115], v[166:167] op_sel_hi:[1,0,1]
	v_pk_fma_f32 v[168:169], v[136:137], v[114:115], v[168:169] op_sel_hi:[1,0,1]
	ds_read_b128 v[130:133], v192 offset:40960
	ds_read_b128 v[134:137], v192 offset:41984
	s_waitcnt lgkmcnt(6)
	v_pk_fma_f32 v[162:163], v[138:139], v[114:115], v[162:163] op_sel:[0,1,0] op_sel_hi:[1,1,1]
	v_pk_fma_f32 v[164:165], v[140:141], v[114:115], v[164:165] op_sel:[0,1,0] op_sel_hi:[1,1,1]
	v_pk_fma_f32 v[166:167], v[142:143], v[114:115], v[166:167] op_sel:[0,1,0] op_sel_hi:[1,1,1]
	v_pk_fma_f32 v[168:169], v[144:145], v[114:115], v[168:169] op_sel:[0,1,0] op_sel_hi:[1,1,1]
	ds_read_b128 v[138:141], v192 offset:43008
	ds_read_b128 v[142:145], v192 offset:44032
	s_waitcnt lgkmcnt(6)
	v_pk_fma_f32 v[162:163], v[146:147], v[116:117], v[162:163] op_sel_hi:[1,0,1]
	v_pk_fma_f32 v[164:165], v[148:149], v[116:117], v[164:165] op_sel_hi:[1,0,1]
	v_pk_fma_f32 v[166:167], v[150:151], v[116:117], v[166:167] op_sel_hi:[1,0,1]
	v_pk_fma_f32 v[168:169], v[152:153], v[116:117], v[168:169] op_sel_hi:[1,0,1]
	ds_read_b128 v[146:149], v192 offset:45056
	ds_read_b128 v[150:153], v192 offset:46080
	s_waitcnt lgkmcnt(6)
	v_pk_fma_f32 v[162:163], v[154:155], v[116:117], v[162:163] op_sel:[0,1,0] op_sel_hi:[1,1,1]
	v_pk_fma_f32 v[164:165], v[156:157], v[116:117], v[164:165] op_sel:[0,1,0] op_sel_hi:[1,1,1]
	v_pk_fma_f32 v[166:167], v[158:159], v[116:117], v[166:167] op_sel:[0,1,0] op_sel_hi:[1,1,1]
	v_pk_fma_f32 v[168:169], v[160:161], v[116:117], v[168:169] op_sel:[0,1,0] op_sel_hi:[1,1,1]
	ds_read_b128 v[154:157], v192 offset:47104
	ds_read_b128 v[158:161], v192 offset:48128
	s_waitcnt lgkmcnt(6)
	v_pk_fma_f32 v[162:163], v[130:131], v[118:119], v[162:163] op_sel_hi:[1,0,1]
	v_pk_fma_f32 v[164:165], v[132:133], v[118:119], v[164:165] op_sel_hi:[1,0,1]
	v_pk_fma_f32 v[166:167], v[134:135], v[118:119], v[166:167] op_sel_hi:[1,0,1]
	v_pk_fma_f32 v[168:169], v[136:137], v[118:119], v[168:169] op_sel_hi:[1,0,1]
	ds_read_b128 v[130:133], v192 offset:49152
	ds_read_b128 v[134:137], v192 offset:50176
	s_waitcnt lgkmcnt(6)
	v_pk_fma_f32 v[162:163], v[138:139], v[118:119], v[162:163] op_sel:[0,1,0] op_sel_hi:[1,1,1]
	v_pk_fma_f32 v[164:165], v[140:141], v[118:119], v[164:165] op_sel:[0,1,0] op_sel_hi:[1,1,1]
	v_pk_fma_f32 v[166:167], v[142:143], v[118:119], v[166:167] op_sel:[0,1,0] op_sel_hi:[1,1,1]
	v_pk_fma_f32 v[168:169], v[144:145], v[118:119], v[168:169] op_sel:[0,1,0] op_sel_hi:[1,1,1]
	ds_read_b128 v[138:141], v192 offset:51200
	ds_read_b128 v[142:145], v192 offset:52224
	s_waitcnt lgkmcnt(6)
	v_pk_fma_f32 v[162:163], v[146:147], v[120:121], v[162:163] op_sel_hi:[1,0,1]
	v_pk_fma_f32 v[164:165], v[148:149], v[120:121], v[164:165] op_sel_hi:[1,0,1]
	v_pk_fma_f32 v[166:167], v[150:151], v[120:121], v[166:167] op_sel_hi:[1,0,1]
	v_pk_fma_f32 v[168:169], v[152:153], v[120:121], v[168:169] op_sel_hi:[1,0,1]
	ds_read_b128 v[146:149], v192 offset:53248
	ds_read_b128 v[150:153], v192 offset:54272
	s_waitcnt lgkmcnt(6)
	v_pk_fma_f32 v[162:163], v[154:155], v[120:121], v[162:163] op_sel:[0,1,0] op_sel_hi:[1,1,1]
	v_pk_fma_f32 v[164:165], v[156:157], v[120:121], v[164:165] op_sel:[0,1,0] op_sel_hi:[1,1,1]
	v_pk_fma_f32 v[166:167], v[158:159], v[120:121], v[166:167] op_sel:[0,1,0] op_sel_hi:[1,1,1]
	v_pk_fma_f32 v[168:169], v[160:161], v[120:121], v[168:169] op_sel:[0,1,0] op_sel_hi:[1,1,1]
	ds_read_b128 v[154:157], v192 offset:55296
	ds_read_b128 v[158:161], v192 offset:56320
	s_waitcnt lgkmcnt(6)
	v_pk_fma_f32 v[162:163], v[130:131], v[122:123], v[162:163] op_sel_hi:[1,0,1]
	v_pk_fma_f32 v[164:165], v[132:133], v[122:123], v[164:165] op_sel_hi:[1,0,1]
	v_pk_fma_f32 v[166:167], v[134:135], v[122:123], v[166:167] op_sel_hi:[1,0,1]
	v_pk_fma_f32 v[168:169], v[136:137], v[122:123], v[168:169] op_sel_hi:[1,0,1]
	ds_read_b128 v[130:133], v192 offset:57344
	ds_read_b128 v[134:137], v192 offset:58368
	s_waitcnt lgkmcnt(6)
	v_pk_fma_f32 v[162:163], v[138:139], v[122:123], v[162:163] op_sel:[0,1,0] op_sel_hi:[1,1,1]
	v_pk_fma_f32 v[164:165], v[140:141], v[122:123], v[164:165] op_sel:[0,1,0] op_sel_hi:[1,1,1]
	v_pk_fma_f32 v[166:167], v[142:143], v[122:123], v[166:167] op_sel:[0,1,0] op_sel_hi:[1,1,1]
	v_pk_fma_f32 v[168:169], v[144:145], v[122:123], v[168:169] op_sel:[0,1,0] op_sel_hi:[1,1,1]
	ds_read_b128 v[138:141], v192 offset:59392
	ds_read_b128 v[142:145], v192 offset:60416
	s_waitcnt lgkmcnt(6)
	v_pk_fma_f32 v[162:163], v[146:147], v[124:125], v[162:163] op_sel_hi:[1,0,1]
	v_pk_fma_f32 v[164:165], v[148:149], v[124:125], v[164:165] op_sel_hi:[1,0,1]
	v_pk_fma_f32 v[166:167], v[150:151], v[124:125], v[166:167] op_sel_hi:[1,0,1]
	v_pk_fma_f32 v[168:169], v[152:153], v[124:125], v[168:169] op_sel_hi:[1,0,1]
	ds_read_b128 v[146:149], v192 offset:61440
	ds_read_b128 v[150:153], v192 offset:62464
	s_waitcnt lgkmcnt(6)
	v_pk_fma_f32 v[162:163], v[154:155], v[124:125], v[162:163] op_sel:[0,1,0] op_sel_hi:[1,1,1]
	v_pk_fma_f32 v[164:165], v[156:157], v[124:125], v[164:165] op_sel:[0,1,0] op_sel_hi:[1,1,1]
	v_pk_fma_f32 v[166:167], v[158:159], v[124:125], v[166:167] op_sel:[0,1,0] op_sel_hi:[1,1,1]
	v_pk_fma_f32 v[168:169], v[160:161], v[124:125], v[168:169] op_sel:[0,1,0] op_sel_hi:[1,1,1]
	ds_read_b128 v[154:157], v192 offset:63488
	ds_read_b128 v[158:161], v192 offset:64512
	s_waitcnt lgkmcnt(6)
	v_pk_fma_f32 v[162:163], v[130:131], v[126:127], v[162:163] op_sel_hi:[1,0,1]
	v_pk_fma_f32 v[164:165], v[132:133], v[126:127], v[164:165] op_sel_hi:[1,0,1]
	v_pk_fma_f32 v[166:167], v[134:135], v[126:127], v[166:167] op_sel_hi:[1,0,1]
	v_pk_fma_f32 v[168:169], v[136:137], v[126:127], v[168:169] op_sel_hi:[1,0,1]
	s_waitcnt lgkmcnt(4)
	v_pk_fma_f32 v[162:163], v[138:139], v[126:127], v[162:163] op_sel:[0,1,0] op_sel_hi:[1,1,1]
	v_pk_fma_f32 v[164:165], v[140:141], v[126:127], v[164:165] op_sel:[0,1,0] op_sel_hi:[1,1,1]
	v_pk_fma_f32 v[166:167], v[142:143], v[126:127], v[166:167] op_sel:[0,1,0] op_sel_hi:[1,1,1]
	v_pk_fma_f32 v[168:169], v[144:145], v[126:127], v[168:169] op_sel:[0,1,0] op_sel_hi:[1,1,1]
	s_waitcnt lgkmcnt(2)
	v_pk_fma_f32 v[162:163], v[146:147], v[128:129], v[162:163] op_sel_hi:[1,0,1]
	v_pk_fma_f32 v[164:165], v[148:149], v[128:129], v[164:165] op_sel_hi:[1,0,1]
	v_pk_fma_f32 v[166:167], v[150:151], v[128:129], v[166:167] op_sel_hi:[1,0,1]
	v_pk_fma_f32 v[168:169], v[152:153], v[128:129], v[168:169] op_sel_hi:[1,0,1]
	s_waitcnt lgkmcnt(0)
	v_pk_fma_f32 v[162:163], v[154:155], v[128:129], v[162:163] op_sel:[0,1,0] op_sel_hi:[1,1,1]
	v_pk_fma_f32 v[164:165], v[156:157], v[128:129], v[164:165] op_sel:[0,1,0] op_sel_hi:[1,1,1]
	v_pk_fma_f32 v[166:167], v[158:159], v[128:129], v[166:167] op_sel:[0,1,0] op_sel_hi:[1,1,1]
	v_pk_fma_f32 v[168:169], v[160:161], v[128:129], v[168:169] op_sel:[0,1,0] op_sel_hi:[1,1,1]
	s_nop 1
	v_add_f32_dpp v162, v162, v162 quad_perm:[1,0,3,2] row_mask:0xf bank_mask:0xf
	v_add_f32_dpp v163, v163, v163 quad_perm:[1,0,3,2] row_mask:0xf bank_mask:0xf
	v_add_f32_dpp v164, v164, v164 quad_perm:[1,0,3,2] row_mask:0xf bank_mask:0xf
	v_add_f32_dpp v165, v165, v165 quad_perm:[1,0,3,2] row_mask:0xf bank_mask:0xf
	v_add_f32_dpp v166, v166, v166 quad_perm:[1,0,3,2] row_mask:0xf bank_mask:0xf
	v_add_f32_dpp v167, v167, v167 quad_perm:[1,0,3,2] row_mask:0xf bank_mask:0xf
	v_add_f32_dpp v168, v168, v168 quad_perm:[1,0,3,2] row_mask:0xf bank_mask:0xf
	v_add_f32_dpp v169, v169, v169 quad_perm:[1,0,3,2] row_mask:0xf bank_mask:0xf
	v_add_f32_dpp v162, v162, v162 quad_perm:[2,3,0,1] row_mask:0xf bank_mask:0xf
	v_add_f32_dpp v163, v163, v163 quad_perm:[2,3,0,1] row_mask:0xf bank_mask:0xf
	v_add_f32_dpp v164, v164, v164 quad_perm:[2,3,0,1] row_mask:0xf bank_mask:0xf
	v_add_f32_dpp v165, v165, v165 quad_perm:[2,3,0,1] row_mask:0xf bank_mask:0xf
	v_add_f32_dpp v166, v166, v166 quad_perm:[2,3,0,1] row_mask:0xf bank_mask:0xf
	v_add_f32_dpp v167, v167, v167 quad_perm:[2,3,0,1] row_mask:0xf bank_mask:0xf
	v_add_f32_dpp v168, v168, v168 quad_perm:[2,3,0,1] row_mask:0xf bank_mask:0xf
	v_add_f32_dpp v169, v169, v169 quad_perm:[2,3,0,1] row_mask:0xf bank_mask:0xf
	v_add_f32_dpp v162, v162, v162 row_half_mirror row_mask:0xf bank_mask:0xf
	v_add_f32_dpp v163, v163, v163 row_half_mirror row_mask:0xf bank_mask:0xf
	v_add_f32_dpp v164, v164, v164 row_half_mirror row_mask:0xf bank_mask:0xf
	v_add_f32_dpp v165, v165, v165 row_half_mirror row_mask:0xf bank_mask:0xf
	v_add_f32_dpp v166, v166, v166 row_half_mirror row_mask:0xf bank_mask:0xf
	v_add_f32_dpp v167, v167, v167 row_half_mirror row_mask:0xf bank_mask:0xf
	v_add_f32_dpp v168, v168, v168 row_half_mirror row_mask:0xf bank_mask:0xf
	v_add_f32_dpp v169, v169, v169 row_half_mirror row_mask:0xf bank_mask:0xf
	v_add_f32_dpp v162, v162, v162 row_mirror row_mask:0xf bank_mask:0xf
	v_add_f32_dpp v163, v163, v163 row_mirror row_mask:0xf bank_mask:0xf
	v_add_f32_dpp v164, v164, v164 row_mirror row_mask:0xf bank_mask:0xf
	v_add_f32_dpp v165, v165, v165 row_mirror row_mask:0xf bank_mask:0xf
	v_add_f32_dpp v166, v166, v166 row_mirror row_mask:0xf bank_mask:0xf
	v_add_f32_dpp v167, v167, v167 row_mirror row_mask:0xf bank_mask:0xf
	v_add_f32_dpp v168, v168, v168 row_mirror row_mask:0xf bank_mask:0xf
	v_add_f32_dpp v169, v169, v169 row_mirror row_mask:0xf bank_mask:0xf
	v_mov_b32_e32 v170, v162
	v_mov_b32_e32 v171, v163
	v_mov_b32_e32 v172, v164
	v_mov_b32_e32 v173, v165
	v_mov_b32_e32 v174, v166
	v_mov_b32_e32 v175, v167
	v_mov_b32_e32 v176, v168
	v_mov_b32_e32 v177, v169
	v_permlane16_swap_b32 v170, v162
	v_permlane16_swap_b32 v171, v163
	v_permlane16_swap_b32 v172, v164
	v_permlane16_swap_b32 v173, v165
	v_permlane16_swap_b32 v174, v166
	v_permlane16_swap_b32 v175, v167
	v_permlane16_swap_b32 v176, v168
	v_permlane16_swap_b32 v177, v169
	v_add_f32_e32 v162, v162, v170
	v_add_f32_e32 v163, v163, v171
	v_add_f32_e32 v164, v164, v172
	v_add_f32_e32 v165, v165, v173
	v_add_f32_e32 v166, v166, v174
	v_add_f32_e32 v167, v167, v175
	v_add_f32_e32 v168, v168, v176
	v_add_f32_e32 v169, v169, v177
	v_mov_b32_e32 v170, v162
	v_mov_b32_e32 v171, v163
	v_mov_b32_e32 v172, v164
	v_mov_b32_e32 v173, v165
	v_mov_b32_e32 v174, v166
	v_mov_b32_e32 v175, v167
	v_mov_b32_e32 v176, v168
	v_mov_b32_e32 v177, v169
	v_permlane32_swap_b32 v170, v162
	v_permlane32_swap_b32 v171, v163
	v_permlane32_swap_b32 v172, v164
	v_permlane32_swap_b32 v173, v165
	v_permlane32_swap_b32 v174, v166
	v_permlane32_swap_b32 v175, v167
	v_permlane32_swap_b32 v176, v168
	v_permlane32_swap_b32 v177, v169
	v_add_f32_e32 v162, v162, v170
	v_add_f32_e32 v163, v163, v171
	v_add_f32_e32 v164, v164, v172
	v_add_f32_e32 v165, v165, v173
	v_add_f32_e32 v166, v166, v174
	v_add_f32_e32 v167, v167, v175
	v_add_f32_e32 v168, v168, v176
	v_add_f32_e32 v169, v169, v177
	v_readfirstlane_b32 s98, v162
	v_readfirstlane_b32 s99, v163
	v_readfirstlane_b32 s100, v164
	v_readfirstlane_b32 s101, v165
	v_writelane_b32 v230, s98, 8
	v_writelane_b32 v230, s99, 9
	v_writelane_b32 v230, s100, 10
	v_writelane_b32 v230, s101, 11
	v_readfirstlane_b32 s98, v166
	v_readfirstlane_b32 s99, v167
	v_readfirstlane_b32 s100, v168
	v_readfirstlane_b32 s101, v169
	v_writelane_b32 v230, s98, 12
	v_writelane_b32 v230, s99, 13
	v_writelane_b32 v230, s100, 14
	v_writelane_b32 v230, s101, 15
	s_waitcnt vmcnt(16)
	v_pk_mul_f32 v[198:199], v[34:35], v[34:35]
	v_pk_mul_f32 v[200:201], v[36:37], v[36:37]
	v_pk_fma_f32 v[198:199], v[38:39], v[38:39], v[198:199]
	v_pk_fma_f32 v[200:201], v[40:41], v[40:41], v[200:201]
	v_pk_fma_f32 v[198:199], v[42:43], v[42:43], v[198:199]
	v_pk_fma_f32 v[200:201], v[44:45], v[44:45], v[200:201]
	v_pk_fma_f32 v[198:199], v[46:47], v[46:47], v[198:199]
	v_pk_fma_f32 v[200:201], v[48:49], v[48:49], v[200:201]
	v_pk_fma_f32 v[198:199], v[50:51], v[50:51], v[198:199]
	v_pk_fma_f32 v[200:201], v[52:53], v[52:53], v[200:201]
	v_pk_fma_f32 v[198:199], v[54:55], v[54:55], v[198:199]
	v_pk_fma_f32 v[200:201], v[56:57], v[56:57], v[200:201]
	v_pk_fma_f32 v[198:199], v[58:59], v[58:59], v[198:199]
	v_pk_fma_f32 v[200:201], v[60:61], v[60:61], v[200:201]
	v_pk_fma_f32 v[198:199], v[62:63], v[62:63], v[198:199]
	v_pk_fma_f32 v[200:201], v[64:65], v[64:65], v[200:201]
	v_pk_add_f32 v[198:199], v[198:199], v[200:201]
	v_add_f32_e32 v198, v198, v199
	s_nop 1
	v_add_f32_dpp v198, v198, v198 quad_perm:[1,0,3,2] row_mask:0xf bank_mask:0xf
	s_nop 1
	v_add_f32_dpp v198, v198, v198 quad_perm:[2,3,0,1] row_mask:0xf bank_mask:0xf
	s_nop 1
	v_add_f32_dpp v198, v198, v198 row_half_mirror row_mask:0xf bank_mask:0xf
	s_nop 1
	v_add_f32_dpp v198, v198, v198 row_mirror row_mask:0xf bank_mask:0xf
	v_mov_b32_e32 v199, v198
	s_nop 1
	v_permlane16_swap_b32 v199, v198
	v_add_f32_e32 v198, v198, v199
	v_mov_b32_e32 v199, v198
	s_nop 1
	v_permlane32_swap_b32 v199, v198
	v_add_f32_e32 v198, v198, v199
	ds_read_b128 v[130:133], v192
	ds_read_b128 v[134:137], v192 offset:1024
	ds_read_b128 v[138:141], v192 offset:2048
	ds_read_b128 v[142:145], v192 offset:3072
	ds_read_b128 v[146:149], v192 offset:4096
	ds_read_b128 v[150:153], v192 offset:5120
	ds_read_b128 v[154:157], v192 offset:6144
	ds_read_b128 v[158:161], v192 offset:7168
	v_fmamk_f32 v198, v198, 0x3a000000, v241
	v_mul_f32_e32 v199, 0x4b800000, v198
	v_cmp_gt_f32_e32 vcc, s17, v198
	s_nop 1
	v_cndmask_b32_e32 v198, v198, v199, vcc
	v_rsq_f32_e32 v198, v198
	s_nop 0
	v_mul_f32_e32 v199, 0x45800000, v198
	v_cndmask_b32_e32 v202, v198, v199, vcc
	v_pk_mul_f32 v[98:99], v[34:35], v[202:203] op_sel_hi:[1,0]
	v_pk_mul_f32 v[98:99], v[2:3], v[98:99]
	v_pk_mul_f32 v[100:101], v[36:37], v[202:203] op_sel_hi:[1,0]
	v_pk_mul_f32 v[100:101], v[4:5], v[100:101]
	v_cvt_pk_bf16_f32 v206, v98, v99
	v_cvt_pk_bf16_f32 v207, v100, v101
	global_store_dwordx2 v194, v[206:207], s[52:53]
	v_pk_mul_f32 v[102:103], v[38:39], v[202:203] op_sel_hi:[1,0]
	v_pk_mul_f32 v[102:103], v[6:7], v[102:103]
	v_pk_mul_f32 v[104:105], v[40:41], v[202:203] op_sel_hi:[1,0]
	v_pk_mul_f32 v[104:105], v[8:9], v[104:105]
	v_cvt_pk_bf16_f32 v206, v102, v103
	v_cvt_pk_bf16_f32 v207, v104, v105
	global_store_dwordx2 v194, v[206:207], s[52:53] offset:512
	v_pk_mul_f32 v[106:107], v[42:43], v[202:203] op_sel_hi:[1,0]
	v_pk_mul_f32 v[106:107], v[10:11], v[106:107]
	v_pk_mul_f32 v[108:109], v[44:45], v[202:203] op_sel_hi:[1,0]
	v_pk_mul_f32 v[108:109], v[12:13], v[108:109]
	v_cvt_pk_bf16_f32 v206, v106, v107
	v_cvt_pk_bf16_f32 v207, v108, v109
	global_store_dwordx2 v194, v[206:207], s[52:53] offset:1024
	v_pk_mul_f32 v[110:111], v[46:47], v[202:203] op_sel_hi:[1,0]
	v_pk_mul_f32 v[110:111], v[14:15], v[110:111]
	v_pk_mul_f32 v[112:113], v[48:49], v[202:203] op_sel_hi:[1,0]
	v_pk_mul_f32 v[112:113], v[16:17], v[112:113]
	v_cvt_pk_bf16_f32 v206, v110, v111
	v_cvt_pk_bf16_f32 v207, v112, v113
	global_store_dwordx2 v194, v[206:207], s[52:53] offset:1536
	v_pk_mul_f32 v[114:115], v[50:51], v[202:203] op_sel_hi:[1,0]
	v_pk_mul_f32 v[114:115], v[18:19], v[114:115]
	v_pk_mul_f32 v[116:117], v[52:53], v[202:203] op_sel_hi:[1,0]
	v_pk_mul_f32 v[116:117], v[20:21], v[116:117]
	v_cvt_pk_bf16_f32 v206, v114, v115
	v_cvt_pk_bf16_f32 v207, v116, v117
	global_store_dwordx2 v194, v[206:207], s[52:53] offset:2048
	v_pk_mul_f32 v[118:119], v[54:55], v[202:203] op_sel_hi:[1,0]
	v_pk_mul_f32 v[118:119], v[22:23], v[118:119]
	v_pk_mul_f32 v[120:121], v[56:57], v[202:203] op_sel_hi:[1,0]
	v_pk_mul_f32 v[120:121], v[24:25], v[120:121]
	v_cvt_pk_bf16_f32 v206, v118, v119
	v_cvt_pk_bf16_f32 v207, v120, v121
	global_store_dwordx2 v194, v[206:207], s[52:53] offset:2560
	v_pk_mul_f32 v[122:123], v[58:59], v[202:203] op_sel_hi:[1,0]
	v_pk_mul_f32 v[122:123], v[26:27], v[122:123]
	v_pk_mul_f32 v[124:125], v[60:61], v[202:203] op_sel_hi:[1,0]
	v_pk_mul_f32 v[124:125], v[28:29], v[124:125]
	v_cvt_pk_bf16_f32 v206, v122, v123
	v_cvt_pk_bf16_f32 v207, v124, v125
	global_store_dwordx2 v194, v[206:207], s[52:53] offset:3072
	v_pk_mul_f32 v[126:127], v[62:63], v[202:203] op_sel_hi:[1,0]
	v_pk_mul_f32 v[126:127], v[30:31], v[126:127]
	v_pk_mul_f32 v[128:129], v[64:65], v[202:203] op_sel_hi:[1,0]
	v_pk_mul_f32 v[128:129], v[32:33], v[128:129]
	v_cvt_pk_bf16_f32 v206, v126, v127
	v_cvt_pk_bf16_f32 v207, v128, v129
	global_store_dwordx2 v194, v[206:207], s[52:53] offset:3584
	v_add_u32_e32 v194, 0x800000, v194
	global_load_dwordx4 v[34:37], v193, s[12:13] offset:-4096 nt
	global_load_dwordx4 v[38:41], v193, s[12:13] offset:-3072 nt
	global_load_dwordx4 v[42:45], v193, s[12:13] offset:-2048 nt
	global_load_dwordx4 v[46:49], v193, s[12:13] offset:-1024 nt
	global_load_dwordx4 v[50:53], v193, s[12:13] offset:0 nt
	global_load_dwordx4 v[54:57], v193, s[12:13] offset:1024 nt
	global_load_dwordx4 v[58:61], v193, s[12:13] offset:2048 nt
	global_load_dwordx4 v[62:65], v193, s[12:13] offset:3072 nt
	v_add_u32_e32 v193, s0, v193
	s_waitcnt lgkmcnt(6)
	v_pk_mul_f32 v[162:163], v[130:131], v[98:99] op_sel_hi:[1,0]
	v_pk_mul_f32 v[164:165], v[132:133], v[98:99] op_sel_hi:[1,0]
	v_pk_mul_f32 v[166:167], v[134:135], v[98:99] op_sel_hi:[1,0]
	v_pk_mul_f32 v[168:169], v[136:137], v[98:99] op_sel_hi:[1,0]
	ds_read_b128 v[130:133], v192 offset:8192
	ds_read_b128 v[134:137], v192 offset:9216
	s_waitcnt lgkmcnt(6)
	v_pk_fma_f32 v[162:163], v[138:139], v[98:99], v[162:163] op_sel:[0,1,0] op_sel_hi:[1,1,1]
	v_pk_fma_f32 v[164:165], v[140:141], v[98:99], v[164:165] op_sel:[0,1,0] op_sel_hi:[1,1,1]
	v_pk_fma_f32 v[166:167], v[142:143], v[98:99], v[166:167] op_sel:[0,1,0] op_sel_hi:[1,1,1]
	v_pk_fma_f32 v[168:169], v[144:145], v[98:99], v[168:169] op_sel:[0,1,0] op_sel_hi:[1,1,1]
	ds_read_b128 v[138:141], v192 offset:10240
	ds_read_b128 v[142:145], v192 offset:11264
	s_waitcnt lgkmcnt(6)
	v_pk_fma_f32 v[162:163], v[146:147], v[100:101], v[162:163] op_sel_hi:[1,0,1]
	v_pk_fma_f32 v[164:165], v[148:149], v[100:101], v[164:165] op_sel_hi:[1,0,1]
	v_pk_fma_f32 v[166:167], v[150:151], v[100:101], v[166:167] op_sel_hi:[1,0,1]
	v_pk_fma_f32 v[168:169], v[152:153], v[100:101], v[168:169] op_sel_hi:[1,0,1]
	ds_read_b128 v[146:149], v192 offset:12288
	ds_read_b128 v[150:153], v192 offset:13312
	s_waitcnt lgkmcnt(6)
	v_pk_fma_f32 v[162:163], v[154:155], v[100:101], v[162:163] op_sel:[0,1,0] op_sel_hi:[1,1,1]
	v_pk_fma_f32 v[164:165], v[156:157], v[100:101], v[164:165] op_sel:[0,1,0] op_sel_hi:[1,1,1]
	v_pk_fma_f32 v[166:167], v[158:159], v[100:101], v[166:167] op_sel:[0,1,0] op_sel_hi:[1,1,1]
	v_pk_fma_f32 v[168:169], v[160:161], v[100:101], v[168:169] op_sel:[0,1,0] op_sel_hi:[1,1,1]
	ds_read_b128 v[154:157], v192 offset:14336
	ds_read_b128 v[158:161], v192 offset:15360
	s_waitcnt lgkmcnt(6)
	v_pk_fma_f32 v[162:163], v[130:131], v[102:103], v[162:163] op_sel_hi:[1,0,1]
	v_pk_fma_f32 v[164:165], v[132:133], v[102:103], v[164:165] op_sel_hi:[1,0,1]
	v_pk_fma_f32 v[166:167], v[134:135], v[102:103], v[166:167] op_sel_hi:[1,0,1]
	v_pk_fma_f32 v[168:169], v[136:137], v[102:103], v[168:169] op_sel_hi:[1,0,1]
	ds_read_b128 v[130:133], v192 offset:16384
	ds_read_b128 v[134:137], v192 offset:17408
	s_waitcnt lgkmcnt(6)
	v_pk_fma_f32 v[162:163], v[138:139], v[102:103], v[162:163] op_sel:[0,1,0] op_sel_hi:[1,1,1]
	v_pk_fma_f32 v[164:165], v[140:141], v[102:103], v[164:165] op_sel:[0,1,0] op_sel_hi:[1,1,1]
	v_pk_fma_f32 v[166:167], v[142:143], v[102:103], v[166:167] op_sel:[0,1,0] op_sel_hi:[1,1,1]
	v_pk_fma_f32 v[168:169], v[144:145], v[102:103], v[168:169] op_sel:[0,1,0] op_sel_hi:[1,1,1]
	ds_read_b128 v[138:141], v192 offset:18432
	ds_read_b128 v[142:145], v192 offset:19456
	s_waitcnt lgkmcnt(6)
	v_pk_fma_f32 v[162:163], v[146:147], v[104:105], v[162:163] op_sel_hi:[1,0,1]
	v_pk_fma_f32 v[164:165], v[148:149], v[104:105], v[164:165] op_sel_hi:[1,0,1]
	v_pk_fma_f32 v[166:167], v[150:151], v[104:105], v[166:167] op_sel_hi:[1,0,1]
	v_pk_fma_f32 v[168:169], v[152:153], v[104:105], v[168:169] op_sel_hi:[1,0,1]
	ds_read_b128 v[146:149], v192 offset:20480
	ds_read_b128 v[150:153], v192 offset:21504
	s_waitcnt lgkmcnt(6)
	v_pk_fma_f32 v[162:163], v[154:155], v[104:105], v[162:163] op_sel:[0,1,0] op_sel_hi:[1,1,1]
	v_pk_fma_f32 v[164:165], v[156:157], v[104:105], v[164:165] op_sel:[0,1,0] op_sel_hi:[1,1,1]
	v_pk_fma_f32 v[166:167], v[158:159], v[104:105], v[166:167] op_sel:[0,1,0] op_sel_hi:[1,1,1]
	v_pk_fma_f32 v[168:169], v[160:161], v[104:105], v[168:169] op_sel:[0,1,0] op_sel_hi:[1,1,1]
	ds_read_b128 v[154:157], v192 offset:22528
	ds_read_b128 v[158:161], v192 offset:23552
	s_waitcnt lgkmcnt(6)
	v_pk_fma_f32 v[162:163], v[130:131], v[106:107], v[162:163] op_sel_hi:[1,0,1]
	v_pk_fma_f32 v[164:165], v[132:133], v[106:107], v[164:165] op_sel_hi:[1,0,1]
	v_pk_fma_f32 v[166:167], v[134:135], v[106:107], v[166:167] op_sel_hi:[1,0,1]
	v_pk_fma_f32 v[168:169], v[136:137], v[106:107], v[168:169] op_sel_hi:[1,0,1]
	ds_read_b128 v[130:133], v192 offset:24576
	ds_read_b128 v[134:137], v192 offset:25600
	s_waitcnt lgkmcnt(6)
	v_pk_fma_f32 v[162:163], v[138:139], v[106:107], v[162:163] op_sel:[0,1,0] op_sel_hi:[1,1,1]
	v_pk_fma_f32 v[164:165], v[140:141], v[106:107], v[164:165] op_sel:[0,1,0] op_sel_hi:[1,1,1]
	v_pk_fma_f32 v[166:167], v[142:143], v[106:107], v[166:167] op_sel:[0,1,0] op_sel_hi:[1,1,1]
	v_pk_fma_f32 v[168:169], v[144:145], v[106:107], v[168:169] op_sel:[0,1,0] op_sel_hi:[1,1,1]
	ds_read_b128 v[138:141], v192 offset:26624
	ds_read_b128 v[142:145], v192 offset:27648
	s_waitcnt lgkmcnt(6)
	v_pk_fma_f32 v[162:163], v[146:147], v[108:109], v[162:163] op_sel_hi:[1,0,1]
	v_pk_fma_f32 v[164:165], v[148:149], v[108:109], v[164:165] op_sel_hi:[1,0,1]
	v_pk_fma_f32 v[166:167], v[150:151], v[108:109], v[166:167] op_sel_hi:[1,0,1]
	v_pk_fma_f32 v[168:169], v[152:153], v[108:109], v[168:169] op_sel_hi:[1,0,1]
	ds_read_b128 v[146:149], v192 offset:28672
	ds_read_b128 v[150:153], v192 offset:29696
	s_waitcnt lgkmcnt(6)
	v_pk_fma_f32 v[162:163], v[154:155], v[108:109], v[162:163] op_sel:[0,1,0] op_sel_hi:[1,1,1]
	v_pk_fma_f32 v[164:165], v[156:157], v[108:109], v[164:165] op_sel:[0,1,0] op_sel_hi:[1,1,1]
	v_pk_fma_f32 v[166:167], v[158:159], v[108:109], v[166:167] op_sel:[0,1,0] op_sel_hi:[1,1,1]
	v_pk_fma_f32 v[168:169], v[160:161], v[108:109], v[168:169] op_sel:[0,1,0] op_sel_hi:[1,1,1]
	ds_read_b128 v[154:157], v192 offset:30720
	ds_read_b128 v[158:161], v192 offset:31744
	s_waitcnt lgkmcnt(6)
	v_pk_fma_f32 v[162:163], v[130:131], v[110:111], v[162:163] op_sel_hi:[1,0,1]
	v_pk_fma_f32 v[164:165], v[132:133], v[110:111], v[164:165] op_sel_hi:[1,0,1]
	v_pk_fma_f32 v[166:167], v[134:135], v[110:111], v[166:167] op_sel_hi:[1,0,1]
	v_pk_fma_f32 v[168:169], v[136:137], v[110:111], v[168:169] op_sel_hi:[1,0,1]
	ds_read_b128 v[130:133], v192 offset:32768
	ds_read_b128 v[134:137], v192 offset:33792
	s_waitcnt lgkmcnt(6)
	v_pk_fma_f32 v[162:163], v[138:139], v[110:111], v[162:163] op_sel:[0,1,0] op_sel_hi:[1,1,1]
	v_pk_fma_f32 v[164:165], v[140:141], v[110:111], v[164:165] op_sel:[0,1,0] op_sel_hi:[1,1,1]
	v_pk_fma_f32 v[166:167], v[142:143], v[110:111], v[166:167] op_sel:[0,1,0] op_sel_hi:[1,1,1]
	v_pk_fma_f32 v[168:169], v[144:145], v[110:111], v[168:169] op_sel:[0,1,0] op_sel_hi:[1,1,1]
	ds_read_b128 v[138:141], v192 offset:34816
	ds_read_b128 v[142:145], v192 offset:35840
	s_waitcnt lgkmcnt(6)
	v_pk_fma_f32 v[162:163], v[146:147], v[112:113], v[162:163] op_sel_hi:[1,0,1]
	v_pk_fma_f32 v[164:165], v[148:149], v[112:113], v[164:165] op_sel_hi:[1,0,1]
	v_pk_fma_f32 v[166:167], v[150:151], v[112:113], v[166:167] op_sel_hi:[1,0,1]
	v_pk_fma_f32 v[168:169], v[152:153], v[112:113], v[168:169] op_sel_hi:[1,0,1]
	ds_read_b128 v[146:149], v192 offset:36864
	ds_read_b128 v[150:153], v192 offset:37888
	s_waitcnt lgkmcnt(6)
	v_pk_fma_f32 v[162:163], v[154:155], v[112:113], v[162:163] op_sel:[0,1,0] op_sel_hi:[1,1,1]
	v_pk_fma_f32 v[164:165], v[156:157], v[112:113], v[164:165] op_sel:[0,1,0] op_sel_hi:[1,1,1]
	v_pk_fma_f32 v[166:167], v[158:159], v[112:113], v[166:167] op_sel:[0,1,0] op_sel_hi:[1,1,1]
	v_pk_fma_f32 v[168:169], v[160:161], v[112:113], v[168:169] op_sel:[0,1,0] op_sel_hi:[1,1,1]
	ds_read_b128 v[154:157], v192 offset:38912
	ds_read_b128 v[158:161], v192 offset:39936
	s_waitcnt lgkmcnt(6)
	v_pk_fma_f32 v[162:163], v[130:131], v[114:115], v[162:163] op_sel_hi:[1,0,1]
	v_pk_fma_f32 v[164:165], v[132:133], v[114:115], v[164:165] op_sel_hi:[1,0,1]
	v_pk_fma_f32 v[166:167], v[134:135], v[114:115], v[166:167] op_sel_hi:[1,0,1]
	v_pk_fma_f32 v[168:169], v[136:137], v[114:115], v[168:169] op_sel_hi:[1,0,1]
	ds_read_b128 v[130:133], v192 offset:40960
	ds_read_b128 v[134:137], v192 offset:41984
	s_waitcnt lgkmcnt(6)
	v_pk_fma_f32 v[162:163], v[138:139], v[114:115], v[162:163] op_sel:[0,1,0] op_sel_hi:[1,1,1]
	v_pk_fma_f32 v[164:165], v[140:141], v[114:115], v[164:165] op_sel:[0,1,0] op_sel_hi:[1,1,1]
	v_pk_fma_f32 v[166:167], v[142:143], v[114:115], v[166:167] op_sel:[0,1,0] op_sel_hi:[1,1,1]
	v_pk_fma_f32 v[168:169], v[144:145], v[114:115], v[168:169] op_sel:[0,1,0] op_sel_hi:[1,1,1]
	ds_read_b128 v[138:141], v192 offset:43008
	ds_read_b128 v[142:145], v192 offset:44032
	s_waitcnt lgkmcnt(6)
	v_pk_fma_f32 v[162:163], v[146:147], v[116:117], v[162:163] op_sel_hi:[1,0,1]
	v_pk_fma_f32 v[164:165], v[148:149], v[116:117], v[164:165] op_sel_hi:[1,0,1]
	v_pk_fma_f32 v[166:167], v[150:151], v[116:117], v[166:167] op_sel_hi:[1,0,1]
	v_pk_fma_f32 v[168:169], v[152:153], v[116:117], v[168:169] op_sel_hi:[1,0,1]
	ds_read_b128 v[146:149], v192 offset:45056
	ds_read_b128 v[150:153], v192 offset:46080
	s_waitcnt lgkmcnt(6)
	v_pk_fma_f32 v[162:163], v[154:155], v[116:117], v[162:163] op_sel:[0,1,0] op_sel_hi:[1,1,1]
	v_pk_fma_f32 v[164:165], v[156:157], v[116:117], v[164:165] op_sel:[0,1,0] op_sel_hi:[1,1,1]
	v_pk_fma_f32 v[166:167], v[158:159], v[116:117], v[166:167] op_sel:[0,1,0] op_sel_hi:[1,1,1]
	v_pk_fma_f32 v[168:169], v[160:161], v[116:117], v[168:169] op_sel:[0,1,0] op_sel_hi:[1,1,1]
	ds_read_b128 v[154:157], v192 offset:47104
	ds_read_b128 v[158:161], v192 offset:48128
	s_waitcnt lgkmcnt(6)
	v_pk_fma_f32 v[162:163], v[130:131], v[118:119], v[162:163] op_sel_hi:[1,0,1]
	v_pk_fma_f32 v[164:165], v[132:133], v[118:119], v[164:165] op_sel_hi:[1,0,1]
	v_pk_fma_f32 v[166:167], v[134:135], v[118:119], v[166:167] op_sel_hi:[1,0,1]
	v_pk_fma_f32 v[168:169], v[136:137], v[118:119], v[168:169] op_sel_hi:[1,0,1]
	ds_read_b128 v[130:133], v192 offset:49152
	ds_read_b128 v[134:137], v192 offset:50176
	s_waitcnt lgkmcnt(6)
	v_pk_fma_f32 v[162:163], v[138:139], v[118:119], v[162:163] op_sel:[0,1,0] op_sel_hi:[1,1,1]
	v_pk_fma_f32 v[164:165], v[140:141], v[118:119], v[164:165] op_sel:[0,1,0] op_sel_hi:[1,1,1]
	v_pk_fma_f32 v[166:167], v[142:143], v[118:119], v[166:167] op_sel:[0,1,0] op_sel_hi:[1,1,1]
	v_pk_fma_f32 v[168:169], v[144:145], v[118:119], v[168:169] op_sel:[0,1,0] op_sel_hi:[1,1,1]
	ds_read_b128 v[138:141], v192 offset:51200
	ds_read_b128 v[142:145], v192 offset:52224
	s_waitcnt lgkmcnt(6)
	v_pk_fma_f32 v[162:163], v[146:147], v[120:121], v[162:163] op_sel_hi:[1,0,1]
	v_pk_fma_f32 v[164:165], v[148:149], v[120:121], v[164:165] op_sel_hi:[1,0,1]
	v_pk_fma_f32 v[166:167], v[150:151], v[120:121], v[166:167] op_sel_hi:[1,0,1]
	v_pk_fma_f32 v[168:169], v[152:153], v[120:121], v[168:169] op_sel_hi:[1,0,1]
	ds_read_b128 v[146:149], v192 offset:53248
	ds_read_b128 v[150:153], v192 offset:54272
	s_waitcnt lgkmcnt(6)
	v_pk_fma_f32 v[162:163], v[154:155], v[120:121], v[162:163] op_sel:[0,1,0] op_sel_hi:[1,1,1]
	v_pk_fma_f32 v[164:165], v[156:157], v[120:121], v[164:165] op_sel:[0,1,0] op_sel_hi:[1,1,1]
	v_pk_fma_f32 v[166:167], v[158:159], v[120:121], v[166:167] op_sel:[0,1,0] op_sel_hi:[1,1,1]
	v_pk_fma_f32 v[168:169], v[160:161], v[120:121], v[168:169] op_sel:[0,1,0] op_sel_hi:[1,1,1]
	ds_read_b128 v[154:157], v192 offset:55296
	ds_read_b128 v[158:161], v192 offset:56320
	s_waitcnt lgkmcnt(6)
	v_pk_fma_f32 v[162:163], v[130:131], v[122:123], v[162:163] op_sel_hi:[1,0,1]
	v_pk_fma_f32 v[164:165], v[132:133], v[122:123], v[164:165] op_sel_hi:[1,0,1]
	v_pk_fma_f32 v[166:167], v[134:135], v[122:123], v[166:167] op_sel_hi:[1,0,1]
	v_pk_fma_f32 v[168:169], v[136:137], v[122:123], v[168:169] op_sel_hi:[1,0,1]
	ds_read_b128 v[130:133], v192 offset:57344
	ds_read_b128 v[134:137], v192 offset:58368
	s_waitcnt lgkmcnt(6)
	v_pk_fma_f32 v[162:163], v[138:139], v[122:123], v[162:163] op_sel:[0,1,0] op_sel_hi:[1,1,1]
	v_pk_fma_f32 v[164:165], v[140:141], v[122:123], v[164:165] op_sel:[0,1,0] op_sel_hi:[1,1,1]
	v_pk_fma_f32 v[166:167], v[142:143], v[122:123], v[166:167] op_sel:[0,1,0] op_sel_hi:[1,1,1]
	v_pk_fma_f32 v[168:169], v[144:145], v[122:123], v[168:169] op_sel:[0,1,0] op_sel_hi:[1,1,1]
	ds_read_b128 v[138:141], v192 offset:59392
	ds_read_b128 v[142:145], v192 offset:60416
	s_waitcnt lgkmcnt(6)
	v_pk_fma_f32 v[162:163], v[146:147], v[124:125], v[162:163] op_sel_hi:[1,0,1]
	v_pk_fma_f32 v[164:165], v[148:149], v[124:125], v[164:165] op_sel_hi:[1,0,1]
	v_pk_fma_f32 v[166:167], v[150:151], v[124:125], v[166:167] op_sel_hi:[1,0,1]
	v_pk_fma_f32 v[168:169], v[152:153], v[124:125], v[168:169] op_sel_hi:[1,0,1]
	ds_read_b128 v[146:149], v192 offset:61440
	ds_read_b128 v[150:153], v192 offset:62464
	s_waitcnt lgkmcnt(6)
	v_pk_fma_f32 v[162:163], v[154:155], v[124:125], v[162:163] op_sel:[0,1,0] op_sel_hi:[1,1,1]
	v_pk_fma_f32 v[164:165], v[156:157], v[124:125], v[164:165] op_sel:[0,1,0] op_sel_hi:[1,1,1]
	v_pk_fma_f32 v[166:167], v[158:159], v[124:125], v[166:167] op_sel:[0,1,0] op_sel_hi:[1,1,1]
	v_pk_fma_f32 v[168:169], v[160:161], v[124:125], v[168:169] op_sel:[0,1,0] op_sel_hi:[1,1,1]
	ds_read_b128 v[154:157], v192 offset:63488
	ds_read_b128 v[158:161], v192 offset:64512
	s_waitcnt lgkmcnt(6)
	v_pk_fma_f32 v[162:163], v[130:131], v[126:127], v[162:163] op_sel_hi:[1,0,1]
	v_pk_fma_f32 v[164:165], v[132:133], v[126:127], v[164:165] op_sel_hi:[1,0,1]
	v_pk_fma_f32 v[166:167], v[134:135], v[126:127], v[166:167] op_sel_hi:[1,0,1]
	v_pk_fma_f32 v[168:169], v[136:137], v[126:127], v[168:169] op_sel_hi:[1,0,1]
	s_waitcnt lgkmcnt(4)
	v_pk_fma_f32 v[162:163], v[138:139], v[126:127], v[162:163] op_sel:[0,1,0] op_sel_hi:[1,1,1]
	v_pk_fma_f32 v[164:165], v[140:141], v[126:127], v[164:165] op_sel:[0,1,0] op_sel_hi:[1,1,1]
	v_pk_fma_f32 v[166:167], v[142:143], v[126:127], v[166:167] op_sel:[0,1,0] op_sel_hi:[1,1,1]
	v_pk_fma_f32 v[168:169], v[144:145], v[126:127], v[168:169] op_sel:[0,1,0] op_sel_hi:[1,1,1]
	s_waitcnt lgkmcnt(2)
	v_pk_fma_f32 v[162:163], v[146:147], v[128:129], v[162:163] op_sel_hi:[1,0,1]
	v_pk_fma_f32 v[164:165], v[148:149], v[128:129], v[164:165] op_sel_hi:[1,0,1]
	v_pk_fma_f32 v[166:167], v[150:151], v[128:129], v[166:167] op_sel_hi:[1,0,1]
	v_pk_fma_f32 v[168:169], v[152:153], v[128:129], v[168:169] op_sel_hi:[1,0,1]
	s_waitcnt lgkmcnt(0)
	v_pk_fma_f32 v[162:163], v[154:155], v[128:129], v[162:163] op_sel:[0,1,0] op_sel_hi:[1,1,1]
	v_pk_fma_f32 v[164:165], v[156:157], v[128:129], v[164:165] op_sel:[0,1,0] op_sel_hi:[1,1,1]
	v_pk_fma_f32 v[166:167], v[158:159], v[128:129], v[166:167] op_sel:[0,1,0] op_sel_hi:[1,1,1]
	v_pk_fma_f32 v[168:169], v[160:161], v[128:129], v[168:169] op_sel:[0,1,0] op_sel_hi:[1,1,1]
	s_nop 1
	v_add_f32_dpp v162, v162, v162 quad_perm:[1,0,3,2] row_mask:0xf bank_mask:0xf
	v_add_f32_dpp v163, v163, v163 quad_perm:[1,0,3,2] row_mask:0xf bank_mask:0xf
	v_add_f32_dpp v164, v164, v164 quad_perm:[1,0,3,2] row_mask:0xf bank_mask:0xf
	v_add_f32_dpp v165, v165, v165 quad_perm:[1,0,3,2] row_mask:0xf bank_mask:0xf
	v_add_f32_dpp v166, v166, v166 quad_perm:[1,0,3,2] row_mask:0xf bank_mask:0xf
	v_add_f32_dpp v167, v167, v167 quad_perm:[1,0,3,2] row_mask:0xf bank_mask:0xf
	v_add_f32_dpp v168, v168, v168 quad_perm:[1,0,3,2] row_mask:0xf bank_mask:0xf
	v_add_f32_dpp v169, v169, v169 quad_perm:[1,0,3,2] row_mask:0xf bank_mask:0xf
	v_add_f32_dpp v162, v162, v162 quad_perm:[2,3,0,1] row_mask:0xf bank_mask:0xf
	v_add_f32_dpp v163, v163, v163 quad_perm:[2,3,0,1] row_mask:0xf bank_mask:0xf
	v_add_f32_dpp v164, v164, v164 quad_perm:[2,3,0,1] row_mask:0xf bank_mask:0xf
	v_add_f32_dpp v165, v165, v165 quad_perm:[2,3,0,1] row_mask:0xf bank_mask:0xf
	v_add_f32_dpp v166, v166, v166 quad_perm:[2,3,0,1] row_mask:0xf bank_mask:0xf
	v_add_f32_dpp v167, v167, v167 quad_perm:[2,3,0,1] row_mask:0xf bank_mask:0xf
	v_add_f32_dpp v168, v168, v168 quad_perm:[2,3,0,1] row_mask:0xf bank_mask:0xf
	v_add_f32_dpp v169, v169, v169 quad_perm:[2,3,0,1] row_mask:0xf bank_mask:0xf
	v_add_f32_dpp v162, v162, v162 row_half_mirror row_mask:0xf bank_mask:0xf
	v_add_f32_dpp v163, v163, v163 row_half_mirror row_mask:0xf bank_mask:0xf
	v_add_f32_dpp v164, v164, v164 row_half_mirror row_mask:0xf bank_mask:0xf
	v_add_f32_dpp v165, v165, v165 row_half_mirror row_mask:0xf bank_mask:0xf
	v_add_f32_dpp v166, v166, v166 row_half_mirror row_mask:0xf bank_mask:0xf
	v_add_f32_dpp v167, v167, v167 row_half_mirror row_mask:0xf bank_mask:0xf
	v_add_f32_dpp v168, v168, v168 row_half_mirror row_mask:0xf bank_mask:0xf
	v_add_f32_dpp v169, v169, v169 row_half_mirror row_mask:0xf bank_mask:0xf
	v_add_f32_dpp v162, v162, v162 row_mirror row_mask:0xf bank_mask:0xf
	v_add_f32_dpp v163, v163, v163 row_mirror row_mask:0xf bank_mask:0xf
	v_add_f32_dpp v164, v164, v164 row_mirror row_mask:0xf bank_mask:0xf
	v_add_f32_dpp v165, v165, v165 row_mirror row_mask:0xf bank_mask:0xf
	v_add_f32_dpp v166, v166, v166 row_mirror row_mask:0xf bank_mask:0xf
	v_add_f32_dpp v167, v167, v167 row_mirror row_mask:0xf bank_mask:0xf
	v_add_f32_dpp v168, v168, v168 row_mirror row_mask:0xf bank_mask:0xf
	v_add_f32_dpp v169, v169, v169 row_mirror row_mask:0xf bank_mask:0xf
	v_mov_b32_e32 v170, v162
	v_mov_b32_e32 v171, v163
	v_mov_b32_e32 v172, v164
	v_mov_b32_e32 v173, v165
	v_mov_b32_e32 v174, v166
	v_mov_b32_e32 v175, v167
	v_mov_b32_e32 v176, v168
	v_mov_b32_e32 v177, v169
	v_permlane16_swap_b32 v170, v162
	v_permlane16_swap_b32 v171, v163
	v_permlane16_swap_b32 v172, v164
	v_permlane16_swap_b32 v173, v165
	v_permlane16_swap_b32 v174, v166
	v_permlane16_swap_b32 v175, v167
	v_permlane16_swap_b32 v176, v168
	v_permlane16_swap_b32 v177, v169
	v_add_f32_e32 v162, v162, v170
	v_add_f32_e32 v163, v163, v171
	v_add_f32_e32 v164, v164, v172
	v_add_f32_e32 v165, v165, v173
	v_add_f32_e32 v166, v166, v174
	v_add_f32_e32 v167, v167, v175
	v_add_f32_e32 v168, v168, v176
	v_add_f32_e32 v169, v169, v177
	v_mov_b32_e32 v170, v162
	v_mov_b32_e32 v171, v163
	v_mov_b32_e32 v172, v164
	v_mov_b32_e32 v173, v165
	v_mov_b32_e32 v174, v166
	v_mov_b32_e32 v175, v167
	v_mov_b32_e32 v176, v168
	v_mov_b32_e32 v177, v169
	v_permlane32_swap_b32 v170, v162
	v_permlane32_swap_b32 v171, v163
	v_permlane32_swap_b32 v172, v164
	v_permlane32_swap_b32 v173, v165
	v_permlane32_swap_b32 v174, v166
	v_permlane32_swap_b32 v175, v167
	v_permlane32_swap_b32 v176, v168
	v_permlane32_swap_b32 v177, v169
	v_add_f32_e32 v162, v162, v170
	v_add_f32_e32 v163, v163, v171
	v_add_f32_e32 v164, v164, v172
	v_add_f32_e32 v165, v165, v173
	v_add_f32_e32 v166, v166, v174
	v_add_f32_e32 v167, v167, v175
	v_add_f32_e32 v168, v168, v176
	v_add_f32_e32 v169, v169, v177
	v_readfirstlane_b32 s98, v162
	v_readfirstlane_b32 s99, v163
	v_readfirstlane_b32 s100, v164
	v_readfirstlane_b32 s101, v165
	v_writelane_b32 v230, s98, 16
	v_writelane_b32 v230, s99, 17
	v_writelane_b32 v230, s100, 18
	v_writelane_b32 v230, s101, 19
	v_readfirstlane_b32 s98, v166
	v_readfirstlane_b32 s99, v167
	v_readfirstlane_b32 s100, v168
	v_readfirstlane_b32 s101, v169
	v_writelane_b32 v230, s98, 20
	v_writelane_b32 v230, s99, 21
	v_writelane_b32 v230, s100, 22
	v_writelane_b32 v230, s101, 23
	s_waitcnt vmcnt(16)
	v_pk_mul_f32 v[198:199], v[66:67], v[66:67]
	v_pk_mul_f32 v[200:201], v[68:69], v[68:69]
	v_pk_fma_f32 v[198:199], v[70:71], v[70:71], v[198:199]
	v_pk_fma_f32 v[200:201], v[72:73], v[72:73], v[200:201]
	v_pk_fma_f32 v[198:199], v[74:75], v[74:75], v[198:199]
	v_pk_fma_f32 v[200:201], v[76:77], v[76:77], v[200:201]
	v_pk_fma_f32 v[198:199], v[78:79], v[78:79], v[198:199]
	v_pk_fma_f32 v[200:201], v[80:81], v[80:81], v[200:201]
	v_pk_fma_f32 v[198:199], v[82:83], v[82:83], v[198:199]
	v_pk_fma_f32 v[200:201], v[84:85], v[84:85], v[200:201]
	v_pk_fma_f32 v[198:199], v[86:87], v[86:87], v[198:199]
	v_pk_fma_f32 v[200:201], v[88:89], v[88:89], v[200:201]
	v_pk_fma_f32 v[198:199], v[90:91], v[90:91], v[198:199]
	v_pk_fma_f32 v[200:201], v[92:93], v[92:93], v[200:201]
	v_pk_fma_f32 v[198:199], v[94:95], v[94:95], v[198:199]
	v_pk_fma_f32 v[200:201], v[96:97], v[96:97], v[200:201]
	v_pk_add_f32 v[198:199], v[198:199], v[200:201]
	v_add_f32_e32 v198, v198, v199
	s_nop 1
	v_add_f32_dpp v198, v198, v198 quad_perm:[1,0,3,2] row_mask:0xf bank_mask:0xf
	s_nop 1
	v_add_f32_dpp v198, v198, v198 quad_perm:[2,3,0,1] row_mask:0xf bank_mask:0xf
	s_nop 1
	v_add_f32_dpp v198, v198, v198 row_half_mirror row_mask:0xf bank_mask:0xf
	s_nop 1
	v_add_f32_dpp v198, v198, v198 row_mirror row_mask:0xf bank_mask:0xf
	v_mov_b32_e32 v199, v198
	s_nop 1
	v_permlane16_swap_b32 v199, v198
	v_add_f32_e32 v198, v198, v199
	v_mov_b32_e32 v199, v198
	s_nop 1
	v_permlane32_swap_b32 v199, v198
	v_add_f32_e32 v198, v198, v199
	ds_read_b128 v[130:133], v192
	ds_read_b128 v[134:137], v192 offset:1024
	ds_read_b128 v[138:141], v192 offset:2048
	ds_read_b128 v[142:145], v192 offset:3072
	ds_read_b128 v[146:149], v192 offset:4096
	ds_read_b128 v[150:153], v192 offset:5120
	ds_read_b128 v[154:157], v192 offset:6144
	ds_read_b128 v[158:161], v192 offset:7168
	v_fmamk_f32 v198, v198, 0x3a000000, v241
	v_mul_f32_e32 v199, 0x4b800000, v198
	v_cmp_gt_f32_e32 vcc, s17, v198
	s_nop 1
	v_cndmask_b32_e32 v198, v198, v199, vcc
	v_rsq_f32_e32 v198, v198
	s_nop 0
	v_mul_f32_e32 v199, 0x45800000, v198
	v_cndmask_b32_e32 v202, v198, v199, vcc
	v_pk_mul_f32 v[98:99], v[66:67], v[202:203] op_sel_hi:[1,0]
	v_pk_mul_f32 v[98:99], v[2:3], v[98:99]
	v_pk_mul_f32 v[100:101], v[68:69], v[202:203] op_sel_hi:[1,0]
	v_pk_mul_f32 v[100:101], v[4:5], v[100:101]
	v_cvt_pk_bf16_f32 v206, v98, v99
	v_cvt_pk_bf16_f32 v207, v100, v101
	global_store_dwordx2 v194, v[206:207], s[52:53]
	v_pk_mul_f32 v[102:103], v[70:71], v[202:203] op_sel_hi:[1,0]
	v_pk_mul_f32 v[102:103], v[6:7], v[102:103]
	v_pk_mul_f32 v[104:105], v[72:73], v[202:203] op_sel_hi:[1,0]
	v_pk_mul_f32 v[104:105], v[8:9], v[104:105]
	v_cvt_pk_bf16_f32 v206, v102, v103
	v_cvt_pk_bf16_f32 v207, v104, v105
	global_store_dwordx2 v194, v[206:207], s[52:53] offset:512
	v_pk_mul_f32 v[106:107], v[74:75], v[202:203] op_sel_hi:[1,0]
	v_pk_mul_f32 v[106:107], v[10:11], v[106:107]
	v_pk_mul_f32 v[108:109], v[76:77], v[202:203] op_sel_hi:[1,0]
	v_pk_mul_f32 v[108:109], v[12:13], v[108:109]
	v_cvt_pk_bf16_f32 v206, v106, v107
	v_cvt_pk_bf16_f32 v207, v108, v109
	global_store_dwordx2 v194, v[206:207], s[52:53] offset:1024
	v_pk_mul_f32 v[110:111], v[78:79], v[202:203] op_sel_hi:[1,0]
	v_pk_mul_f32 v[110:111], v[14:15], v[110:111]
	v_pk_mul_f32 v[112:113], v[80:81], v[202:203] op_sel_hi:[1,0]
	v_pk_mul_f32 v[112:113], v[16:17], v[112:113]
	v_cvt_pk_bf16_f32 v206, v110, v111
	v_cvt_pk_bf16_f32 v207, v112, v113
	global_store_dwordx2 v194, v[206:207], s[52:53] offset:1536
	v_pk_mul_f32 v[114:115], v[82:83], v[202:203] op_sel_hi:[1,0]
	v_pk_mul_f32 v[114:115], v[18:19], v[114:115]
	v_pk_mul_f32 v[116:117], v[84:85], v[202:203] op_sel_hi:[1,0]
	v_pk_mul_f32 v[116:117], v[20:21], v[116:117]
	v_cvt_pk_bf16_f32 v206, v114, v115
	v_cvt_pk_bf16_f32 v207, v116, v117
	global_store_dwordx2 v194, v[206:207], s[52:53] offset:2048
	v_pk_mul_f32 v[118:119], v[86:87], v[202:203] op_sel_hi:[1,0]
	v_pk_mul_f32 v[118:119], v[22:23], v[118:119]
	v_pk_mul_f32 v[120:121], v[88:89], v[202:203] op_sel_hi:[1,0]
	v_pk_mul_f32 v[120:121], v[24:25], v[120:121]
	v_cvt_pk_bf16_f32 v206, v118, v119
	v_cvt_pk_bf16_f32 v207, v120, v121
	global_store_dwordx2 v194, v[206:207], s[52:53] offset:2560
	v_pk_mul_f32 v[122:123], v[90:91], v[202:203] op_sel_hi:[1,0]
	v_pk_mul_f32 v[122:123], v[26:27], v[122:123]
	v_pk_mul_f32 v[124:125], v[92:93], v[202:203] op_sel_hi:[1,0]
	v_pk_mul_f32 v[124:125], v[28:29], v[124:125]
	v_cvt_pk_bf16_f32 v206, v122, v123
	v_cvt_pk_bf16_f32 v207, v124, v125
	global_store_dwordx2 v194, v[206:207], s[52:53] offset:3072
	v_pk_mul_f32 v[126:127], v[94:95], v[202:203] op_sel_hi:[1,0]
	v_pk_mul_f32 v[126:127], v[30:31], v[126:127]
	v_pk_mul_f32 v[128:129], v[96:97], v[202:203] op_sel_hi:[1,0]
	v_pk_mul_f32 v[128:129], v[32:33], v[128:129]
	v_cvt_pk_bf16_f32 v206, v126, v127
	v_cvt_pk_bf16_f32 v207, v128, v129
	global_store_dwordx2 v194, v[206:207], s[52:53] offset:3584
	v_add_u32_e32 v194, 0x800000, v194
	global_load_dwordx4 v[66:69], v193, s[12:13] offset:-4096 nt
	global_load_dwordx4 v[70:73], v193, s[12:13] offset:-3072 nt
	global_load_dwordx4 v[74:77], v193, s[12:13] offset:-2048 nt
	global_load_dwordx4 v[78:81], v193, s[12:13] offset:-1024 nt
	global_load_dwordx4 v[82:85], v193, s[12:13] offset:0 nt
	global_load_dwordx4 v[86:89], v193, s[12:13] offset:1024 nt
	global_load_dwordx4 v[90:93], v193, s[12:13] offset:2048 nt
	global_load_dwordx4 v[94:97], v193, s[12:13] offset:3072 nt
	v_add_u32_e32 v193, s0, v193
	s_waitcnt lgkmcnt(6)
	v_pk_mul_f32 v[162:163], v[130:131], v[98:99] op_sel_hi:[1,0]
	v_pk_mul_f32 v[164:165], v[132:133], v[98:99] op_sel_hi:[1,0]
	v_pk_mul_f32 v[166:167], v[134:135], v[98:99] op_sel_hi:[1,0]
	v_pk_mul_f32 v[168:169], v[136:137], v[98:99] op_sel_hi:[1,0]
	ds_read_b128 v[130:133], v192 offset:8192
	ds_read_b128 v[134:137], v192 offset:9216
	s_waitcnt lgkmcnt(6)
	v_pk_fma_f32 v[162:163], v[138:139], v[98:99], v[162:163] op_sel:[0,1,0] op_sel_hi:[1,1,1]
	v_pk_fma_f32 v[164:165], v[140:141], v[98:99], v[164:165] op_sel:[0,1,0] op_sel_hi:[1,1,1]
	v_pk_fma_f32 v[166:167], v[142:143], v[98:99], v[166:167] op_sel:[0,1,0] op_sel_hi:[1,1,1]
	v_pk_fma_f32 v[168:169], v[144:145], v[98:99], v[168:169] op_sel:[0,1,0] op_sel_hi:[1,1,1]
	ds_read_b128 v[138:141], v192 offset:10240
	ds_read_b128 v[142:145], v192 offset:11264
	s_waitcnt lgkmcnt(6)
	v_pk_fma_f32 v[162:163], v[146:147], v[100:101], v[162:163] op_sel_hi:[1,0,1]
	v_pk_fma_f32 v[164:165], v[148:149], v[100:101], v[164:165] op_sel_hi:[1,0,1]
	v_pk_fma_f32 v[166:167], v[150:151], v[100:101], v[166:167] op_sel_hi:[1,0,1]
	v_pk_fma_f32 v[168:169], v[152:153], v[100:101], v[168:169] op_sel_hi:[1,0,1]
	ds_read_b128 v[146:149], v192 offset:12288
	ds_read_b128 v[150:153], v192 offset:13312
	s_waitcnt lgkmcnt(6)
	v_pk_fma_f32 v[162:163], v[154:155], v[100:101], v[162:163] op_sel:[0,1,0] op_sel_hi:[1,1,1]
	v_pk_fma_f32 v[164:165], v[156:157], v[100:101], v[164:165] op_sel:[0,1,0] op_sel_hi:[1,1,1]
	v_pk_fma_f32 v[166:167], v[158:159], v[100:101], v[166:167] op_sel:[0,1,0] op_sel_hi:[1,1,1]
	v_pk_fma_f32 v[168:169], v[160:161], v[100:101], v[168:169] op_sel:[0,1,0] op_sel_hi:[1,1,1]
	ds_read_b128 v[154:157], v192 offset:14336
	ds_read_b128 v[158:161], v192 offset:15360
	s_waitcnt lgkmcnt(6)
	v_pk_fma_f32 v[162:163], v[130:131], v[102:103], v[162:163] op_sel_hi:[1,0,1]
	v_pk_fma_f32 v[164:165], v[132:133], v[102:103], v[164:165] op_sel_hi:[1,0,1]
	v_pk_fma_f32 v[166:167], v[134:135], v[102:103], v[166:167] op_sel_hi:[1,0,1]
	v_pk_fma_f32 v[168:169], v[136:137], v[102:103], v[168:169] op_sel_hi:[1,0,1]
	ds_read_b128 v[130:133], v192 offset:16384
	ds_read_b128 v[134:137], v192 offset:17408
	s_waitcnt lgkmcnt(6)
	v_pk_fma_f32 v[162:163], v[138:139], v[102:103], v[162:163] op_sel:[0,1,0] op_sel_hi:[1,1,1]
	v_pk_fma_f32 v[164:165], v[140:141], v[102:103], v[164:165] op_sel:[0,1,0] op_sel_hi:[1,1,1]
	v_pk_fma_f32 v[166:167], v[142:143], v[102:103], v[166:167] op_sel:[0,1,0] op_sel_hi:[1,1,1]
	v_pk_fma_f32 v[168:169], v[144:145], v[102:103], v[168:169] op_sel:[0,1,0] op_sel_hi:[1,1,1]
	ds_read_b128 v[138:141], v192 offset:18432
	ds_read_b128 v[142:145], v192 offset:19456
	s_waitcnt lgkmcnt(6)
	v_pk_fma_f32 v[162:163], v[146:147], v[104:105], v[162:163] op_sel_hi:[1,0,1]
	v_pk_fma_f32 v[164:165], v[148:149], v[104:105], v[164:165] op_sel_hi:[1,0,1]
	v_pk_fma_f32 v[166:167], v[150:151], v[104:105], v[166:167] op_sel_hi:[1,0,1]
	v_pk_fma_f32 v[168:169], v[152:153], v[104:105], v[168:169] op_sel_hi:[1,0,1]
	ds_read_b128 v[146:149], v192 offset:20480
	ds_read_b128 v[150:153], v192 offset:21504
	s_waitcnt lgkmcnt(6)
	v_pk_fma_f32 v[162:163], v[154:155], v[104:105], v[162:163] op_sel:[0,1,0] op_sel_hi:[1,1,1]
	v_pk_fma_f32 v[164:165], v[156:157], v[104:105], v[164:165] op_sel:[0,1,0] op_sel_hi:[1,1,1]
	v_pk_fma_f32 v[166:167], v[158:159], v[104:105], v[166:167] op_sel:[0,1,0] op_sel_hi:[1,1,1]
	v_pk_fma_f32 v[168:169], v[160:161], v[104:105], v[168:169] op_sel:[0,1,0] op_sel_hi:[1,1,1]
	ds_read_b128 v[154:157], v192 offset:22528
	ds_read_b128 v[158:161], v192 offset:23552
	s_waitcnt lgkmcnt(6)
	v_pk_fma_f32 v[162:163], v[130:131], v[106:107], v[162:163] op_sel_hi:[1,0,1]
	v_pk_fma_f32 v[164:165], v[132:133], v[106:107], v[164:165] op_sel_hi:[1,0,1]
	v_pk_fma_f32 v[166:167], v[134:135], v[106:107], v[166:167] op_sel_hi:[1,0,1]
	v_pk_fma_f32 v[168:169], v[136:137], v[106:107], v[168:169] op_sel_hi:[1,0,1]
	ds_read_b128 v[130:133], v192 offset:24576
	ds_read_b128 v[134:137], v192 offset:25600
	s_waitcnt lgkmcnt(6)
	v_pk_fma_f32 v[162:163], v[138:139], v[106:107], v[162:163] op_sel:[0,1,0] op_sel_hi:[1,1,1]
	v_pk_fma_f32 v[164:165], v[140:141], v[106:107], v[164:165] op_sel:[0,1,0] op_sel_hi:[1,1,1]
	v_pk_fma_f32 v[166:167], v[142:143], v[106:107], v[166:167] op_sel:[0,1,0] op_sel_hi:[1,1,1]
	v_pk_fma_f32 v[168:169], v[144:145], v[106:107], v[168:169] op_sel:[0,1,0] op_sel_hi:[1,1,1]
	ds_read_b128 v[138:141], v192 offset:26624
	ds_read_b128 v[142:145], v192 offset:27648
	s_waitcnt lgkmcnt(6)
	v_pk_fma_f32 v[162:163], v[146:147], v[108:109], v[162:163] op_sel_hi:[1,0,1]
	v_pk_fma_f32 v[164:165], v[148:149], v[108:109], v[164:165] op_sel_hi:[1,0,1]
	v_pk_fma_f32 v[166:167], v[150:151], v[108:109], v[166:167] op_sel_hi:[1,0,1]
	v_pk_fma_f32 v[168:169], v[152:153], v[108:109], v[168:169] op_sel_hi:[1,0,1]
	ds_read_b128 v[146:149], v192 offset:28672
	ds_read_b128 v[150:153], v192 offset:29696
	s_waitcnt lgkmcnt(6)
	v_pk_fma_f32 v[162:163], v[154:155], v[108:109], v[162:163] op_sel:[0,1,0] op_sel_hi:[1,1,1]
	v_pk_fma_f32 v[164:165], v[156:157], v[108:109], v[164:165] op_sel:[0,1,0] op_sel_hi:[1,1,1]
	v_pk_fma_f32 v[166:167], v[158:159], v[108:109], v[166:167] op_sel:[0,1,0] op_sel_hi:[1,1,1]
	v_pk_fma_f32 v[168:169], v[160:161], v[108:109], v[168:169] op_sel:[0,1,0] op_sel_hi:[1,1,1]
	ds_read_b128 v[154:157], v192 offset:30720
	ds_read_b128 v[158:161], v192 offset:31744
	s_waitcnt lgkmcnt(6)
	v_pk_fma_f32 v[162:163], v[130:131], v[110:111], v[162:163] op_sel_hi:[1,0,1]
	v_pk_fma_f32 v[164:165], v[132:133], v[110:111], v[164:165] op_sel_hi:[1,0,1]
	v_pk_fma_f32 v[166:167], v[134:135], v[110:111], v[166:167] op_sel_hi:[1,0,1]
	v_pk_fma_f32 v[168:169], v[136:137], v[110:111], v[168:169] op_sel_hi:[1,0,1]
	ds_read_b128 v[130:133], v192 offset:32768
	ds_read_b128 v[134:137], v192 offset:33792
	s_waitcnt lgkmcnt(6)
	v_pk_fma_f32 v[162:163], v[138:139], v[110:111], v[162:163] op_sel:[0,1,0] op_sel_hi:[1,1,1]
	v_pk_fma_f32 v[164:165], v[140:141], v[110:111], v[164:165] op_sel:[0,1,0] op_sel_hi:[1,1,1]
	v_pk_fma_f32 v[166:167], v[142:143], v[110:111], v[166:167] op_sel:[0,1,0] op_sel_hi:[1,1,1]
	v_pk_fma_f32 v[168:169], v[144:145], v[110:111], v[168:169] op_sel:[0,1,0] op_sel_hi:[1,1,1]
	ds_read_b128 v[138:141], v192 offset:34816
	ds_read_b128 v[142:145], v192 offset:35840
	s_waitcnt lgkmcnt(6)
	v_pk_fma_f32 v[162:163], v[146:147], v[112:113], v[162:163] op_sel_hi:[1,0,1]
	v_pk_fma_f32 v[164:165], v[148:149], v[112:113], v[164:165] op_sel_hi:[1,0,1]
	v_pk_fma_f32 v[166:167], v[150:151], v[112:113], v[166:167] op_sel_hi:[1,0,1]
	v_pk_fma_f32 v[168:169], v[152:153], v[112:113], v[168:169] op_sel_hi:[1,0,1]
	ds_read_b128 v[146:149], v192 offset:36864
	ds_read_b128 v[150:153], v192 offset:37888
	s_waitcnt lgkmcnt(6)
	v_pk_fma_f32 v[162:163], v[154:155], v[112:113], v[162:163] op_sel:[0,1,0] op_sel_hi:[1,1,1]
	v_pk_fma_f32 v[164:165], v[156:157], v[112:113], v[164:165] op_sel:[0,1,0] op_sel_hi:[1,1,1]
	v_pk_fma_f32 v[166:167], v[158:159], v[112:113], v[166:167] op_sel:[0,1,0] op_sel_hi:[1,1,1]
	v_pk_fma_f32 v[168:169], v[160:161], v[112:113], v[168:169] op_sel:[0,1,0] op_sel_hi:[1,1,1]
	ds_read_b128 v[154:157], v192 offset:38912
	ds_read_b128 v[158:161], v192 offset:39936
	s_waitcnt lgkmcnt(6)
	v_pk_fma_f32 v[162:163], v[130:131], v[114:115], v[162:163] op_sel_hi:[1,0,1]
	v_pk_fma_f32 v[164:165], v[132:133], v[114:115], v[164:165] op_sel_hi:[1,0,1]
	v_pk_fma_f32 v[166:167], v[134:135], v[114:115], v[166:167] op_sel_hi:[1,0,1]
	v_pk_fma_f32 v[168:169], v[136:137], v[114:115], v[168:169] op_sel_hi:[1,0,1]
	ds_read_b128 v[130:133], v192 offset:40960
	ds_read_b128 v[134:137], v192 offset:41984
	s_waitcnt lgkmcnt(6)
	v_pk_fma_f32 v[162:163], v[138:139], v[114:115], v[162:163] op_sel:[0,1,0] op_sel_hi:[1,1,1]
	v_pk_fma_f32 v[164:165], v[140:141], v[114:115], v[164:165] op_sel:[0,1,0] op_sel_hi:[1,1,1]
	v_pk_fma_f32 v[166:167], v[142:143], v[114:115], v[166:167] op_sel:[0,1,0] op_sel_hi:[1,1,1]
	v_pk_fma_f32 v[168:169], v[144:145], v[114:115], v[168:169] op_sel:[0,1,0] op_sel_hi:[1,1,1]
	ds_read_b128 v[138:141], v192 offset:43008
	ds_read_b128 v[142:145], v192 offset:44032
	s_waitcnt lgkmcnt(6)
	v_pk_fma_f32 v[162:163], v[146:147], v[116:117], v[162:163] op_sel_hi:[1,0,1]
	v_pk_fma_f32 v[164:165], v[148:149], v[116:117], v[164:165] op_sel_hi:[1,0,1]
	v_pk_fma_f32 v[166:167], v[150:151], v[116:117], v[166:167] op_sel_hi:[1,0,1]
	v_pk_fma_f32 v[168:169], v[152:153], v[116:117], v[168:169] op_sel_hi:[1,0,1]
	ds_read_b128 v[146:149], v192 offset:45056
	ds_read_b128 v[150:153], v192 offset:46080
	s_waitcnt lgkmcnt(6)
	v_pk_fma_f32 v[162:163], v[154:155], v[116:117], v[162:163] op_sel:[0,1,0] op_sel_hi:[1,1,1]
	v_pk_fma_f32 v[164:165], v[156:157], v[116:117], v[164:165] op_sel:[0,1,0] op_sel_hi:[1,1,1]
	v_pk_fma_f32 v[166:167], v[158:159], v[116:117], v[166:167] op_sel:[0,1,0] op_sel_hi:[1,1,1]
	v_pk_fma_f32 v[168:169], v[160:161], v[116:117], v[168:169] op_sel:[0,1,0] op_sel_hi:[1,1,1]
	ds_read_b128 v[154:157], v192 offset:47104
	ds_read_b128 v[158:161], v192 offset:48128
	s_waitcnt lgkmcnt(6)
	v_pk_fma_f32 v[162:163], v[130:131], v[118:119], v[162:163] op_sel_hi:[1,0,1]
	v_pk_fma_f32 v[164:165], v[132:133], v[118:119], v[164:165] op_sel_hi:[1,0,1]
	v_pk_fma_f32 v[166:167], v[134:135], v[118:119], v[166:167] op_sel_hi:[1,0,1]
	v_pk_fma_f32 v[168:169], v[136:137], v[118:119], v[168:169] op_sel_hi:[1,0,1]
	ds_read_b128 v[130:133], v192 offset:49152
	ds_read_b128 v[134:137], v192 offset:50176
	s_waitcnt lgkmcnt(6)
	v_pk_fma_f32 v[162:163], v[138:139], v[118:119], v[162:163] op_sel:[0,1,0] op_sel_hi:[1,1,1]
	v_pk_fma_f32 v[164:165], v[140:141], v[118:119], v[164:165] op_sel:[0,1,0] op_sel_hi:[1,1,1]
	v_pk_fma_f32 v[166:167], v[142:143], v[118:119], v[166:167] op_sel:[0,1,0] op_sel_hi:[1,1,1]
	v_pk_fma_f32 v[168:169], v[144:145], v[118:119], v[168:169] op_sel:[0,1,0] op_sel_hi:[1,1,1]
	ds_read_b128 v[138:141], v192 offset:51200
	ds_read_b128 v[142:145], v192 offset:52224
	s_waitcnt lgkmcnt(6)
	v_pk_fma_f32 v[162:163], v[146:147], v[120:121], v[162:163] op_sel_hi:[1,0,1]
	v_pk_fma_f32 v[164:165], v[148:149], v[120:121], v[164:165] op_sel_hi:[1,0,1]
	v_pk_fma_f32 v[166:167], v[150:151], v[120:121], v[166:167] op_sel_hi:[1,0,1]
	v_pk_fma_f32 v[168:169], v[152:153], v[120:121], v[168:169] op_sel_hi:[1,0,1]
	ds_read_b128 v[146:149], v192 offset:53248
	ds_read_b128 v[150:153], v192 offset:54272
	s_waitcnt lgkmcnt(6)
	v_pk_fma_f32 v[162:163], v[154:155], v[120:121], v[162:163] op_sel:[0,1,0] op_sel_hi:[1,1,1]
	v_pk_fma_f32 v[164:165], v[156:157], v[120:121], v[164:165] op_sel:[0,1,0] op_sel_hi:[1,1,1]
	v_pk_fma_f32 v[166:167], v[158:159], v[120:121], v[166:167] op_sel:[0,1,0] op_sel_hi:[1,1,1]
	v_pk_fma_f32 v[168:169], v[160:161], v[120:121], v[168:169] op_sel:[0,1,0] op_sel_hi:[1,1,1]
	ds_read_b128 v[154:157], v192 offset:55296
	ds_read_b128 v[158:161], v192 offset:56320
	s_waitcnt lgkmcnt(6)
	v_pk_fma_f32 v[162:163], v[130:131], v[122:123], v[162:163] op_sel_hi:[1,0,1]
	v_pk_fma_f32 v[164:165], v[132:133], v[122:123], v[164:165] op_sel_hi:[1,0,1]
	v_pk_fma_f32 v[166:167], v[134:135], v[122:123], v[166:167] op_sel_hi:[1,0,1]
	v_pk_fma_f32 v[168:169], v[136:137], v[122:123], v[168:169] op_sel_hi:[1,0,1]
	ds_read_b128 v[130:133], v192 offset:57344
	ds_read_b128 v[134:137], v192 offset:58368
	s_waitcnt lgkmcnt(6)
	v_pk_fma_f32 v[162:163], v[138:139], v[122:123], v[162:163] op_sel:[0,1,0] op_sel_hi:[1,1,1]
	v_pk_fma_f32 v[164:165], v[140:141], v[122:123], v[164:165] op_sel:[0,1,0] op_sel_hi:[1,1,1]
	v_pk_fma_f32 v[166:167], v[142:143], v[122:123], v[166:167] op_sel:[0,1,0] op_sel_hi:[1,1,1]
	v_pk_fma_f32 v[168:169], v[144:145], v[122:123], v[168:169] op_sel:[0,1,0] op_sel_hi:[1,1,1]
	ds_read_b128 v[138:141], v192 offset:59392
	ds_read_b128 v[142:145], v192 offset:60416
	s_waitcnt lgkmcnt(6)
	v_pk_fma_f32 v[162:163], v[146:147], v[124:125], v[162:163] op_sel_hi:[1,0,1]
	v_pk_fma_f32 v[164:165], v[148:149], v[124:125], v[164:165] op_sel_hi:[1,0,1]
	v_pk_fma_f32 v[166:167], v[150:151], v[124:125], v[166:167] op_sel_hi:[1,0,1]
	v_pk_fma_f32 v[168:169], v[152:153], v[124:125], v[168:169] op_sel_hi:[1,0,1]
	ds_read_b128 v[146:149], v192 offset:61440
	ds_read_b128 v[150:153], v192 offset:62464
	s_waitcnt lgkmcnt(6)
	v_pk_fma_f32 v[162:163], v[154:155], v[124:125], v[162:163] op_sel:[0,1,0] op_sel_hi:[1,1,1]
	v_pk_fma_f32 v[164:165], v[156:157], v[124:125], v[164:165] op_sel:[0,1,0] op_sel_hi:[1,1,1]
	v_pk_fma_f32 v[166:167], v[158:159], v[124:125], v[166:167] op_sel:[0,1,0] op_sel_hi:[1,1,1]
	v_pk_fma_f32 v[168:169], v[160:161], v[124:125], v[168:169] op_sel:[0,1,0] op_sel_hi:[1,1,1]
	ds_read_b128 v[154:157], v192 offset:63488
	ds_read_b128 v[158:161], v192 offset:64512
	s_waitcnt lgkmcnt(6)
	v_pk_fma_f32 v[162:163], v[130:131], v[126:127], v[162:163] op_sel_hi:[1,0,1]
	v_pk_fma_f32 v[164:165], v[132:133], v[126:127], v[164:165] op_sel_hi:[1,0,1]
	v_pk_fma_f32 v[166:167], v[134:135], v[126:127], v[166:167] op_sel_hi:[1,0,1]
	v_pk_fma_f32 v[168:169], v[136:137], v[126:127], v[168:169] op_sel_hi:[1,0,1]
	s_waitcnt lgkmcnt(4)
	v_pk_fma_f32 v[162:163], v[138:139], v[126:127], v[162:163] op_sel:[0,1,0] op_sel_hi:[1,1,1]
	v_pk_fma_f32 v[164:165], v[140:141], v[126:127], v[164:165] op_sel:[0,1,0] op_sel_hi:[1,1,1]
	v_pk_fma_f32 v[166:167], v[142:143], v[126:127], v[166:167] op_sel:[0,1,0] op_sel_hi:[1,1,1]
	v_pk_fma_f32 v[168:169], v[144:145], v[126:127], v[168:169] op_sel:[0,1,0] op_sel_hi:[1,1,1]
	s_waitcnt lgkmcnt(2)
	v_pk_fma_f32 v[162:163], v[146:147], v[128:129], v[162:163] op_sel_hi:[1,0,1]
	v_pk_fma_f32 v[164:165], v[148:149], v[128:129], v[164:165] op_sel_hi:[1,0,1]
	v_pk_fma_f32 v[166:167], v[150:151], v[128:129], v[166:167] op_sel_hi:[1,0,1]
	v_pk_fma_f32 v[168:169], v[152:153], v[128:129], v[168:169] op_sel_hi:[1,0,1]
	s_waitcnt lgkmcnt(0)
	v_pk_fma_f32 v[162:163], v[154:155], v[128:129], v[162:163] op_sel:[0,1,0] op_sel_hi:[1,1,1]
	v_pk_fma_f32 v[164:165], v[156:157], v[128:129], v[164:165] op_sel:[0,1,0] op_sel_hi:[1,1,1]
	v_pk_fma_f32 v[166:167], v[158:159], v[128:129], v[166:167] op_sel:[0,1,0] op_sel_hi:[1,1,1]
	v_pk_fma_f32 v[168:169], v[160:161], v[128:129], v[168:169] op_sel:[0,1,0] op_sel_hi:[1,1,1]
	s_nop 1
	v_add_f32_dpp v162, v162, v162 quad_perm:[1,0,3,2] row_mask:0xf bank_mask:0xf
	v_add_f32_dpp v163, v163, v163 quad_perm:[1,0,3,2] row_mask:0xf bank_mask:0xf
	v_add_f32_dpp v164, v164, v164 quad_perm:[1,0,3,2] row_mask:0xf bank_mask:0xf
	v_add_f32_dpp v165, v165, v165 quad_perm:[1,0,3,2] row_mask:0xf bank_mask:0xf
	v_add_f32_dpp v166, v166, v166 quad_perm:[1,0,3,2] row_mask:0xf bank_mask:0xf
	v_add_f32_dpp v167, v167, v167 quad_perm:[1,0,3,2] row_mask:0xf bank_mask:0xf
	v_add_f32_dpp v168, v168, v168 quad_perm:[1,0,3,2] row_mask:0xf bank_mask:0xf
	v_add_f32_dpp v169, v169, v169 quad_perm:[1,0,3,2] row_mask:0xf bank_mask:0xf
	v_add_f32_dpp v162, v162, v162 quad_perm:[2,3,0,1] row_mask:0xf bank_mask:0xf
	v_add_f32_dpp v163, v163, v163 quad_perm:[2,3,0,1] row_mask:0xf bank_mask:0xf
	v_add_f32_dpp v164, v164, v164 quad_perm:[2,3,0,1] row_mask:0xf bank_mask:0xf
	v_add_f32_dpp v165, v165, v165 quad_perm:[2,3,0,1] row_mask:0xf bank_mask:0xf
	v_add_f32_dpp v166, v166, v166 quad_perm:[2,3,0,1] row_mask:0xf bank_mask:0xf
	v_add_f32_dpp v167, v167, v167 quad_perm:[2,3,0,1] row_mask:0xf bank_mask:0xf
	v_add_f32_dpp v168, v168, v168 quad_perm:[2,3,0,1] row_mask:0xf bank_mask:0xf
	v_add_f32_dpp v169, v169, v169 quad_perm:[2,3,0,1] row_mask:0xf bank_mask:0xf
	v_add_f32_dpp v162, v162, v162 row_half_mirror row_mask:0xf bank_mask:0xf
	v_add_f32_dpp v163, v163, v163 row_half_mirror row_mask:0xf bank_mask:0xf
	v_add_f32_dpp v164, v164, v164 row_half_mirror row_mask:0xf bank_mask:0xf
	v_add_f32_dpp v165, v165, v165 row_half_mirror row_mask:0xf bank_mask:0xf
	v_add_f32_dpp v166, v166, v166 row_half_mirror row_mask:0xf bank_mask:0xf
	v_add_f32_dpp v167, v167, v167 row_half_mirror row_mask:0xf bank_mask:0xf
	v_add_f32_dpp v168, v168, v168 row_half_mirror row_mask:0xf bank_mask:0xf
	v_add_f32_dpp v169, v169, v169 row_half_mirror row_mask:0xf bank_mask:0xf
	v_add_f32_dpp v162, v162, v162 row_mirror row_mask:0xf bank_mask:0xf
	v_add_f32_dpp v163, v163, v163 row_mirror row_mask:0xf bank_mask:0xf
	v_add_f32_dpp v164, v164, v164 row_mirror row_mask:0xf bank_mask:0xf
	v_add_f32_dpp v165, v165, v165 row_mirror row_mask:0xf bank_mask:0xf
	v_add_f32_dpp v166, v166, v166 row_mirror row_mask:0xf bank_mask:0xf
	v_add_f32_dpp v167, v167, v167 row_mirror row_mask:0xf bank_mask:0xf
	v_add_f32_dpp v168, v168, v168 row_mirror row_mask:0xf bank_mask:0xf
	v_add_f32_dpp v169, v169, v169 row_mirror row_mask:0xf bank_mask:0xf
	v_mov_b32_e32 v170, v162
	v_mov_b32_e32 v171, v163
	v_mov_b32_e32 v172, v164
	v_mov_b32_e32 v173, v165
	v_mov_b32_e32 v174, v166
	v_mov_b32_e32 v175, v167
	v_mov_b32_e32 v176, v168
	v_mov_b32_e32 v177, v169
	v_permlane16_swap_b32 v170, v162
	v_permlane16_swap_b32 v171, v163
	v_permlane16_swap_b32 v172, v164
	v_permlane16_swap_b32 v173, v165
	v_permlane16_swap_b32 v174, v166
	v_permlane16_swap_b32 v175, v167
	v_permlane16_swap_b32 v176, v168
	v_permlane16_swap_b32 v177, v169
	v_add_f32_e32 v162, v162, v170
	v_add_f32_e32 v163, v163, v171
	v_add_f32_e32 v164, v164, v172
	v_add_f32_e32 v165, v165, v173
	v_add_f32_e32 v166, v166, v174
	v_add_f32_e32 v167, v167, v175
	v_add_f32_e32 v168, v168, v176
	v_add_f32_e32 v169, v169, v177
	v_mov_b32_e32 v170, v162
	v_mov_b32_e32 v171, v163
	v_mov_b32_e32 v172, v164
	v_mov_b32_e32 v173, v165
	v_mov_b32_e32 v174, v166
	v_mov_b32_e32 v175, v167
	v_mov_b32_e32 v176, v168
	v_mov_b32_e32 v177, v169
	v_permlane32_swap_b32 v170, v162
	v_permlane32_swap_b32 v171, v163
	v_permlane32_swap_b32 v172, v164
	v_permlane32_swap_b32 v173, v165
	v_permlane32_swap_b32 v174, v166
	v_permlane32_swap_b32 v175, v167
	v_permlane32_swap_b32 v176, v168
	v_permlane32_swap_b32 v177, v169
	v_add_f32_e32 v162, v162, v170
	v_add_f32_e32 v163, v163, v171
	v_add_f32_e32 v164, v164, v172
	v_add_f32_e32 v165, v165, v173
	v_add_f32_e32 v166, v166, v174
	v_add_f32_e32 v167, v167, v175
	v_add_f32_e32 v168, v168, v176
	v_add_f32_e32 v169, v169, v177
	v_readfirstlane_b32 s98, v162
	v_readfirstlane_b32 s99, v163
	v_readfirstlane_b32 s100, v164
	v_readfirstlane_b32 s101, v165
	v_writelane_b32 v230, s98, 24
	v_writelane_b32 v230, s99, 25
	v_writelane_b32 v230, s100, 26
	v_writelane_b32 v230, s101, 27
	v_readfirstlane_b32 s98, v166
	v_readfirstlane_b32 s99, v167
	v_readfirstlane_b32 s100, v168
	v_readfirstlane_b32 s101, v169
	v_writelane_b32 v230, s98, 28
	v_writelane_b32 v230, s99, 29
	v_writelane_b32 v230, s100, 30
	v_writelane_b32 v230, s101, 31
	s_waitcnt vmcnt(16)
	v_pk_mul_f32 v[198:199], v[34:35], v[34:35]
	v_pk_mul_f32 v[200:201], v[36:37], v[36:37]
	v_pk_fma_f32 v[198:199], v[38:39], v[38:39], v[198:199]
	v_pk_fma_f32 v[200:201], v[40:41], v[40:41], v[200:201]
	v_pk_fma_f32 v[198:199], v[42:43], v[42:43], v[198:199]
	v_pk_fma_f32 v[200:201], v[44:45], v[44:45], v[200:201]
	v_pk_fma_f32 v[198:199], v[46:47], v[46:47], v[198:199]
	v_pk_fma_f32 v[200:201], v[48:49], v[48:49], v[200:201]
	v_pk_fma_f32 v[198:199], v[50:51], v[50:51], v[198:199]
	v_pk_fma_f32 v[200:201], v[52:53], v[52:53], v[200:201]
	v_pk_fma_f32 v[198:199], v[54:55], v[54:55], v[198:199]
	v_pk_fma_f32 v[200:201], v[56:57], v[56:57], v[200:201]
	v_pk_fma_f32 v[198:199], v[58:59], v[58:59], v[198:199]
	v_pk_fma_f32 v[200:201], v[60:61], v[60:61], v[200:201]
	v_pk_fma_f32 v[198:199], v[62:63], v[62:63], v[198:199]
	v_pk_fma_f32 v[200:201], v[64:65], v[64:65], v[200:201]
	v_pk_add_f32 v[198:199], v[198:199], v[200:201]
	v_add_f32_e32 v198, v198, v199
	s_nop 1
	v_add_f32_dpp v198, v198, v198 quad_perm:[1,0,3,2] row_mask:0xf bank_mask:0xf
	s_nop 1
	v_add_f32_dpp v198, v198, v198 quad_perm:[2,3,0,1] row_mask:0xf bank_mask:0xf
	s_nop 1
	v_add_f32_dpp v198, v198, v198 row_half_mirror row_mask:0xf bank_mask:0xf
	s_nop 1
	v_add_f32_dpp v198, v198, v198 row_mirror row_mask:0xf bank_mask:0xf
	v_mov_b32_e32 v199, v198
	s_nop 1
	v_permlane16_swap_b32 v199, v198
	v_add_f32_e32 v198, v198, v199
	v_mov_b32_e32 v199, v198
	s_nop 1
	v_permlane32_swap_b32 v199, v198
	v_add_f32_e32 v198, v198, v199
	ds_read_b128 v[130:133], v192
	ds_read_b128 v[134:137], v192 offset:1024
	ds_read_b128 v[138:141], v192 offset:2048
	ds_read_b128 v[142:145], v192 offset:3072
	ds_read_b128 v[146:149], v192 offset:4096
	ds_read_b128 v[150:153], v192 offset:5120
	ds_read_b128 v[154:157], v192 offset:6144
	ds_read_b128 v[158:161], v192 offset:7168
	v_fmamk_f32 v198, v198, 0x3a000000, v241
	v_mul_f32_e32 v199, 0x4b800000, v198
	v_cmp_gt_f32_e32 vcc, s17, v198
	s_nop 1
	v_cndmask_b32_e32 v198, v198, v199, vcc
	v_rsq_f32_e32 v198, v198
	s_nop 0
	v_mul_f32_e32 v199, 0x45800000, v198
	v_cndmask_b32_e32 v202, v198, v199, vcc
	v_pk_mul_f32 v[98:99], v[34:35], v[202:203] op_sel_hi:[1,0]
	v_pk_mul_f32 v[98:99], v[2:3], v[98:99]
	v_pk_mul_f32 v[100:101], v[36:37], v[202:203] op_sel_hi:[1,0]
	v_pk_mul_f32 v[100:101], v[4:5], v[100:101]
	v_cvt_pk_bf16_f32 v206, v98, v99
	v_cvt_pk_bf16_f32 v207, v100, v101
	global_store_dwordx2 v194, v[206:207], s[52:53]
	v_pk_mul_f32 v[102:103], v[38:39], v[202:203] op_sel_hi:[1,0]
	v_pk_mul_f32 v[102:103], v[6:7], v[102:103]
	v_pk_mul_f32 v[104:105], v[40:41], v[202:203] op_sel_hi:[1,0]
	v_pk_mul_f32 v[104:105], v[8:9], v[104:105]
	v_cvt_pk_bf16_f32 v206, v102, v103
	v_cvt_pk_bf16_f32 v207, v104, v105
	global_store_dwordx2 v194, v[206:207], s[52:53] offset:512
	v_pk_mul_f32 v[106:107], v[42:43], v[202:203] op_sel_hi:[1,0]
	v_pk_mul_f32 v[106:107], v[10:11], v[106:107]
	v_pk_mul_f32 v[108:109], v[44:45], v[202:203] op_sel_hi:[1,0]
	v_pk_mul_f32 v[108:109], v[12:13], v[108:109]
	v_cvt_pk_bf16_f32 v206, v106, v107
	v_cvt_pk_bf16_f32 v207, v108, v109
	global_store_dwordx2 v194, v[206:207], s[52:53] offset:1024
	v_pk_mul_f32 v[110:111], v[46:47], v[202:203] op_sel_hi:[1,0]
	v_pk_mul_f32 v[110:111], v[14:15], v[110:111]
	v_pk_mul_f32 v[112:113], v[48:49], v[202:203] op_sel_hi:[1,0]
	v_pk_mul_f32 v[112:113], v[16:17], v[112:113]
	v_cvt_pk_bf16_f32 v206, v110, v111
	v_cvt_pk_bf16_f32 v207, v112, v113
	global_store_dwordx2 v194, v[206:207], s[52:53] offset:1536
	v_pk_mul_f32 v[114:115], v[50:51], v[202:203] op_sel_hi:[1,0]
	v_pk_mul_f32 v[114:115], v[18:19], v[114:115]
	v_pk_mul_f32 v[116:117], v[52:53], v[202:203] op_sel_hi:[1,0]
	v_pk_mul_f32 v[116:117], v[20:21], v[116:117]
	v_cvt_pk_bf16_f32 v206, v114, v115
	v_cvt_pk_bf16_f32 v207, v116, v117
	global_store_dwordx2 v194, v[206:207], s[52:53] offset:2048
	v_pk_mul_f32 v[118:119], v[54:55], v[202:203] op_sel_hi:[1,0]
	v_pk_mul_f32 v[118:119], v[22:23], v[118:119]
	v_pk_mul_f32 v[120:121], v[56:57], v[202:203] op_sel_hi:[1,0]
	v_pk_mul_f32 v[120:121], v[24:25], v[120:121]
	v_cvt_pk_bf16_f32 v206, v118, v119
	v_cvt_pk_bf16_f32 v207, v120, v121
	global_store_dwordx2 v194, v[206:207], s[52:53] offset:2560
	v_pk_mul_f32 v[122:123], v[58:59], v[202:203] op_sel_hi:[1,0]
	v_pk_mul_f32 v[122:123], v[26:27], v[122:123]
	v_pk_mul_f32 v[124:125], v[60:61], v[202:203] op_sel_hi:[1,0]
	v_pk_mul_f32 v[124:125], v[28:29], v[124:125]
	v_cvt_pk_bf16_f32 v206, v122, v123
	v_cvt_pk_bf16_f32 v207, v124, v125
	global_store_dwordx2 v194, v[206:207], s[52:53] offset:3072
	v_pk_mul_f32 v[126:127], v[62:63], v[202:203] op_sel_hi:[1,0]
	v_pk_mul_f32 v[126:127], v[30:31], v[126:127]
	v_pk_mul_f32 v[128:129], v[64:65], v[202:203] op_sel_hi:[1,0]
	v_pk_mul_f32 v[128:129], v[32:33], v[128:129]
	v_cvt_pk_bf16_f32 v206, v126, v127
	v_cvt_pk_bf16_f32 v207, v128, v129
	global_store_dwordx2 v194, v[206:207], s[52:53] offset:3584
	v_add_u32_e32 v194, 0x800000, v194
	global_load_dwordx4 v[34:37], v193, s[12:13] offset:-4096 nt
	global_load_dwordx4 v[38:41], v193, s[12:13] offset:-3072 nt
	global_load_dwordx4 v[42:45], v193, s[12:13] offset:-2048 nt
	global_load_dwordx4 v[46:49], v193, s[12:13] offset:-1024 nt
	global_load_dwordx4 v[50:53], v193, s[12:13] offset:0 nt
	global_load_dwordx4 v[54:57], v193, s[12:13] offset:1024 nt
	global_load_dwordx4 v[58:61], v193, s[12:13] offset:2048 nt
	global_load_dwordx4 v[62:65], v193, s[12:13] offset:3072 nt
	v_add_u32_e32 v193, s0, v193
	s_waitcnt lgkmcnt(6)
	v_pk_mul_f32 v[162:163], v[130:131], v[98:99] op_sel_hi:[1,0]
	v_pk_mul_f32 v[164:165], v[132:133], v[98:99] op_sel_hi:[1,0]
	v_pk_mul_f32 v[166:167], v[134:135], v[98:99] op_sel_hi:[1,0]
	v_pk_mul_f32 v[168:169], v[136:137], v[98:99] op_sel_hi:[1,0]
	ds_read_b128 v[130:133], v192 offset:8192
	ds_read_b128 v[134:137], v192 offset:9216
	s_waitcnt lgkmcnt(6)
	v_pk_fma_f32 v[162:163], v[138:139], v[98:99], v[162:163] op_sel:[0,1,0] op_sel_hi:[1,1,1]
	v_pk_fma_f32 v[164:165], v[140:141], v[98:99], v[164:165] op_sel:[0,1,0] op_sel_hi:[1,1,1]
	v_pk_fma_f32 v[166:167], v[142:143], v[98:99], v[166:167] op_sel:[0,1,0] op_sel_hi:[1,1,1]
	v_pk_fma_f32 v[168:169], v[144:145], v[98:99], v[168:169] op_sel:[0,1,0] op_sel_hi:[1,1,1]
	ds_read_b128 v[138:141], v192 offset:10240
	ds_read_b128 v[142:145], v192 offset:11264
	s_waitcnt lgkmcnt(6)
	v_pk_fma_f32 v[162:163], v[146:147], v[100:101], v[162:163] op_sel_hi:[1,0,1]
	v_pk_fma_f32 v[164:165], v[148:149], v[100:101], v[164:165] op_sel_hi:[1,0,1]
	v_pk_fma_f32 v[166:167], v[150:151], v[100:101], v[166:167] op_sel_hi:[1,0,1]
	v_pk_fma_f32 v[168:169], v[152:153], v[100:101], v[168:169] op_sel_hi:[1,0,1]
	ds_read_b128 v[146:149], v192 offset:12288
	ds_read_b128 v[150:153], v192 offset:13312
	s_waitcnt lgkmcnt(6)
	v_pk_fma_f32 v[162:163], v[154:155], v[100:101], v[162:163] op_sel:[0,1,0] op_sel_hi:[1,1,1]
	v_pk_fma_f32 v[164:165], v[156:157], v[100:101], v[164:165] op_sel:[0,1,0] op_sel_hi:[1,1,1]
	v_pk_fma_f32 v[166:167], v[158:159], v[100:101], v[166:167] op_sel:[0,1,0] op_sel_hi:[1,1,1]
	v_pk_fma_f32 v[168:169], v[160:161], v[100:101], v[168:169] op_sel:[0,1,0] op_sel_hi:[1,1,1]
	ds_read_b128 v[154:157], v192 offset:14336
	ds_read_b128 v[158:161], v192 offset:15360
	s_waitcnt lgkmcnt(6)
	v_pk_fma_f32 v[162:163], v[130:131], v[102:103], v[162:163] op_sel_hi:[1,0,1]
	v_pk_fma_f32 v[164:165], v[132:133], v[102:103], v[164:165] op_sel_hi:[1,0,1]
	v_pk_fma_f32 v[166:167], v[134:135], v[102:103], v[166:167] op_sel_hi:[1,0,1]
	v_pk_fma_f32 v[168:169], v[136:137], v[102:103], v[168:169] op_sel_hi:[1,0,1]
	ds_read_b128 v[130:133], v192 offset:16384
	ds_read_b128 v[134:137], v192 offset:17408
	s_waitcnt lgkmcnt(6)
	v_pk_fma_f32 v[162:163], v[138:139], v[102:103], v[162:163] op_sel:[0,1,0] op_sel_hi:[1,1,1]
	v_pk_fma_f32 v[164:165], v[140:141], v[102:103], v[164:165] op_sel:[0,1,0] op_sel_hi:[1,1,1]
	v_pk_fma_f32 v[166:167], v[142:143], v[102:103], v[166:167] op_sel:[0,1,0] op_sel_hi:[1,1,1]
	v_pk_fma_f32 v[168:169], v[144:145], v[102:103], v[168:169] op_sel:[0,1,0] op_sel_hi:[1,1,1]
	ds_read_b128 v[138:141], v192 offset:18432
	ds_read_b128 v[142:145], v192 offset:19456
	s_waitcnt lgkmcnt(6)
	v_pk_fma_f32 v[162:163], v[146:147], v[104:105], v[162:163] op_sel_hi:[1,0,1]
	v_pk_fma_f32 v[164:165], v[148:149], v[104:105], v[164:165] op_sel_hi:[1,0,1]
	v_pk_fma_f32 v[166:167], v[150:151], v[104:105], v[166:167] op_sel_hi:[1,0,1]
	v_pk_fma_f32 v[168:169], v[152:153], v[104:105], v[168:169] op_sel_hi:[1,0,1]
	ds_read_b128 v[146:149], v192 offset:20480
	ds_read_b128 v[150:153], v192 offset:21504
	s_waitcnt lgkmcnt(6)
	v_pk_fma_f32 v[162:163], v[154:155], v[104:105], v[162:163] op_sel:[0,1,0] op_sel_hi:[1,1,1]
	v_pk_fma_f32 v[164:165], v[156:157], v[104:105], v[164:165] op_sel:[0,1,0] op_sel_hi:[1,1,1]
	v_pk_fma_f32 v[166:167], v[158:159], v[104:105], v[166:167] op_sel:[0,1,0] op_sel_hi:[1,1,1]
	v_pk_fma_f32 v[168:169], v[160:161], v[104:105], v[168:169] op_sel:[0,1,0] op_sel_hi:[1,1,1]
	ds_read_b128 v[154:157], v192 offset:22528
	ds_read_b128 v[158:161], v192 offset:23552
	s_waitcnt lgkmcnt(6)
	v_pk_fma_f32 v[162:163], v[130:131], v[106:107], v[162:163] op_sel_hi:[1,0,1]
	v_pk_fma_f32 v[164:165], v[132:133], v[106:107], v[164:165] op_sel_hi:[1,0,1]
	v_pk_fma_f32 v[166:167], v[134:135], v[106:107], v[166:167] op_sel_hi:[1,0,1]
	v_pk_fma_f32 v[168:169], v[136:137], v[106:107], v[168:169] op_sel_hi:[1,0,1]
	ds_read_b128 v[130:133], v192 offset:24576
	ds_read_b128 v[134:137], v192 offset:25600
	s_waitcnt lgkmcnt(6)
	v_pk_fma_f32 v[162:163], v[138:139], v[106:107], v[162:163] op_sel:[0,1,0] op_sel_hi:[1,1,1]
	v_pk_fma_f32 v[164:165], v[140:141], v[106:107], v[164:165] op_sel:[0,1,0] op_sel_hi:[1,1,1]
	v_pk_fma_f32 v[166:167], v[142:143], v[106:107], v[166:167] op_sel:[0,1,0] op_sel_hi:[1,1,1]
	v_pk_fma_f32 v[168:169], v[144:145], v[106:107], v[168:169] op_sel:[0,1,0] op_sel_hi:[1,1,1]
	ds_read_b128 v[138:141], v192 offset:26624
	ds_read_b128 v[142:145], v192 offset:27648
	s_waitcnt lgkmcnt(6)
	v_pk_fma_f32 v[162:163], v[146:147], v[108:109], v[162:163] op_sel_hi:[1,0,1]
	v_pk_fma_f32 v[164:165], v[148:149], v[108:109], v[164:165] op_sel_hi:[1,0,1]
	v_pk_fma_f32 v[166:167], v[150:151], v[108:109], v[166:167] op_sel_hi:[1,0,1]
	v_pk_fma_f32 v[168:169], v[152:153], v[108:109], v[168:169] op_sel_hi:[1,0,1]
	ds_read_b128 v[146:149], v192 offset:28672
	ds_read_b128 v[150:153], v192 offset:29696
	s_waitcnt lgkmcnt(6)
	v_pk_fma_f32 v[162:163], v[154:155], v[108:109], v[162:163] op_sel:[0,1,0] op_sel_hi:[1,1,1]
	v_pk_fma_f32 v[164:165], v[156:157], v[108:109], v[164:165] op_sel:[0,1,0] op_sel_hi:[1,1,1]
	v_pk_fma_f32 v[166:167], v[158:159], v[108:109], v[166:167] op_sel:[0,1,0] op_sel_hi:[1,1,1]
	v_pk_fma_f32 v[168:169], v[160:161], v[108:109], v[168:169] op_sel:[0,1,0] op_sel_hi:[1,1,1]
	ds_read_b128 v[154:157], v192 offset:30720
	ds_read_b128 v[158:161], v192 offset:31744
	s_waitcnt lgkmcnt(6)
	v_pk_fma_f32 v[162:163], v[130:131], v[110:111], v[162:163] op_sel_hi:[1,0,1]
	v_pk_fma_f32 v[164:165], v[132:133], v[110:111], v[164:165] op_sel_hi:[1,0,1]
	v_pk_fma_f32 v[166:167], v[134:135], v[110:111], v[166:167] op_sel_hi:[1,0,1]
	v_pk_fma_f32 v[168:169], v[136:137], v[110:111], v[168:169] op_sel_hi:[1,0,1]
	ds_read_b128 v[130:133], v192 offset:32768
	ds_read_b128 v[134:137], v192 offset:33792
	s_waitcnt lgkmcnt(6)
	v_pk_fma_f32 v[162:163], v[138:139], v[110:111], v[162:163] op_sel:[0,1,0] op_sel_hi:[1,1,1]
	v_pk_fma_f32 v[164:165], v[140:141], v[110:111], v[164:165] op_sel:[0,1,0] op_sel_hi:[1,1,1]
	v_pk_fma_f32 v[166:167], v[142:143], v[110:111], v[166:167] op_sel:[0,1,0] op_sel_hi:[1,1,1]
	v_pk_fma_f32 v[168:169], v[144:145], v[110:111], v[168:169] op_sel:[0,1,0] op_sel_hi:[1,1,1]
	ds_read_b128 v[138:141], v192 offset:34816
	ds_read_b128 v[142:145], v192 offset:35840
	s_waitcnt lgkmcnt(6)
	v_pk_fma_f32 v[162:163], v[146:147], v[112:113], v[162:163] op_sel_hi:[1,0,1]
	v_pk_fma_f32 v[164:165], v[148:149], v[112:113], v[164:165] op_sel_hi:[1,0,1]
	v_pk_fma_f32 v[166:167], v[150:151], v[112:113], v[166:167] op_sel_hi:[1,0,1]
	v_pk_fma_f32 v[168:169], v[152:153], v[112:113], v[168:169] op_sel_hi:[1,0,1]
	ds_read_b128 v[146:149], v192 offset:36864
	ds_read_b128 v[150:153], v192 offset:37888
	s_waitcnt lgkmcnt(6)
	v_pk_fma_f32 v[162:163], v[154:155], v[112:113], v[162:163] op_sel:[0,1,0] op_sel_hi:[1,1,1]
	v_pk_fma_f32 v[164:165], v[156:157], v[112:113], v[164:165] op_sel:[0,1,0] op_sel_hi:[1,1,1]
	v_pk_fma_f32 v[166:167], v[158:159], v[112:113], v[166:167] op_sel:[0,1,0] op_sel_hi:[1,1,1]
	v_pk_fma_f32 v[168:169], v[160:161], v[112:113], v[168:169] op_sel:[0,1,0] op_sel_hi:[1,1,1]
	ds_read_b128 v[154:157], v192 offset:38912
	ds_read_b128 v[158:161], v192 offset:39936
	s_waitcnt lgkmcnt(6)
	v_pk_fma_f32 v[162:163], v[130:131], v[114:115], v[162:163] op_sel_hi:[1,0,1]
	v_pk_fma_f32 v[164:165], v[132:133], v[114:115], v[164:165] op_sel_hi:[1,0,1]
	v_pk_fma_f32 v[166:167], v[134:135], v[114:115], v[166:167] op_sel_hi:[1,0,1]
	v_pk_fma_f32 v[168:169], v[136:137], v[114:115], v[168:169] op_sel_hi:[1,0,1]
	ds_read_b128 v[130:133], v192 offset:40960
	ds_read_b128 v[134:137], v192 offset:41984
	s_waitcnt lgkmcnt(6)
	v_pk_fma_f32 v[162:163], v[138:139], v[114:115], v[162:163] op_sel:[0,1,0] op_sel_hi:[1,1,1]
	v_pk_fma_f32 v[164:165], v[140:141], v[114:115], v[164:165] op_sel:[0,1,0] op_sel_hi:[1,1,1]
	v_pk_fma_f32 v[166:167], v[142:143], v[114:115], v[166:167] op_sel:[0,1,0] op_sel_hi:[1,1,1]
	v_pk_fma_f32 v[168:169], v[144:145], v[114:115], v[168:169] op_sel:[0,1,0] op_sel_hi:[1,1,1]
	ds_read_b128 v[138:141], v192 offset:43008
	ds_read_b128 v[142:145], v192 offset:44032
	s_waitcnt lgkmcnt(6)
	v_pk_fma_f32 v[162:163], v[146:147], v[116:117], v[162:163] op_sel_hi:[1,0,1]
	v_pk_fma_f32 v[164:165], v[148:149], v[116:117], v[164:165] op_sel_hi:[1,0,1]
	v_pk_fma_f32 v[166:167], v[150:151], v[116:117], v[166:167] op_sel_hi:[1,0,1]
	v_pk_fma_f32 v[168:169], v[152:153], v[116:117], v[168:169] op_sel_hi:[1,0,1]
	ds_read_b128 v[146:149], v192 offset:45056
	ds_read_b128 v[150:153], v192 offset:46080
	s_waitcnt lgkmcnt(6)
	v_pk_fma_f32 v[162:163], v[154:155], v[116:117], v[162:163] op_sel:[0,1,0] op_sel_hi:[1,1,1]
	v_pk_fma_f32 v[164:165], v[156:157], v[116:117], v[164:165] op_sel:[0,1,0] op_sel_hi:[1,1,1]
	v_pk_fma_f32 v[166:167], v[158:159], v[116:117], v[166:167] op_sel:[0,1,0] op_sel_hi:[1,1,1]
	v_pk_fma_f32 v[168:169], v[160:161], v[116:117], v[168:169] op_sel:[0,1,0] op_sel_hi:[1,1,1]
	ds_read_b128 v[154:157], v192 offset:47104
	ds_read_b128 v[158:161], v192 offset:48128
	s_waitcnt lgkmcnt(6)
	v_pk_fma_f32 v[162:163], v[130:131], v[118:119], v[162:163] op_sel_hi:[1,0,1]
	v_pk_fma_f32 v[164:165], v[132:133], v[118:119], v[164:165] op_sel_hi:[1,0,1]
	v_pk_fma_f32 v[166:167], v[134:135], v[118:119], v[166:167] op_sel_hi:[1,0,1]
	v_pk_fma_f32 v[168:169], v[136:137], v[118:119], v[168:169] op_sel_hi:[1,0,1]
	ds_read_b128 v[130:133], v192 offset:49152
	ds_read_b128 v[134:137], v192 offset:50176
	s_waitcnt lgkmcnt(6)
	v_pk_fma_f32 v[162:163], v[138:139], v[118:119], v[162:163] op_sel:[0,1,0] op_sel_hi:[1,1,1]
	v_pk_fma_f32 v[164:165], v[140:141], v[118:119], v[164:165] op_sel:[0,1,0] op_sel_hi:[1,1,1]
	v_pk_fma_f32 v[166:167], v[142:143], v[118:119], v[166:167] op_sel:[0,1,0] op_sel_hi:[1,1,1]
	v_pk_fma_f32 v[168:169], v[144:145], v[118:119], v[168:169] op_sel:[0,1,0] op_sel_hi:[1,1,1]
	ds_read_b128 v[138:141], v192 offset:51200
	ds_read_b128 v[142:145], v192 offset:52224
	s_waitcnt lgkmcnt(6)
	v_pk_fma_f32 v[162:163], v[146:147], v[120:121], v[162:163] op_sel_hi:[1,0,1]
	v_pk_fma_f32 v[164:165], v[148:149], v[120:121], v[164:165] op_sel_hi:[1,0,1]
	v_pk_fma_f32 v[166:167], v[150:151], v[120:121], v[166:167] op_sel_hi:[1,0,1]
	v_pk_fma_f32 v[168:169], v[152:153], v[120:121], v[168:169] op_sel_hi:[1,0,1]
	ds_read_b128 v[146:149], v192 offset:53248
	ds_read_b128 v[150:153], v192 offset:54272
	s_waitcnt lgkmcnt(6)
	v_pk_fma_f32 v[162:163], v[154:155], v[120:121], v[162:163] op_sel:[0,1,0] op_sel_hi:[1,1,1]
	v_pk_fma_f32 v[164:165], v[156:157], v[120:121], v[164:165] op_sel:[0,1,0] op_sel_hi:[1,1,1]
	v_pk_fma_f32 v[166:167], v[158:159], v[120:121], v[166:167] op_sel:[0,1,0] op_sel_hi:[1,1,1]
	v_pk_fma_f32 v[168:169], v[160:161], v[120:121], v[168:169] op_sel:[0,1,0] op_sel_hi:[1,1,1]
	ds_read_b128 v[154:157], v192 offset:55296
	ds_read_b128 v[158:161], v192 offset:56320
	s_waitcnt lgkmcnt(6)
	v_pk_fma_f32 v[162:163], v[130:131], v[122:123], v[162:163] op_sel_hi:[1,0,1]
	v_pk_fma_f32 v[164:165], v[132:133], v[122:123], v[164:165] op_sel_hi:[1,0,1]
	v_pk_fma_f32 v[166:167], v[134:135], v[122:123], v[166:167] op_sel_hi:[1,0,1]
	v_pk_fma_f32 v[168:169], v[136:137], v[122:123], v[168:169] op_sel_hi:[1,0,1]
	ds_read_b128 v[130:133], v192 offset:57344
	ds_read_b128 v[134:137], v192 offset:58368
	s_waitcnt lgkmcnt(6)
	v_pk_fma_f32 v[162:163], v[138:139], v[122:123], v[162:163] op_sel:[0,1,0] op_sel_hi:[1,1,1]
	v_pk_fma_f32 v[164:165], v[140:141], v[122:123], v[164:165] op_sel:[0,1,0] op_sel_hi:[1,1,1]
	v_pk_fma_f32 v[166:167], v[142:143], v[122:123], v[166:167] op_sel:[0,1,0] op_sel_hi:[1,1,1]
	v_pk_fma_f32 v[168:169], v[144:145], v[122:123], v[168:169] op_sel:[0,1,0] op_sel_hi:[1,1,1]
	ds_read_b128 v[138:141], v192 offset:59392
	ds_read_b128 v[142:145], v192 offset:60416
	s_waitcnt lgkmcnt(6)
	v_pk_fma_f32 v[162:163], v[146:147], v[124:125], v[162:163] op_sel_hi:[1,0,1]
	v_pk_fma_f32 v[164:165], v[148:149], v[124:125], v[164:165] op_sel_hi:[1,0,1]
	v_pk_fma_f32 v[166:167], v[150:151], v[124:125], v[166:167] op_sel_hi:[1,0,1]
	v_pk_fma_f32 v[168:169], v[152:153], v[124:125], v[168:169] op_sel_hi:[1,0,1]
	ds_read_b128 v[146:149], v192 offset:61440
	ds_read_b128 v[150:153], v192 offset:62464
	s_waitcnt lgkmcnt(6)
	v_pk_fma_f32 v[162:163], v[154:155], v[124:125], v[162:163] op_sel:[0,1,0] op_sel_hi:[1,1,1]
	v_pk_fma_f32 v[164:165], v[156:157], v[124:125], v[164:165] op_sel:[0,1,0] op_sel_hi:[1,1,1]
	v_pk_fma_f32 v[166:167], v[158:159], v[124:125], v[166:167] op_sel:[0,1,0] op_sel_hi:[1,1,1]
	v_pk_fma_f32 v[168:169], v[160:161], v[124:125], v[168:169] op_sel:[0,1,0] op_sel_hi:[1,1,1]
	ds_read_b128 v[154:157], v192 offset:63488
	ds_read_b128 v[158:161], v192 offset:64512
	s_waitcnt lgkmcnt(6)
	v_pk_fma_f32 v[162:163], v[130:131], v[126:127], v[162:163] op_sel_hi:[1,0,1]
	v_pk_fma_f32 v[164:165], v[132:133], v[126:127], v[164:165] op_sel_hi:[1,0,1]
	v_pk_fma_f32 v[166:167], v[134:135], v[126:127], v[166:167] op_sel_hi:[1,0,1]
	v_pk_fma_f32 v[168:169], v[136:137], v[126:127], v[168:169] op_sel_hi:[1,0,1]
	s_waitcnt lgkmcnt(4)
	v_pk_fma_f32 v[162:163], v[138:139], v[126:127], v[162:163] op_sel:[0,1,0] op_sel_hi:[1,1,1]
	v_pk_fma_f32 v[164:165], v[140:141], v[126:127], v[164:165] op_sel:[0,1,0] op_sel_hi:[1,1,1]
	v_pk_fma_f32 v[166:167], v[142:143], v[126:127], v[166:167] op_sel:[0,1,0] op_sel_hi:[1,1,1]
	v_pk_fma_f32 v[168:169], v[144:145], v[126:127], v[168:169] op_sel:[0,1,0] op_sel_hi:[1,1,1]
	s_waitcnt lgkmcnt(2)
	v_pk_fma_f32 v[162:163], v[146:147], v[128:129], v[162:163] op_sel_hi:[1,0,1]
	v_pk_fma_f32 v[164:165], v[148:149], v[128:129], v[164:165] op_sel_hi:[1,0,1]
	v_pk_fma_f32 v[166:167], v[150:151], v[128:129], v[166:167] op_sel_hi:[1,0,1]
	v_pk_fma_f32 v[168:169], v[152:153], v[128:129], v[168:169] op_sel_hi:[1,0,1]
	s_waitcnt lgkmcnt(0)
	v_pk_fma_f32 v[162:163], v[154:155], v[128:129], v[162:163] op_sel:[0,1,0] op_sel_hi:[1,1,1]
	v_pk_fma_f32 v[164:165], v[156:157], v[128:129], v[164:165] op_sel:[0,1,0] op_sel_hi:[1,1,1]
	v_pk_fma_f32 v[166:167], v[158:159], v[128:129], v[166:167] op_sel:[0,1,0] op_sel_hi:[1,1,1]
	v_pk_fma_f32 v[168:169], v[160:161], v[128:129], v[168:169] op_sel:[0,1,0] op_sel_hi:[1,1,1]
	s_nop 1
	v_add_f32_dpp v162, v162, v162 quad_perm:[1,0,3,2] row_mask:0xf bank_mask:0xf
	v_add_f32_dpp v163, v163, v163 quad_perm:[1,0,3,2] row_mask:0xf bank_mask:0xf
	v_add_f32_dpp v164, v164, v164 quad_perm:[1,0,3,2] row_mask:0xf bank_mask:0xf
	v_add_f32_dpp v165, v165, v165 quad_perm:[1,0,3,2] row_mask:0xf bank_mask:0xf
	v_add_f32_dpp v166, v166, v166 quad_perm:[1,0,3,2] row_mask:0xf bank_mask:0xf
	v_add_f32_dpp v167, v167, v167 quad_perm:[1,0,3,2] row_mask:0xf bank_mask:0xf
	v_add_f32_dpp v168, v168, v168 quad_perm:[1,0,3,2] row_mask:0xf bank_mask:0xf
	v_add_f32_dpp v169, v169, v169 quad_perm:[1,0,3,2] row_mask:0xf bank_mask:0xf
	v_add_f32_dpp v162, v162, v162 quad_perm:[2,3,0,1] row_mask:0xf bank_mask:0xf
	v_add_f32_dpp v163, v163, v163 quad_perm:[2,3,0,1] row_mask:0xf bank_mask:0xf
	v_add_f32_dpp v164, v164, v164 quad_perm:[2,3,0,1] row_mask:0xf bank_mask:0xf
	v_add_f32_dpp v165, v165, v165 quad_perm:[2,3,0,1] row_mask:0xf bank_mask:0xf
	v_add_f32_dpp v166, v166, v166 quad_perm:[2,3,0,1] row_mask:0xf bank_mask:0xf
	v_add_f32_dpp v167, v167, v167 quad_perm:[2,3,0,1] row_mask:0xf bank_mask:0xf
	v_add_f32_dpp v168, v168, v168 quad_perm:[2,3,0,1] row_mask:0xf bank_mask:0xf
	v_add_f32_dpp v169, v169, v169 quad_perm:[2,3,0,1] row_mask:0xf bank_mask:0xf
	v_add_f32_dpp v162, v162, v162 row_half_mirror row_mask:0xf bank_mask:0xf
	v_add_f32_dpp v163, v163, v163 row_half_mirror row_mask:0xf bank_mask:0xf
	v_add_f32_dpp v164, v164, v164 row_half_mirror row_mask:0xf bank_mask:0xf
	v_add_f32_dpp v165, v165, v165 row_half_mirror row_mask:0xf bank_mask:0xf
	v_add_f32_dpp v166, v166, v166 row_half_mirror row_mask:0xf bank_mask:0xf
	v_add_f32_dpp v167, v167, v167 row_half_mirror row_mask:0xf bank_mask:0xf
	v_add_f32_dpp v168, v168, v168 row_half_mirror row_mask:0xf bank_mask:0xf
	v_add_f32_dpp v169, v169, v169 row_half_mirror row_mask:0xf bank_mask:0xf
	v_add_f32_dpp v162, v162, v162 row_mirror row_mask:0xf bank_mask:0xf
	v_add_f32_dpp v163, v163, v163 row_mirror row_mask:0xf bank_mask:0xf
	v_add_f32_dpp v164, v164, v164 row_mirror row_mask:0xf bank_mask:0xf
	v_add_f32_dpp v165, v165, v165 row_mirror row_mask:0xf bank_mask:0xf
	v_add_f32_dpp v166, v166, v166 row_mirror row_mask:0xf bank_mask:0xf
	v_add_f32_dpp v167, v167, v167 row_mirror row_mask:0xf bank_mask:0xf
	v_add_f32_dpp v168, v168, v168 row_mirror row_mask:0xf bank_mask:0xf
	v_add_f32_dpp v169, v169, v169 row_mirror row_mask:0xf bank_mask:0xf
	v_mov_b32_e32 v170, v162
	v_mov_b32_e32 v171, v163
	v_mov_b32_e32 v172, v164
	v_mov_b32_e32 v173, v165
	v_mov_b32_e32 v174, v166
	v_mov_b32_e32 v175, v167
	v_mov_b32_e32 v176, v168
	v_mov_b32_e32 v177, v169
	v_permlane16_swap_b32 v170, v162
	v_permlane16_swap_b32 v171, v163
	v_permlane16_swap_b32 v172, v164
	v_permlane16_swap_b32 v173, v165
	v_permlane16_swap_b32 v174, v166
	v_permlane16_swap_b32 v175, v167
	v_permlane16_swap_b32 v176, v168
	v_permlane16_swap_b32 v177, v169
	v_add_f32_e32 v162, v162, v170
	v_add_f32_e32 v163, v163, v171
	v_add_f32_e32 v164, v164, v172
	v_add_f32_e32 v165, v165, v173
	v_add_f32_e32 v166, v166, v174
	v_add_f32_e32 v167, v167, v175
	v_add_f32_e32 v168, v168, v176
	v_add_f32_e32 v169, v169, v177
	v_mov_b32_e32 v170, v162
	v_mov_b32_e32 v171, v163
	v_mov_b32_e32 v172, v164
	v_mov_b32_e32 v173, v165
	v_mov_b32_e32 v174, v166
	v_mov_b32_e32 v175, v167
	v_mov_b32_e32 v176, v168
	v_mov_b32_e32 v177, v169
	v_permlane32_swap_b32 v170, v162
	v_permlane32_swap_b32 v171, v163
	v_permlane32_swap_b32 v172, v164
	v_permlane32_swap_b32 v173, v165
	v_permlane32_swap_b32 v174, v166
	v_permlane32_swap_b32 v175, v167
	v_permlane32_swap_b32 v176, v168
	v_permlane32_swap_b32 v177, v169
	v_add_f32_e32 v162, v162, v170
	v_add_f32_e32 v163, v163, v171
	v_add_f32_e32 v164, v164, v172
	v_add_f32_e32 v165, v165, v173
	v_add_f32_e32 v166, v166, v174
	v_add_f32_e32 v167, v167, v175
	v_add_f32_e32 v168, v168, v176
	v_add_f32_e32 v169, v169, v177
	v_readfirstlane_b32 s98, v162
	v_readfirstlane_b32 s99, v163
	v_readfirstlane_b32 s100, v164
	v_readfirstlane_b32 s101, v165
	v_writelane_b32 v230, s98, 32
	v_writelane_b32 v230, s99, 33
	v_writelane_b32 v230, s100, 34
	v_writelane_b32 v230, s101, 35
	v_readfirstlane_b32 s98, v166
	v_readfirstlane_b32 s99, v167
	v_readfirstlane_b32 s100, v168
	v_readfirstlane_b32 s101, v169
	v_writelane_b32 v230, s98, 36
	v_writelane_b32 v230, s99, 37
	v_writelane_b32 v230, s100, 38
	v_writelane_b32 v230, s101, 39
	s_waitcnt vmcnt(16)
	v_pk_mul_f32 v[198:199], v[66:67], v[66:67]
	v_pk_mul_f32 v[200:201], v[68:69], v[68:69]
	v_pk_fma_f32 v[198:199], v[70:71], v[70:71], v[198:199]
	v_pk_fma_f32 v[200:201], v[72:73], v[72:73], v[200:201]
	v_pk_fma_f32 v[198:199], v[74:75], v[74:75], v[198:199]
	v_pk_fma_f32 v[200:201], v[76:77], v[76:77], v[200:201]
	v_pk_fma_f32 v[198:199], v[78:79], v[78:79], v[198:199]
	v_pk_fma_f32 v[200:201], v[80:81], v[80:81], v[200:201]
	v_pk_fma_f32 v[198:199], v[82:83], v[82:83], v[198:199]
	v_pk_fma_f32 v[200:201], v[84:85], v[84:85], v[200:201]
	v_pk_fma_f32 v[198:199], v[86:87], v[86:87], v[198:199]
	v_pk_fma_f32 v[200:201], v[88:89], v[88:89], v[200:201]
	v_pk_fma_f32 v[198:199], v[90:91], v[90:91], v[198:199]
	v_pk_fma_f32 v[200:201], v[92:93], v[92:93], v[200:201]
	v_pk_fma_f32 v[198:199], v[94:95], v[94:95], v[198:199]
	v_pk_fma_f32 v[200:201], v[96:97], v[96:97], v[200:201]
	v_pk_add_f32 v[198:199], v[198:199], v[200:201]
	v_add_f32_e32 v198, v198, v199
	s_nop 1
	v_add_f32_dpp v198, v198, v198 quad_perm:[1,0,3,2] row_mask:0xf bank_mask:0xf
	s_nop 1
	v_add_f32_dpp v198, v198, v198 quad_perm:[2,3,0,1] row_mask:0xf bank_mask:0xf
	s_nop 1
	v_add_f32_dpp v198, v198, v198 row_half_mirror row_mask:0xf bank_mask:0xf
	s_nop 1
	v_add_f32_dpp v198, v198, v198 row_mirror row_mask:0xf bank_mask:0xf
	v_mov_b32_e32 v199, v198
	s_nop 1
	v_permlane16_swap_b32 v199, v198
	v_add_f32_e32 v198, v198, v199
	v_mov_b32_e32 v199, v198
	s_nop 1
	v_permlane32_swap_b32 v199, v198
	v_add_f32_e32 v198, v198, v199
	ds_read_b128 v[130:133], v192
	ds_read_b128 v[134:137], v192 offset:1024
	ds_read_b128 v[138:141], v192 offset:2048
	ds_read_b128 v[142:145], v192 offset:3072
	ds_read_b128 v[146:149], v192 offset:4096
	ds_read_b128 v[150:153], v192 offset:5120
	ds_read_b128 v[154:157], v192 offset:6144
	ds_read_b128 v[158:161], v192 offset:7168
	v_fmamk_f32 v198, v198, 0x3a000000, v241
	v_mul_f32_e32 v199, 0x4b800000, v198
	v_cmp_gt_f32_e32 vcc, s17, v198
	s_nop 1
	v_cndmask_b32_e32 v198, v198, v199, vcc
	v_rsq_f32_e32 v198, v198
	s_nop 0
	v_mul_f32_e32 v199, 0x45800000, v198
	v_cndmask_b32_e32 v202, v198, v199, vcc
	v_pk_mul_f32 v[98:99], v[66:67], v[202:203] op_sel_hi:[1,0]
	v_pk_mul_f32 v[98:99], v[2:3], v[98:99]
	v_pk_mul_f32 v[100:101], v[68:69], v[202:203] op_sel_hi:[1,0]
	v_pk_mul_f32 v[100:101], v[4:5], v[100:101]
	v_cvt_pk_bf16_f32 v206, v98, v99
	v_cvt_pk_bf16_f32 v207, v100, v101
	global_store_dwordx2 v194, v[206:207], s[52:53]
	v_pk_mul_f32 v[102:103], v[70:71], v[202:203] op_sel_hi:[1,0]
	v_pk_mul_f32 v[102:103], v[6:7], v[102:103]
	v_pk_mul_f32 v[104:105], v[72:73], v[202:203] op_sel_hi:[1,0]
	v_pk_mul_f32 v[104:105], v[8:9], v[104:105]
	v_cvt_pk_bf16_f32 v206, v102, v103
	v_cvt_pk_bf16_f32 v207, v104, v105
	global_store_dwordx2 v194, v[206:207], s[52:53] offset:512
	v_pk_mul_f32 v[106:107], v[74:75], v[202:203] op_sel_hi:[1,0]
	v_pk_mul_f32 v[106:107], v[10:11], v[106:107]
	v_pk_mul_f32 v[108:109], v[76:77], v[202:203] op_sel_hi:[1,0]
	v_pk_mul_f32 v[108:109], v[12:13], v[108:109]
	v_cvt_pk_bf16_f32 v206, v106, v107
	v_cvt_pk_bf16_f32 v207, v108, v109
	global_store_dwordx2 v194, v[206:207], s[52:53] offset:1024
	v_pk_mul_f32 v[110:111], v[78:79], v[202:203] op_sel_hi:[1,0]
	v_pk_mul_f32 v[110:111], v[14:15], v[110:111]
	v_pk_mul_f32 v[112:113], v[80:81], v[202:203] op_sel_hi:[1,0]
	v_pk_mul_f32 v[112:113], v[16:17], v[112:113]
	v_cvt_pk_bf16_f32 v206, v110, v111
	v_cvt_pk_bf16_f32 v207, v112, v113
	global_store_dwordx2 v194, v[206:207], s[52:53] offset:1536
	v_pk_mul_f32 v[114:115], v[82:83], v[202:203] op_sel_hi:[1,0]
	v_pk_mul_f32 v[114:115], v[18:19], v[114:115]
	v_pk_mul_f32 v[116:117], v[84:85], v[202:203] op_sel_hi:[1,0]
	v_pk_mul_f32 v[116:117], v[20:21], v[116:117]
	v_cvt_pk_bf16_f32 v206, v114, v115
	v_cvt_pk_bf16_f32 v207, v116, v117
	global_store_dwordx2 v194, v[206:207], s[52:53] offset:2048
	v_pk_mul_f32 v[118:119], v[86:87], v[202:203] op_sel_hi:[1,0]
	v_pk_mul_f32 v[118:119], v[22:23], v[118:119]
	v_pk_mul_f32 v[120:121], v[88:89], v[202:203] op_sel_hi:[1,0]
	v_pk_mul_f32 v[120:121], v[24:25], v[120:121]
	v_cvt_pk_bf16_f32 v206, v118, v119
	v_cvt_pk_bf16_f32 v207, v120, v121
	global_store_dwordx2 v194, v[206:207], s[52:53] offset:2560
	v_pk_mul_f32 v[122:123], v[90:91], v[202:203] op_sel_hi:[1,0]
	v_pk_mul_f32 v[122:123], v[26:27], v[122:123]
	v_pk_mul_f32 v[124:125], v[92:93], v[202:203] op_sel_hi:[1,0]
	v_pk_mul_f32 v[124:125], v[28:29], v[124:125]
	v_cvt_pk_bf16_f32 v206, v122, v123
	v_cvt_pk_bf16_f32 v207, v124, v125
	global_store_dwordx2 v194, v[206:207], s[52:53] offset:3072
	v_pk_mul_f32 v[126:127], v[94:95], v[202:203] op_sel_hi:[1,0]
	v_pk_mul_f32 v[126:127], v[30:31], v[126:127]
	v_pk_mul_f32 v[128:129], v[96:97], v[202:203] op_sel_hi:[1,0]
	v_pk_mul_f32 v[128:129], v[32:33], v[128:129]
	v_cvt_pk_bf16_f32 v206, v126, v127
	v_cvt_pk_bf16_f32 v207, v128, v129
	global_store_dwordx2 v194, v[206:207], s[52:53] offset:3584
	v_add_u32_e32 v194, 0x800000, v194
	global_load_dwordx4 v[66:69], v193, s[12:13] offset:-4096 nt
	global_load_dwordx4 v[70:73], v193, s[12:13] offset:-3072 nt
	global_load_dwordx4 v[74:77], v193, s[12:13] offset:-2048 nt
	global_load_dwordx4 v[78:81], v193, s[12:13] offset:-1024 nt
	global_load_dwordx4 v[82:85], v193, s[12:13] offset:0 nt
	global_load_dwordx4 v[86:89], v193, s[12:13] offset:1024 nt
	global_load_dwordx4 v[90:93], v193, s[12:13] offset:2048 nt
	global_load_dwordx4 v[94:97], v193, s[12:13] offset:3072 nt
	v_add_u32_e32 v193, s0, v193
	s_waitcnt lgkmcnt(6)
	v_pk_mul_f32 v[162:163], v[130:131], v[98:99] op_sel_hi:[1,0]
	v_pk_mul_f32 v[164:165], v[132:133], v[98:99] op_sel_hi:[1,0]
	v_pk_mul_f32 v[166:167], v[134:135], v[98:99] op_sel_hi:[1,0]
	v_pk_mul_f32 v[168:169], v[136:137], v[98:99] op_sel_hi:[1,0]
	ds_read_b128 v[130:133], v192 offset:8192
	ds_read_b128 v[134:137], v192 offset:9216
	s_waitcnt lgkmcnt(6)
	v_pk_fma_f32 v[162:163], v[138:139], v[98:99], v[162:163] op_sel:[0,1,0] op_sel_hi:[1,1,1]
	v_pk_fma_f32 v[164:165], v[140:141], v[98:99], v[164:165] op_sel:[0,1,0] op_sel_hi:[1,1,1]
	v_pk_fma_f32 v[166:167], v[142:143], v[98:99], v[166:167] op_sel:[0,1,0] op_sel_hi:[1,1,1]
	v_pk_fma_f32 v[168:169], v[144:145], v[98:99], v[168:169] op_sel:[0,1,0] op_sel_hi:[1,1,1]
	ds_read_b128 v[138:141], v192 offset:10240
	ds_read_b128 v[142:145], v192 offset:11264
	s_waitcnt lgkmcnt(6)
	v_pk_fma_f32 v[162:163], v[146:147], v[100:101], v[162:163] op_sel_hi:[1,0,1]
	v_pk_fma_f32 v[164:165], v[148:149], v[100:101], v[164:165] op_sel_hi:[1,0,1]
	v_pk_fma_f32 v[166:167], v[150:151], v[100:101], v[166:167] op_sel_hi:[1,0,1]
	v_pk_fma_f32 v[168:169], v[152:153], v[100:101], v[168:169] op_sel_hi:[1,0,1]
	ds_read_b128 v[146:149], v192 offset:12288
	ds_read_b128 v[150:153], v192 offset:13312
	s_waitcnt lgkmcnt(6)
	v_pk_fma_f32 v[162:163], v[154:155], v[100:101], v[162:163] op_sel:[0,1,0] op_sel_hi:[1,1,1]
	v_pk_fma_f32 v[164:165], v[156:157], v[100:101], v[164:165] op_sel:[0,1,0] op_sel_hi:[1,1,1]
	v_pk_fma_f32 v[166:167], v[158:159], v[100:101], v[166:167] op_sel:[0,1,0] op_sel_hi:[1,1,1]
	v_pk_fma_f32 v[168:169], v[160:161], v[100:101], v[168:169] op_sel:[0,1,0] op_sel_hi:[1,1,1]
	ds_read_b128 v[154:157], v192 offset:14336
	ds_read_b128 v[158:161], v192 offset:15360
	s_waitcnt lgkmcnt(6)
	v_pk_fma_f32 v[162:163], v[130:131], v[102:103], v[162:163] op_sel_hi:[1,0,1]
	v_pk_fma_f32 v[164:165], v[132:133], v[102:103], v[164:165] op_sel_hi:[1,0,1]
	v_pk_fma_f32 v[166:167], v[134:135], v[102:103], v[166:167] op_sel_hi:[1,0,1]
	v_pk_fma_f32 v[168:169], v[136:137], v[102:103], v[168:169] op_sel_hi:[1,0,1]
	ds_read_b128 v[130:133], v192 offset:16384
	ds_read_b128 v[134:137], v192 offset:17408
	s_waitcnt lgkmcnt(6)
	v_pk_fma_f32 v[162:163], v[138:139], v[102:103], v[162:163] op_sel:[0,1,0] op_sel_hi:[1,1,1]
	v_pk_fma_f32 v[164:165], v[140:141], v[102:103], v[164:165] op_sel:[0,1,0] op_sel_hi:[1,1,1]
	v_pk_fma_f32 v[166:167], v[142:143], v[102:103], v[166:167] op_sel:[0,1,0] op_sel_hi:[1,1,1]
	v_pk_fma_f32 v[168:169], v[144:145], v[102:103], v[168:169] op_sel:[0,1,0] op_sel_hi:[1,1,1]
	ds_read_b128 v[138:141], v192 offset:18432
	ds_read_b128 v[142:145], v192 offset:19456
	s_waitcnt lgkmcnt(6)
	v_pk_fma_f32 v[162:163], v[146:147], v[104:105], v[162:163] op_sel_hi:[1,0,1]
	v_pk_fma_f32 v[164:165], v[148:149], v[104:105], v[164:165] op_sel_hi:[1,0,1]
	v_pk_fma_f32 v[166:167], v[150:151], v[104:105], v[166:167] op_sel_hi:[1,0,1]
	v_pk_fma_f32 v[168:169], v[152:153], v[104:105], v[168:169] op_sel_hi:[1,0,1]
	ds_read_b128 v[146:149], v192 offset:20480
	ds_read_b128 v[150:153], v192 offset:21504
	s_waitcnt lgkmcnt(6)
	v_pk_fma_f32 v[162:163], v[154:155], v[104:105], v[162:163] op_sel:[0,1,0] op_sel_hi:[1,1,1]
	v_pk_fma_f32 v[164:165], v[156:157], v[104:105], v[164:165] op_sel:[0,1,0] op_sel_hi:[1,1,1]
	v_pk_fma_f32 v[166:167], v[158:159], v[104:105], v[166:167] op_sel:[0,1,0] op_sel_hi:[1,1,1]
	v_pk_fma_f32 v[168:169], v[160:161], v[104:105], v[168:169] op_sel:[0,1,0] op_sel_hi:[1,1,1]
	ds_read_b128 v[154:157], v192 offset:22528
	ds_read_b128 v[158:161], v192 offset:23552
	s_waitcnt lgkmcnt(6)
	v_pk_fma_f32 v[162:163], v[130:131], v[106:107], v[162:163] op_sel_hi:[1,0,1]
	v_pk_fma_f32 v[164:165], v[132:133], v[106:107], v[164:165] op_sel_hi:[1,0,1]
	v_pk_fma_f32 v[166:167], v[134:135], v[106:107], v[166:167] op_sel_hi:[1,0,1]
	v_pk_fma_f32 v[168:169], v[136:137], v[106:107], v[168:169] op_sel_hi:[1,0,1]
	ds_read_b128 v[130:133], v192 offset:24576
	ds_read_b128 v[134:137], v192 offset:25600
	s_waitcnt lgkmcnt(6)
	v_pk_fma_f32 v[162:163], v[138:139], v[106:107], v[162:163] op_sel:[0,1,0] op_sel_hi:[1,1,1]
	v_pk_fma_f32 v[164:165], v[140:141], v[106:107], v[164:165] op_sel:[0,1,0] op_sel_hi:[1,1,1]
	v_pk_fma_f32 v[166:167], v[142:143], v[106:107], v[166:167] op_sel:[0,1,0] op_sel_hi:[1,1,1]
	v_pk_fma_f32 v[168:169], v[144:145], v[106:107], v[168:169] op_sel:[0,1,0] op_sel_hi:[1,1,1]
	ds_read_b128 v[138:141], v192 offset:26624
	ds_read_b128 v[142:145], v192 offset:27648
	s_waitcnt lgkmcnt(6)
	v_pk_fma_f32 v[162:163], v[146:147], v[108:109], v[162:163] op_sel_hi:[1,0,1]
	v_pk_fma_f32 v[164:165], v[148:149], v[108:109], v[164:165] op_sel_hi:[1,0,1]
	v_pk_fma_f32 v[166:167], v[150:151], v[108:109], v[166:167] op_sel_hi:[1,0,1]
	v_pk_fma_f32 v[168:169], v[152:153], v[108:109], v[168:169] op_sel_hi:[1,0,1]
	ds_read_b128 v[146:149], v192 offset:28672
	ds_read_b128 v[150:153], v192 offset:29696
	s_waitcnt lgkmcnt(6)
	v_pk_fma_f32 v[162:163], v[154:155], v[108:109], v[162:163] op_sel:[0,1,0] op_sel_hi:[1,1,1]
	v_pk_fma_f32 v[164:165], v[156:157], v[108:109], v[164:165] op_sel:[0,1,0] op_sel_hi:[1,1,1]
	v_pk_fma_f32 v[166:167], v[158:159], v[108:109], v[166:167] op_sel:[0,1,0] op_sel_hi:[1,1,1]
	v_pk_fma_f32 v[168:169], v[160:161], v[108:109], v[168:169] op_sel:[0,1,0] op_sel_hi:[1,1,1]
	ds_read_b128 v[154:157], v192 offset:30720
	ds_read_b128 v[158:161], v192 offset:31744
	s_waitcnt lgkmcnt(6)
	v_pk_fma_f32 v[162:163], v[130:131], v[110:111], v[162:163] op_sel_hi:[1,0,1]
	v_pk_fma_f32 v[164:165], v[132:133], v[110:111], v[164:165] op_sel_hi:[1,0,1]
	v_pk_fma_f32 v[166:167], v[134:135], v[110:111], v[166:167] op_sel_hi:[1,0,1]
	v_pk_fma_f32 v[168:169], v[136:137], v[110:111], v[168:169] op_sel_hi:[1,0,1]
	ds_read_b128 v[130:133], v192 offset:32768
	ds_read_b128 v[134:137], v192 offset:33792
	s_waitcnt lgkmcnt(6)
	v_pk_fma_f32 v[162:163], v[138:139], v[110:111], v[162:163] op_sel:[0,1,0] op_sel_hi:[1,1,1]
	v_pk_fma_f32 v[164:165], v[140:141], v[110:111], v[164:165] op_sel:[0,1,0] op_sel_hi:[1,1,1]
	v_pk_fma_f32 v[166:167], v[142:143], v[110:111], v[166:167] op_sel:[0,1,0] op_sel_hi:[1,1,1]
	v_pk_fma_f32 v[168:169], v[144:145], v[110:111], v[168:169] op_sel:[0,1,0] op_sel_hi:[1,1,1]
	ds_read_b128 v[138:141], v192 offset:34816
	ds_read_b128 v[142:145], v192 offset:35840
	s_waitcnt lgkmcnt(6)
	v_pk_fma_f32 v[162:163], v[146:147], v[112:113], v[162:163] op_sel_hi:[1,0,1]
	v_pk_fma_f32 v[164:165], v[148:149], v[112:113], v[164:165] op_sel_hi:[1,0,1]
	v_pk_fma_f32 v[166:167], v[150:151], v[112:113], v[166:167] op_sel_hi:[1,0,1]
	v_pk_fma_f32 v[168:169], v[152:153], v[112:113], v[168:169] op_sel_hi:[1,0,1]
	ds_read_b128 v[146:149], v192 offset:36864
	ds_read_b128 v[150:153], v192 offset:37888
	s_waitcnt lgkmcnt(6)
	v_pk_fma_f32 v[162:163], v[154:155], v[112:113], v[162:163] op_sel:[0,1,0] op_sel_hi:[1,1,1]
	v_pk_fma_f32 v[164:165], v[156:157], v[112:113], v[164:165] op_sel:[0,1,0] op_sel_hi:[1,1,1]
	v_pk_fma_f32 v[166:167], v[158:159], v[112:113], v[166:167] op_sel:[0,1,0] op_sel_hi:[1,1,1]
	v_pk_fma_f32 v[168:169], v[160:161], v[112:113], v[168:169] op_sel:[0,1,0] op_sel_hi:[1,1,1]
	ds_read_b128 v[154:157], v192 offset:38912
	ds_read_b128 v[158:161], v192 offset:39936
	s_waitcnt lgkmcnt(6)
	v_pk_fma_f32 v[162:163], v[130:131], v[114:115], v[162:163] op_sel_hi:[1,0,1]
	v_pk_fma_f32 v[164:165], v[132:133], v[114:115], v[164:165] op_sel_hi:[1,0,1]
	v_pk_fma_f32 v[166:167], v[134:135], v[114:115], v[166:167] op_sel_hi:[1,0,1]
	v_pk_fma_f32 v[168:169], v[136:137], v[114:115], v[168:169] op_sel_hi:[1,0,1]
	ds_read_b128 v[130:133], v192 offset:40960
	ds_read_b128 v[134:137], v192 offset:41984
	s_waitcnt lgkmcnt(6)
	v_pk_fma_f32 v[162:163], v[138:139], v[114:115], v[162:163] op_sel:[0,1,0] op_sel_hi:[1,1,1]
	v_pk_fma_f32 v[164:165], v[140:141], v[114:115], v[164:165] op_sel:[0,1,0] op_sel_hi:[1,1,1]
	v_pk_fma_f32 v[166:167], v[142:143], v[114:115], v[166:167] op_sel:[0,1,0] op_sel_hi:[1,1,1]
	v_pk_fma_f32 v[168:169], v[144:145], v[114:115], v[168:169] op_sel:[0,1,0] op_sel_hi:[1,1,1]
	ds_read_b128 v[138:141], v192 offset:43008
	ds_read_b128 v[142:145], v192 offset:44032
	s_waitcnt lgkmcnt(6)
	v_pk_fma_f32 v[162:163], v[146:147], v[116:117], v[162:163] op_sel_hi:[1,0,1]
	v_pk_fma_f32 v[164:165], v[148:149], v[116:117], v[164:165] op_sel_hi:[1,0,1]
	v_pk_fma_f32 v[166:167], v[150:151], v[116:117], v[166:167] op_sel_hi:[1,0,1]
	v_pk_fma_f32 v[168:169], v[152:153], v[116:117], v[168:169] op_sel_hi:[1,0,1]
	ds_read_b128 v[146:149], v192 offset:45056
	ds_read_b128 v[150:153], v192 offset:46080
	s_waitcnt lgkmcnt(6)
	v_pk_fma_f32 v[162:163], v[154:155], v[116:117], v[162:163] op_sel:[0,1,0] op_sel_hi:[1,1,1]
	v_pk_fma_f32 v[164:165], v[156:157], v[116:117], v[164:165] op_sel:[0,1,0] op_sel_hi:[1,1,1]
	v_pk_fma_f32 v[166:167], v[158:159], v[116:117], v[166:167] op_sel:[0,1,0] op_sel_hi:[1,1,1]
	v_pk_fma_f32 v[168:169], v[160:161], v[116:117], v[168:169] op_sel:[0,1,0] op_sel_hi:[1,1,1]
	ds_read_b128 v[154:157], v192 offset:47104
	ds_read_b128 v[158:161], v192 offset:48128
	s_waitcnt lgkmcnt(6)
	v_pk_fma_f32 v[162:163], v[130:131], v[118:119], v[162:163] op_sel_hi:[1,0,1]
	v_pk_fma_f32 v[164:165], v[132:133], v[118:119], v[164:165] op_sel_hi:[1,0,1]
	v_pk_fma_f32 v[166:167], v[134:135], v[118:119], v[166:167] op_sel_hi:[1,0,1]
	v_pk_fma_f32 v[168:169], v[136:137], v[118:119], v[168:169] op_sel_hi:[1,0,1]
	ds_read_b128 v[130:133], v192 offset:49152
	ds_read_b128 v[134:137], v192 offset:50176
	s_waitcnt lgkmcnt(6)
	v_pk_fma_f32 v[162:163], v[138:139], v[118:119], v[162:163] op_sel:[0,1,0] op_sel_hi:[1,1,1]
	v_pk_fma_f32 v[164:165], v[140:141], v[118:119], v[164:165] op_sel:[0,1,0] op_sel_hi:[1,1,1]
	v_pk_fma_f32 v[166:167], v[142:143], v[118:119], v[166:167] op_sel:[0,1,0] op_sel_hi:[1,1,1]
	v_pk_fma_f32 v[168:169], v[144:145], v[118:119], v[168:169] op_sel:[0,1,0] op_sel_hi:[1,1,1]
	ds_read_b128 v[138:141], v192 offset:51200
	ds_read_b128 v[142:145], v192 offset:52224
	s_waitcnt lgkmcnt(6)
	v_pk_fma_f32 v[162:163], v[146:147], v[120:121], v[162:163] op_sel_hi:[1,0,1]
	v_pk_fma_f32 v[164:165], v[148:149], v[120:121], v[164:165] op_sel_hi:[1,0,1]
	v_pk_fma_f32 v[166:167], v[150:151], v[120:121], v[166:167] op_sel_hi:[1,0,1]
	v_pk_fma_f32 v[168:169], v[152:153], v[120:121], v[168:169] op_sel_hi:[1,0,1]
	ds_read_b128 v[146:149], v192 offset:53248
	ds_read_b128 v[150:153], v192 offset:54272
	s_waitcnt lgkmcnt(6)
	v_pk_fma_f32 v[162:163], v[154:155], v[120:121], v[162:163] op_sel:[0,1,0] op_sel_hi:[1,1,1]
	v_pk_fma_f32 v[164:165], v[156:157], v[120:121], v[164:165] op_sel:[0,1,0] op_sel_hi:[1,1,1]
	v_pk_fma_f32 v[166:167], v[158:159], v[120:121], v[166:167] op_sel:[0,1,0] op_sel_hi:[1,1,1]
	v_pk_fma_f32 v[168:169], v[160:161], v[120:121], v[168:169] op_sel:[0,1,0] op_sel_hi:[1,1,1]
	ds_read_b128 v[154:157], v192 offset:55296
	ds_read_b128 v[158:161], v192 offset:56320
	s_waitcnt lgkmcnt(6)
	v_pk_fma_f32 v[162:163], v[130:131], v[122:123], v[162:163] op_sel_hi:[1,0,1]
	v_pk_fma_f32 v[164:165], v[132:133], v[122:123], v[164:165] op_sel_hi:[1,0,1]
	v_pk_fma_f32 v[166:167], v[134:135], v[122:123], v[166:167] op_sel_hi:[1,0,1]
	v_pk_fma_f32 v[168:169], v[136:137], v[122:123], v[168:169] op_sel_hi:[1,0,1]
	ds_read_b128 v[130:133], v192 offset:57344
	ds_read_b128 v[134:137], v192 offset:58368
	s_waitcnt lgkmcnt(6)
	v_pk_fma_f32 v[162:163], v[138:139], v[122:123], v[162:163] op_sel:[0,1,0] op_sel_hi:[1,1,1]
	v_pk_fma_f32 v[164:165], v[140:141], v[122:123], v[164:165] op_sel:[0,1,0] op_sel_hi:[1,1,1]
	v_pk_fma_f32 v[166:167], v[142:143], v[122:123], v[166:167] op_sel:[0,1,0] op_sel_hi:[1,1,1]
	v_pk_fma_f32 v[168:169], v[144:145], v[122:123], v[168:169] op_sel:[0,1,0] op_sel_hi:[1,1,1]
	ds_read_b128 v[138:141], v192 offset:59392
	ds_read_b128 v[142:145], v192 offset:60416
	s_waitcnt lgkmcnt(6)
	v_pk_fma_f32 v[162:163], v[146:147], v[124:125], v[162:163] op_sel_hi:[1,0,1]
	v_pk_fma_f32 v[164:165], v[148:149], v[124:125], v[164:165] op_sel_hi:[1,0,1]
	v_pk_fma_f32 v[166:167], v[150:151], v[124:125], v[166:167] op_sel_hi:[1,0,1]
	v_pk_fma_f32 v[168:169], v[152:153], v[124:125], v[168:169] op_sel_hi:[1,0,1]
	ds_read_b128 v[146:149], v192 offset:61440
	ds_read_b128 v[150:153], v192 offset:62464
	s_waitcnt lgkmcnt(6)
	v_pk_fma_f32 v[162:163], v[154:155], v[124:125], v[162:163] op_sel:[0,1,0] op_sel_hi:[1,1,1]
	v_pk_fma_f32 v[164:165], v[156:157], v[124:125], v[164:165] op_sel:[0,1,0] op_sel_hi:[1,1,1]
	v_pk_fma_f32 v[166:167], v[158:159], v[124:125], v[166:167] op_sel:[0,1,0] op_sel_hi:[1,1,1]
	v_pk_fma_f32 v[168:169], v[160:161], v[124:125], v[168:169] op_sel:[0,1,0] op_sel_hi:[1,1,1]
	ds_read_b128 v[154:157], v192 offset:63488
	ds_read_b128 v[158:161], v192 offset:64512
	s_waitcnt lgkmcnt(6)
	v_pk_fma_f32 v[162:163], v[130:131], v[126:127], v[162:163] op_sel_hi:[1,0,1]
	v_pk_fma_f32 v[164:165], v[132:133], v[126:127], v[164:165] op_sel_hi:[1,0,1]
	v_pk_fma_f32 v[166:167], v[134:135], v[126:127], v[166:167] op_sel_hi:[1,0,1]
	v_pk_fma_f32 v[168:169], v[136:137], v[126:127], v[168:169] op_sel_hi:[1,0,1]
	s_waitcnt lgkmcnt(4)
	v_pk_fma_f32 v[162:163], v[138:139], v[126:127], v[162:163] op_sel:[0,1,0] op_sel_hi:[1,1,1]
	v_pk_fma_f32 v[164:165], v[140:141], v[126:127], v[164:165] op_sel:[0,1,0] op_sel_hi:[1,1,1]
	v_pk_fma_f32 v[166:167], v[142:143], v[126:127], v[166:167] op_sel:[0,1,0] op_sel_hi:[1,1,1]
	v_pk_fma_f32 v[168:169], v[144:145], v[126:127], v[168:169] op_sel:[0,1,0] op_sel_hi:[1,1,1]
	s_waitcnt lgkmcnt(2)
	v_pk_fma_f32 v[162:163], v[146:147], v[128:129], v[162:163] op_sel_hi:[1,0,1]
	v_pk_fma_f32 v[164:165], v[148:149], v[128:129], v[164:165] op_sel_hi:[1,0,1]
	v_pk_fma_f32 v[166:167], v[150:151], v[128:129], v[166:167] op_sel_hi:[1,0,1]
	v_pk_fma_f32 v[168:169], v[152:153], v[128:129], v[168:169] op_sel_hi:[1,0,1]
	s_waitcnt lgkmcnt(0)
	v_pk_fma_f32 v[162:163], v[154:155], v[128:129], v[162:163] op_sel:[0,1,0] op_sel_hi:[1,1,1]
	v_pk_fma_f32 v[164:165], v[156:157], v[128:129], v[164:165] op_sel:[0,1,0] op_sel_hi:[1,1,1]
	v_pk_fma_f32 v[166:167], v[158:159], v[128:129], v[166:167] op_sel:[0,1,0] op_sel_hi:[1,1,1]
	v_pk_fma_f32 v[168:169], v[160:161], v[128:129], v[168:169] op_sel:[0,1,0] op_sel_hi:[1,1,1]
	s_nop 1
	v_add_f32_dpp v162, v162, v162 quad_perm:[1,0,3,2] row_mask:0xf bank_mask:0xf
	v_add_f32_dpp v163, v163, v163 quad_perm:[1,0,3,2] row_mask:0xf bank_mask:0xf
	v_add_f32_dpp v164, v164, v164 quad_perm:[1,0,3,2] row_mask:0xf bank_mask:0xf
	v_add_f32_dpp v165, v165, v165 quad_perm:[1,0,3,2] row_mask:0xf bank_mask:0xf
	v_add_f32_dpp v166, v166, v166 quad_perm:[1,0,3,2] row_mask:0xf bank_mask:0xf
	v_add_f32_dpp v167, v167, v167 quad_perm:[1,0,3,2] row_mask:0xf bank_mask:0xf
	v_add_f32_dpp v168, v168, v168 quad_perm:[1,0,3,2] row_mask:0xf bank_mask:0xf
	v_add_f32_dpp v169, v169, v169 quad_perm:[1,0,3,2] row_mask:0xf bank_mask:0xf
	v_add_f32_dpp v162, v162, v162 quad_perm:[2,3,0,1] row_mask:0xf bank_mask:0xf
	v_add_f32_dpp v163, v163, v163 quad_perm:[2,3,0,1] row_mask:0xf bank_mask:0xf
	v_add_f32_dpp v164, v164, v164 quad_perm:[2,3,0,1] row_mask:0xf bank_mask:0xf
	v_add_f32_dpp v165, v165, v165 quad_perm:[2,3,0,1] row_mask:0xf bank_mask:0xf
	v_add_f32_dpp v166, v166, v166 quad_perm:[2,3,0,1] row_mask:0xf bank_mask:0xf
	v_add_f32_dpp v167, v167, v167 quad_perm:[2,3,0,1] row_mask:0xf bank_mask:0xf
	v_add_f32_dpp v168, v168, v168 quad_perm:[2,3,0,1] row_mask:0xf bank_mask:0xf
	v_add_f32_dpp v169, v169, v169 quad_perm:[2,3,0,1] row_mask:0xf bank_mask:0xf
	v_add_f32_dpp v162, v162, v162 row_half_mirror row_mask:0xf bank_mask:0xf
	v_add_f32_dpp v163, v163, v163 row_half_mirror row_mask:0xf bank_mask:0xf
	v_add_f32_dpp v164, v164, v164 row_half_mirror row_mask:0xf bank_mask:0xf
	v_add_f32_dpp v165, v165, v165 row_half_mirror row_mask:0xf bank_mask:0xf
	v_add_f32_dpp v166, v166, v166 row_half_mirror row_mask:0xf bank_mask:0xf
	v_add_f32_dpp v167, v167, v167 row_half_mirror row_mask:0xf bank_mask:0xf
	v_add_f32_dpp v168, v168, v168 row_half_mirror row_mask:0xf bank_mask:0xf
	v_add_f32_dpp v169, v169, v169 row_half_mirror row_mask:0xf bank_mask:0xf
	v_add_f32_dpp v162, v162, v162 row_mirror row_mask:0xf bank_mask:0xf
	v_add_f32_dpp v163, v163, v163 row_mirror row_mask:0xf bank_mask:0xf
	v_add_f32_dpp v164, v164, v164 row_mirror row_mask:0xf bank_mask:0xf
	v_add_f32_dpp v165, v165, v165 row_mirror row_mask:0xf bank_mask:0xf
	v_add_f32_dpp v166, v166, v166 row_mirror row_mask:0xf bank_mask:0xf
	v_add_f32_dpp v167, v167, v167 row_mirror row_mask:0xf bank_mask:0xf
	v_add_f32_dpp v168, v168, v168 row_mirror row_mask:0xf bank_mask:0xf
	v_add_f32_dpp v169, v169, v169 row_mirror row_mask:0xf bank_mask:0xf
	v_mov_b32_e32 v170, v162
	v_mov_b32_e32 v171, v163
	v_mov_b32_e32 v172, v164
	v_mov_b32_e32 v173, v165
	v_mov_b32_e32 v174, v166
	v_mov_b32_e32 v175, v167
	v_mov_b32_e32 v176, v168
	v_mov_b32_e32 v177, v169
	v_permlane16_swap_b32 v170, v162
	v_permlane16_swap_b32 v171, v163
	v_permlane16_swap_b32 v172, v164
	v_permlane16_swap_b32 v173, v165
	v_permlane16_swap_b32 v174, v166
	v_permlane16_swap_b32 v175, v167
	v_permlane16_swap_b32 v176, v168
	v_permlane16_swap_b32 v177, v169
	v_add_f32_e32 v162, v162, v170
	v_add_f32_e32 v163, v163, v171
	v_add_f32_e32 v164, v164, v172
	v_add_f32_e32 v165, v165, v173
	v_add_f32_e32 v166, v166, v174
	v_add_f32_e32 v167, v167, v175
	v_add_f32_e32 v168, v168, v176
	v_add_f32_e32 v169, v169, v177
	v_mov_b32_e32 v170, v162
	v_mov_b32_e32 v171, v163
	v_mov_b32_e32 v172, v164
	v_mov_b32_e32 v173, v165
	v_mov_b32_e32 v174, v166
	v_mov_b32_e32 v175, v167
	v_mov_b32_e32 v176, v168
	v_mov_b32_e32 v177, v169
	v_permlane32_swap_b32 v170, v162
	v_permlane32_swap_b32 v171, v163
	v_permlane32_swap_b32 v172, v164
	v_permlane32_swap_b32 v173, v165
	v_permlane32_swap_b32 v174, v166
	v_permlane32_swap_b32 v175, v167
	v_permlane32_swap_b32 v176, v168
	v_permlane32_swap_b32 v177, v169
	v_add_f32_e32 v162, v162, v170
	v_add_f32_e32 v163, v163, v171
	v_add_f32_e32 v164, v164, v172
	v_add_f32_e32 v165, v165, v173
	v_add_f32_e32 v166, v166, v174
	v_add_f32_e32 v167, v167, v175
	v_add_f32_e32 v168, v168, v176
	v_add_f32_e32 v169, v169, v177
	v_readfirstlane_b32 s98, v162
	v_readfirstlane_b32 s99, v163
	v_readfirstlane_b32 s100, v164
	v_readfirstlane_b32 s101, v165
	v_writelane_b32 v230, s98, 40
	v_writelane_b32 v230, s99, 41
	v_writelane_b32 v230, s100, 42
	v_writelane_b32 v230, s101, 43
	v_readfirstlane_b32 s98, v166
	v_readfirstlane_b32 s99, v167
	v_readfirstlane_b32 s100, v168
	v_readfirstlane_b32 s101, v169
	v_writelane_b32 v230, s98, 44
	v_writelane_b32 v230, s99, 45
	v_writelane_b32 v230, s100, 46
	v_writelane_b32 v230, s101, 47
	s_waitcnt vmcnt(16)
	v_pk_mul_f32 v[198:199], v[34:35], v[34:35]
	v_pk_mul_f32 v[200:201], v[36:37], v[36:37]
	v_pk_fma_f32 v[198:199], v[38:39], v[38:39], v[198:199]
	v_pk_fma_f32 v[200:201], v[40:41], v[40:41], v[200:201]
	v_pk_fma_f32 v[198:199], v[42:43], v[42:43], v[198:199]
	v_pk_fma_f32 v[200:201], v[44:45], v[44:45], v[200:201]
	v_pk_fma_f32 v[198:199], v[46:47], v[46:47], v[198:199]
	v_pk_fma_f32 v[200:201], v[48:49], v[48:49], v[200:201]
	v_pk_fma_f32 v[198:199], v[50:51], v[50:51], v[198:199]
	v_pk_fma_f32 v[200:201], v[52:53], v[52:53], v[200:201]
	v_pk_fma_f32 v[198:199], v[54:55], v[54:55], v[198:199]
	v_pk_fma_f32 v[200:201], v[56:57], v[56:57], v[200:201]
	v_pk_fma_f32 v[198:199], v[58:59], v[58:59], v[198:199]
	v_pk_fma_f32 v[200:201], v[60:61], v[60:61], v[200:201]
	v_pk_fma_f32 v[198:199], v[62:63], v[62:63], v[198:199]
	v_pk_fma_f32 v[200:201], v[64:65], v[64:65], v[200:201]
	v_pk_add_f32 v[198:199], v[198:199], v[200:201]
	v_add_f32_e32 v198, v198, v199
	s_nop 1
	v_add_f32_dpp v198, v198, v198 quad_perm:[1,0,3,2] row_mask:0xf bank_mask:0xf
	s_nop 1
	v_add_f32_dpp v198, v198, v198 quad_perm:[2,3,0,1] row_mask:0xf bank_mask:0xf
	s_nop 1
	v_add_f32_dpp v198, v198, v198 row_half_mirror row_mask:0xf bank_mask:0xf
	s_nop 1
	v_add_f32_dpp v198, v198, v198 row_mirror row_mask:0xf bank_mask:0xf
	v_mov_b32_e32 v199, v198
	s_nop 1
	v_permlane16_swap_b32 v199, v198
	v_add_f32_e32 v198, v198, v199
	v_mov_b32_e32 v199, v198
	s_nop 1
	v_permlane32_swap_b32 v199, v198
	v_add_f32_e32 v198, v198, v199
	ds_read_b128 v[130:133], v192
	ds_read_b128 v[134:137], v192 offset:1024
	ds_read_b128 v[138:141], v192 offset:2048
	ds_read_b128 v[142:145], v192 offset:3072
	ds_read_b128 v[146:149], v192 offset:4096
	ds_read_b128 v[150:153], v192 offset:5120
	ds_read_b128 v[154:157], v192 offset:6144
	ds_read_b128 v[158:161], v192 offset:7168
	v_fmamk_f32 v198, v198, 0x3a000000, v241
	v_mul_f32_e32 v199, 0x4b800000, v198
	v_cmp_gt_f32_e32 vcc, s17, v198
	s_nop 1
	v_cndmask_b32_e32 v198, v198, v199, vcc
	v_rsq_f32_e32 v198, v198
	s_nop 0
	v_mul_f32_e32 v199, 0x45800000, v198
	v_cndmask_b32_e32 v202, v198, v199, vcc
	v_pk_mul_f32 v[98:99], v[34:35], v[202:203] op_sel_hi:[1,0]
	v_pk_mul_f32 v[98:99], v[2:3], v[98:99]
	v_pk_mul_f32 v[100:101], v[36:37], v[202:203] op_sel_hi:[1,0]
	v_pk_mul_f32 v[100:101], v[4:5], v[100:101]
	v_cvt_pk_bf16_f32 v206, v98, v99
	v_cvt_pk_bf16_f32 v207, v100, v101
	global_store_dwordx2 v194, v[206:207], s[52:53]
	v_pk_mul_f32 v[102:103], v[38:39], v[202:203] op_sel_hi:[1,0]
	v_pk_mul_f32 v[102:103], v[6:7], v[102:103]
	v_pk_mul_f32 v[104:105], v[40:41], v[202:203] op_sel_hi:[1,0]
	v_pk_mul_f32 v[104:105], v[8:9], v[104:105]
	v_cvt_pk_bf16_f32 v206, v102, v103
	v_cvt_pk_bf16_f32 v207, v104, v105
	global_store_dwordx2 v194, v[206:207], s[52:53] offset:512
	v_pk_mul_f32 v[106:107], v[42:43], v[202:203] op_sel_hi:[1,0]
	v_pk_mul_f32 v[106:107], v[10:11], v[106:107]
	v_pk_mul_f32 v[108:109], v[44:45], v[202:203] op_sel_hi:[1,0]
	v_pk_mul_f32 v[108:109], v[12:13], v[108:109]
	v_cvt_pk_bf16_f32 v206, v106, v107
	v_cvt_pk_bf16_f32 v207, v108, v109
	global_store_dwordx2 v194, v[206:207], s[52:53] offset:1024
	v_pk_mul_f32 v[110:111], v[46:47], v[202:203] op_sel_hi:[1,0]
	v_pk_mul_f32 v[110:111], v[14:15], v[110:111]
	v_pk_mul_f32 v[112:113], v[48:49], v[202:203] op_sel_hi:[1,0]
	v_pk_mul_f32 v[112:113], v[16:17], v[112:113]
	v_cvt_pk_bf16_f32 v206, v110, v111
	v_cvt_pk_bf16_f32 v207, v112, v113
	global_store_dwordx2 v194, v[206:207], s[52:53] offset:1536
	v_pk_mul_f32 v[114:115], v[50:51], v[202:203] op_sel_hi:[1,0]
	v_pk_mul_f32 v[114:115], v[18:19], v[114:115]
	v_pk_mul_f32 v[116:117], v[52:53], v[202:203] op_sel_hi:[1,0]
	v_pk_mul_f32 v[116:117], v[20:21], v[116:117]
	v_cvt_pk_bf16_f32 v206, v114, v115
	v_cvt_pk_bf16_f32 v207, v116, v117
	global_store_dwordx2 v194, v[206:207], s[52:53] offset:2048
	v_pk_mul_f32 v[118:119], v[54:55], v[202:203] op_sel_hi:[1,0]
	v_pk_mul_f32 v[118:119], v[22:23], v[118:119]
	v_pk_mul_f32 v[120:121], v[56:57], v[202:203] op_sel_hi:[1,0]
	v_pk_mul_f32 v[120:121], v[24:25], v[120:121]
	v_cvt_pk_bf16_f32 v206, v118, v119
	v_cvt_pk_bf16_f32 v207, v120, v121
	global_store_dwordx2 v194, v[206:207], s[52:53] offset:2560
	v_pk_mul_f32 v[122:123], v[58:59], v[202:203] op_sel_hi:[1,0]
	v_pk_mul_f32 v[122:123], v[26:27], v[122:123]
	v_pk_mul_f32 v[124:125], v[60:61], v[202:203] op_sel_hi:[1,0]
	v_pk_mul_f32 v[124:125], v[28:29], v[124:125]
	v_cvt_pk_bf16_f32 v206, v122, v123
	v_cvt_pk_bf16_f32 v207, v124, v125
	global_store_dwordx2 v194, v[206:207], s[52:53] offset:3072
	v_pk_mul_f32 v[126:127], v[62:63], v[202:203] op_sel_hi:[1,0]
	v_pk_mul_f32 v[126:127], v[30:31], v[126:127]
	v_pk_mul_f32 v[128:129], v[64:65], v[202:203] op_sel_hi:[1,0]
	v_pk_mul_f32 v[128:129], v[32:33], v[128:129]
	v_cvt_pk_bf16_f32 v206, v126, v127
	v_cvt_pk_bf16_f32 v207, v128, v129
	global_store_dwordx2 v194, v[206:207], s[52:53] offset:3584
	v_add_u32_e32 v194, 0x800000, v194
	s_waitcnt lgkmcnt(6)
	v_pk_mul_f32 v[162:163], v[130:131], v[98:99] op_sel_hi:[1,0]
	v_pk_mul_f32 v[164:165], v[132:133], v[98:99] op_sel_hi:[1,0]
	v_pk_mul_f32 v[166:167], v[134:135], v[98:99] op_sel_hi:[1,0]
	v_pk_mul_f32 v[168:169], v[136:137], v[98:99] op_sel_hi:[1,0]
	ds_read_b128 v[130:133], v192 offset:8192
	ds_read_b128 v[134:137], v192 offset:9216
	s_waitcnt lgkmcnt(6)
	v_pk_fma_f32 v[162:163], v[138:139], v[98:99], v[162:163] op_sel:[0,1,0] op_sel_hi:[1,1,1]
	v_pk_fma_f32 v[164:165], v[140:141], v[98:99], v[164:165] op_sel:[0,1,0] op_sel_hi:[1,1,1]
	v_pk_fma_f32 v[166:167], v[142:143], v[98:99], v[166:167] op_sel:[0,1,0] op_sel_hi:[1,1,1]
	v_pk_fma_f32 v[168:169], v[144:145], v[98:99], v[168:169] op_sel:[0,1,0] op_sel_hi:[1,1,1]
	ds_read_b128 v[138:141], v192 offset:10240
	ds_read_b128 v[142:145], v192 offset:11264
	s_waitcnt lgkmcnt(6)
	v_pk_fma_f32 v[162:163], v[146:147], v[100:101], v[162:163] op_sel_hi:[1,0,1]
	v_pk_fma_f32 v[164:165], v[148:149], v[100:101], v[164:165] op_sel_hi:[1,0,1]
	v_pk_fma_f32 v[166:167], v[150:151], v[100:101], v[166:167] op_sel_hi:[1,0,1]
	v_pk_fma_f32 v[168:169], v[152:153], v[100:101], v[168:169] op_sel_hi:[1,0,1]
	ds_read_b128 v[146:149], v192 offset:12288
	ds_read_b128 v[150:153], v192 offset:13312
	s_waitcnt lgkmcnt(6)
	v_pk_fma_f32 v[162:163], v[154:155], v[100:101], v[162:163] op_sel:[0,1,0] op_sel_hi:[1,1,1]
	v_pk_fma_f32 v[164:165], v[156:157], v[100:101], v[164:165] op_sel:[0,1,0] op_sel_hi:[1,1,1]
	v_pk_fma_f32 v[166:167], v[158:159], v[100:101], v[166:167] op_sel:[0,1,0] op_sel_hi:[1,1,1]
	v_pk_fma_f32 v[168:169], v[160:161], v[100:101], v[168:169] op_sel:[0,1,0] op_sel_hi:[1,1,1]
	ds_read_b128 v[154:157], v192 offset:14336
	ds_read_b128 v[158:161], v192 offset:15360
	s_waitcnt lgkmcnt(6)
	v_pk_fma_f32 v[162:163], v[130:131], v[102:103], v[162:163] op_sel_hi:[1,0,1]
	v_pk_fma_f32 v[164:165], v[132:133], v[102:103], v[164:165] op_sel_hi:[1,0,1]
	v_pk_fma_f32 v[166:167], v[134:135], v[102:103], v[166:167] op_sel_hi:[1,0,1]
	v_pk_fma_f32 v[168:169], v[136:137], v[102:103], v[168:169] op_sel_hi:[1,0,1]
	ds_read_b128 v[130:133], v192 offset:16384
	ds_read_b128 v[134:137], v192 offset:17408
	s_waitcnt lgkmcnt(6)
	v_pk_fma_f32 v[162:163], v[138:139], v[102:103], v[162:163] op_sel:[0,1,0] op_sel_hi:[1,1,1]
	v_pk_fma_f32 v[164:165], v[140:141], v[102:103], v[164:165] op_sel:[0,1,0] op_sel_hi:[1,1,1]
	v_pk_fma_f32 v[166:167], v[142:143], v[102:103], v[166:167] op_sel:[0,1,0] op_sel_hi:[1,1,1]
	v_pk_fma_f32 v[168:169], v[144:145], v[102:103], v[168:169] op_sel:[0,1,0] op_sel_hi:[1,1,1]
	ds_read_b128 v[138:141], v192 offset:18432
	ds_read_b128 v[142:145], v192 offset:19456
	s_waitcnt lgkmcnt(6)
	v_pk_fma_f32 v[162:163], v[146:147], v[104:105], v[162:163] op_sel_hi:[1,0,1]
	v_pk_fma_f32 v[164:165], v[148:149], v[104:105], v[164:165] op_sel_hi:[1,0,1]
	v_pk_fma_f32 v[166:167], v[150:151], v[104:105], v[166:167] op_sel_hi:[1,0,1]
	v_pk_fma_f32 v[168:169], v[152:153], v[104:105], v[168:169] op_sel_hi:[1,0,1]
	ds_read_b128 v[146:149], v192 offset:20480
	ds_read_b128 v[150:153], v192 offset:21504
	s_waitcnt lgkmcnt(6)
	v_pk_fma_f32 v[162:163], v[154:155], v[104:105], v[162:163] op_sel:[0,1,0] op_sel_hi:[1,1,1]
	v_pk_fma_f32 v[164:165], v[156:157], v[104:105], v[164:165] op_sel:[0,1,0] op_sel_hi:[1,1,1]
	v_pk_fma_f32 v[166:167], v[158:159], v[104:105], v[166:167] op_sel:[0,1,0] op_sel_hi:[1,1,1]
	v_pk_fma_f32 v[168:169], v[160:161], v[104:105], v[168:169] op_sel:[0,1,0] op_sel_hi:[1,1,1]
	ds_read_b128 v[154:157], v192 offset:22528
	ds_read_b128 v[158:161], v192 offset:23552
	s_waitcnt lgkmcnt(6)
	v_pk_fma_f32 v[162:163], v[130:131], v[106:107], v[162:163] op_sel_hi:[1,0,1]
	v_pk_fma_f32 v[164:165], v[132:133], v[106:107], v[164:165] op_sel_hi:[1,0,1]
	v_pk_fma_f32 v[166:167], v[134:135], v[106:107], v[166:167] op_sel_hi:[1,0,1]
	v_pk_fma_f32 v[168:169], v[136:137], v[106:107], v[168:169] op_sel_hi:[1,0,1]
	ds_read_b128 v[130:133], v192 offset:24576
	ds_read_b128 v[134:137], v192 offset:25600
	s_waitcnt lgkmcnt(6)
	v_pk_fma_f32 v[162:163], v[138:139], v[106:107], v[162:163] op_sel:[0,1,0] op_sel_hi:[1,1,1]
	v_pk_fma_f32 v[164:165], v[140:141], v[106:107], v[164:165] op_sel:[0,1,0] op_sel_hi:[1,1,1]
	v_pk_fma_f32 v[166:167], v[142:143], v[106:107], v[166:167] op_sel:[0,1,0] op_sel_hi:[1,1,1]
	v_pk_fma_f32 v[168:169], v[144:145], v[106:107], v[168:169] op_sel:[0,1,0] op_sel_hi:[1,1,1]
	ds_read_b128 v[138:141], v192 offset:26624
	ds_read_b128 v[142:145], v192 offset:27648
	s_waitcnt lgkmcnt(6)
	v_pk_fma_f32 v[162:163], v[146:147], v[108:109], v[162:163] op_sel_hi:[1,0,1]
	v_pk_fma_f32 v[164:165], v[148:149], v[108:109], v[164:165] op_sel_hi:[1,0,1]
	v_pk_fma_f32 v[166:167], v[150:151], v[108:109], v[166:167] op_sel_hi:[1,0,1]
	v_pk_fma_f32 v[168:169], v[152:153], v[108:109], v[168:169] op_sel_hi:[1,0,1]
	ds_read_b128 v[146:149], v192 offset:28672
	ds_read_b128 v[150:153], v192 offset:29696
	s_waitcnt lgkmcnt(6)
	v_pk_fma_f32 v[162:163], v[154:155], v[108:109], v[162:163] op_sel:[0,1,0] op_sel_hi:[1,1,1]
	v_pk_fma_f32 v[164:165], v[156:157], v[108:109], v[164:165] op_sel:[0,1,0] op_sel_hi:[1,1,1]
	v_pk_fma_f32 v[166:167], v[158:159], v[108:109], v[166:167] op_sel:[0,1,0] op_sel_hi:[1,1,1]
	v_pk_fma_f32 v[168:169], v[160:161], v[108:109], v[168:169] op_sel:[0,1,0] op_sel_hi:[1,1,1]
	ds_read_b128 v[154:157], v192 offset:30720
	ds_read_b128 v[158:161], v192 offset:31744
	s_waitcnt lgkmcnt(6)
	v_pk_fma_f32 v[162:163], v[130:131], v[110:111], v[162:163] op_sel_hi:[1,0,1]
	v_pk_fma_f32 v[164:165], v[132:133], v[110:111], v[164:165] op_sel_hi:[1,0,1]
	v_pk_fma_f32 v[166:167], v[134:135], v[110:111], v[166:167] op_sel_hi:[1,0,1]
	v_pk_fma_f32 v[168:169], v[136:137], v[110:111], v[168:169] op_sel_hi:[1,0,1]
	ds_read_b128 v[130:133], v192 offset:32768
	ds_read_b128 v[134:137], v192 offset:33792
	s_waitcnt lgkmcnt(6)
	v_pk_fma_f32 v[162:163], v[138:139], v[110:111], v[162:163] op_sel:[0,1,0] op_sel_hi:[1,1,1]
	v_pk_fma_f32 v[164:165], v[140:141], v[110:111], v[164:165] op_sel:[0,1,0] op_sel_hi:[1,1,1]
	v_pk_fma_f32 v[166:167], v[142:143], v[110:111], v[166:167] op_sel:[0,1,0] op_sel_hi:[1,1,1]
	v_pk_fma_f32 v[168:169], v[144:145], v[110:111], v[168:169] op_sel:[0,1,0] op_sel_hi:[1,1,1]
	ds_read_b128 v[138:141], v192 offset:34816
	ds_read_b128 v[142:145], v192 offset:35840
	s_waitcnt lgkmcnt(6)
	v_pk_fma_f32 v[162:163], v[146:147], v[112:113], v[162:163] op_sel_hi:[1,0,1]
	v_pk_fma_f32 v[164:165], v[148:149], v[112:113], v[164:165] op_sel_hi:[1,0,1]
	v_pk_fma_f32 v[166:167], v[150:151], v[112:113], v[166:167] op_sel_hi:[1,0,1]
	v_pk_fma_f32 v[168:169], v[152:153], v[112:113], v[168:169] op_sel_hi:[1,0,1]
	ds_read_b128 v[146:149], v192 offset:36864
	ds_read_b128 v[150:153], v192 offset:37888
	s_waitcnt lgkmcnt(6)
	v_pk_fma_f32 v[162:163], v[154:155], v[112:113], v[162:163] op_sel:[0,1,0] op_sel_hi:[1,1,1]
	v_pk_fma_f32 v[164:165], v[156:157], v[112:113], v[164:165] op_sel:[0,1,0] op_sel_hi:[1,1,1]
	v_pk_fma_f32 v[166:167], v[158:159], v[112:113], v[166:167] op_sel:[0,1,0] op_sel_hi:[1,1,1]
	v_pk_fma_f32 v[168:169], v[160:161], v[112:113], v[168:169] op_sel:[0,1,0] op_sel_hi:[1,1,1]
	ds_read_b128 v[154:157], v192 offset:38912
	ds_read_b128 v[158:161], v192 offset:39936
	s_waitcnt lgkmcnt(6)
	v_pk_fma_f32 v[162:163], v[130:131], v[114:115], v[162:163] op_sel_hi:[1,0,1]
	v_pk_fma_f32 v[164:165], v[132:133], v[114:115], v[164:165] op_sel_hi:[1,0,1]
	v_pk_fma_f32 v[166:167], v[134:135], v[114:115], v[166:167] op_sel_hi:[1,0,1]
	v_pk_fma_f32 v[168:169], v[136:137], v[114:115], v[168:169] op_sel_hi:[1,0,1]
	ds_read_b128 v[130:133], v192 offset:40960
	ds_read_b128 v[134:137], v192 offset:41984
	s_waitcnt lgkmcnt(6)
	v_pk_fma_f32 v[162:163], v[138:139], v[114:115], v[162:163] op_sel:[0,1,0] op_sel_hi:[1,1,1]
	v_pk_fma_f32 v[164:165], v[140:141], v[114:115], v[164:165] op_sel:[0,1,0] op_sel_hi:[1,1,1]
	v_pk_fma_f32 v[166:167], v[142:143], v[114:115], v[166:167] op_sel:[0,1,0] op_sel_hi:[1,1,1]
	v_pk_fma_f32 v[168:169], v[144:145], v[114:115], v[168:169] op_sel:[0,1,0] op_sel_hi:[1,1,1]
	ds_read_b128 v[138:141], v192 offset:43008
	ds_read_b128 v[142:145], v192 offset:44032
	s_waitcnt lgkmcnt(6)
	v_pk_fma_f32 v[162:163], v[146:147], v[116:117], v[162:163] op_sel_hi:[1,0,1]
	v_pk_fma_f32 v[164:165], v[148:149], v[116:117], v[164:165] op_sel_hi:[1,0,1]
	v_pk_fma_f32 v[166:167], v[150:151], v[116:117], v[166:167] op_sel_hi:[1,0,1]
	v_pk_fma_f32 v[168:169], v[152:153], v[116:117], v[168:169] op_sel_hi:[1,0,1]
	ds_read_b128 v[146:149], v192 offset:45056
	ds_read_b128 v[150:153], v192 offset:46080
	s_waitcnt lgkmcnt(6)
	v_pk_fma_f32 v[162:163], v[154:155], v[116:117], v[162:163] op_sel:[0,1,0] op_sel_hi:[1,1,1]
	v_pk_fma_f32 v[164:165], v[156:157], v[116:117], v[164:165] op_sel:[0,1,0] op_sel_hi:[1,1,1]
	v_pk_fma_f32 v[166:167], v[158:159], v[116:117], v[166:167] op_sel:[0,1,0] op_sel_hi:[1,1,1]
	v_pk_fma_f32 v[168:169], v[160:161], v[116:117], v[168:169] op_sel:[0,1,0] op_sel_hi:[1,1,1]
	ds_read_b128 v[154:157], v192 offset:47104
	ds_read_b128 v[158:161], v192 offset:48128
	s_waitcnt lgkmcnt(6)
	v_pk_fma_f32 v[162:163], v[130:131], v[118:119], v[162:163] op_sel_hi:[1,0,1]
	v_pk_fma_f32 v[164:165], v[132:133], v[118:119], v[164:165] op_sel_hi:[1,0,1]
	v_pk_fma_f32 v[166:167], v[134:135], v[118:119], v[166:167] op_sel_hi:[1,0,1]
	v_pk_fma_f32 v[168:169], v[136:137], v[118:119], v[168:169] op_sel_hi:[1,0,1]
	ds_read_b128 v[130:133], v192 offset:49152
	ds_read_b128 v[134:137], v192 offset:50176
	s_waitcnt lgkmcnt(6)
	v_pk_fma_f32 v[162:163], v[138:139], v[118:119], v[162:163] op_sel:[0,1,0] op_sel_hi:[1,1,1]
	v_pk_fma_f32 v[164:165], v[140:141], v[118:119], v[164:165] op_sel:[0,1,0] op_sel_hi:[1,1,1]
	v_pk_fma_f32 v[166:167], v[142:143], v[118:119], v[166:167] op_sel:[0,1,0] op_sel_hi:[1,1,1]
	v_pk_fma_f32 v[168:169], v[144:145], v[118:119], v[168:169] op_sel:[0,1,0] op_sel_hi:[1,1,1]
	ds_read_b128 v[138:141], v192 offset:51200
	ds_read_b128 v[142:145], v192 offset:52224
	s_waitcnt lgkmcnt(6)
	v_pk_fma_f32 v[162:163], v[146:147], v[120:121], v[162:163] op_sel_hi:[1,0,1]
	v_pk_fma_f32 v[164:165], v[148:149], v[120:121], v[164:165] op_sel_hi:[1,0,1]
	v_pk_fma_f32 v[166:167], v[150:151], v[120:121], v[166:167] op_sel_hi:[1,0,1]
	v_pk_fma_f32 v[168:169], v[152:153], v[120:121], v[168:169] op_sel_hi:[1,0,1]
	ds_read_b128 v[146:149], v192 offset:53248
	ds_read_b128 v[150:153], v192 offset:54272
	s_waitcnt lgkmcnt(6)
	v_pk_fma_f32 v[162:163], v[154:155], v[120:121], v[162:163] op_sel:[0,1,0] op_sel_hi:[1,1,1]
	v_pk_fma_f32 v[164:165], v[156:157], v[120:121], v[164:165] op_sel:[0,1,0] op_sel_hi:[1,1,1]
	v_pk_fma_f32 v[166:167], v[158:159], v[120:121], v[166:167] op_sel:[0,1,0] op_sel_hi:[1,1,1]
	v_pk_fma_f32 v[168:169], v[160:161], v[120:121], v[168:169] op_sel:[0,1,0] op_sel_hi:[1,1,1]
	ds_read_b128 v[154:157], v192 offset:55296
	ds_read_b128 v[158:161], v192 offset:56320
	s_waitcnt lgkmcnt(6)
	v_pk_fma_f32 v[162:163], v[130:131], v[122:123], v[162:163] op_sel_hi:[1,0,1]
	v_pk_fma_f32 v[164:165], v[132:133], v[122:123], v[164:165] op_sel_hi:[1,0,1]
	v_pk_fma_f32 v[166:167], v[134:135], v[122:123], v[166:167] op_sel_hi:[1,0,1]
	v_pk_fma_f32 v[168:169], v[136:137], v[122:123], v[168:169] op_sel_hi:[1,0,1]
	ds_read_b128 v[130:133], v192 offset:57344
	ds_read_b128 v[134:137], v192 offset:58368
	s_waitcnt lgkmcnt(6)
	v_pk_fma_f32 v[162:163], v[138:139], v[122:123], v[162:163] op_sel:[0,1,0] op_sel_hi:[1,1,1]
	v_pk_fma_f32 v[164:165], v[140:141], v[122:123], v[164:165] op_sel:[0,1,0] op_sel_hi:[1,1,1]
	v_pk_fma_f32 v[166:167], v[142:143], v[122:123], v[166:167] op_sel:[0,1,0] op_sel_hi:[1,1,1]
	v_pk_fma_f32 v[168:169], v[144:145], v[122:123], v[168:169] op_sel:[0,1,0] op_sel_hi:[1,1,1]
	ds_read_b128 v[138:141], v192 offset:59392
	ds_read_b128 v[142:145], v192 offset:60416
	s_waitcnt lgkmcnt(6)
	v_pk_fma_f32 v[162:163], v[146:147], v[124:125], v[162:163] op_sel_hi:[1,0,1]
	v_pk_fma_f32 v[164:165], v[148:149], v[124:125], v[164:165] op_sel_hi:[1,0,1]
	v_pk_fma_f32 v[166:167], v[150:151], v[124:125], v[166:167] op_sel_hi:[1,0,1]
	v_pk_fma_f32 v[168:169], v[152:153], v[124:125], v[168:169] op_sel_hi:[1,0,1]
	ds_read_b128 v[146:149], v192 offset:61440
	ds_read_b128 v[150:153], v192 offset:62464
	s_waitcnt lgkmcnt(6)
	v_pk_fma_f32 v[162:163], v[154:155], v[124:125], v[162:163] op_sel:[0,1,0] op_sel_hi:[1,1,1]
	v_pk_fma_f32 v[164:165], v[156:157], v[124:125], v[164:165] op_sel:[0,1,0] op_sel_hi:[1,1,1]
	v_pk_fma_f32 v[166:167], v[158:159], v[124:125], v[166:167] op_sel:[0,1,0] op_sel_hi:[1,1,1]
	v_pk_fma_f32 v[168:169], v[160:161], v[124:125], v[168:169] op_sel:[0,1,0] op_sel_hi:[1,1,1]
	ds_read_b128 v[154:157], v192 offset:63488
	ds_read_b128 v[158:161], v192 offset:64512
	s_waitcnt lgkmcnt(6)
	v_pk_fma_f32 v[162:163], v[130:131], v[126:127], v[162:163] op_sel_hi:[1,0,1]
	v_pk_fma_f32 v[164:165], v[132:133], v[126:127], v[164:165] op_sel_hi:[1,0,1]
	v_pk_fma_f32 v[166:167], v[134:135], v[126:127], v[166:167] op_sel_hi:[1,0,1]
	v_pk_fma_f32 v[168:169], v[136:137], v[126:127], v[168:169] op_sel_hi:[1,0,1]
	s_waitcnt lgkmcnt(4)
	v_pk_fma_f32 v[162:163], v[138:139], v[126:127], v[162:163] op_sel:[0,1,0] op_sel_hi:[1,1,1]
	v_pk_fma_f32 v[164:165], v[140:141], v[126:127], v[164:165] op_sel:[0,1,0] op_sel_hi:[1,1,1]
	v_pk_fma_f32 v[166:167], v[142:143], v[126:127], v[166:167] op_sel:[0,1,0] op_sel_hi:[1,1,1]
	v_pk_fma_f32 v[168:169], v[144:145], v[126:127], v[168:169] op_sel:[0,1,0] op_sel_hi:[1,1,1]
	s_waitcnt lgkmcnt(2)
	v_pk_fma_f32 v[162:163], v[146:147], v[128:129], v[162:163] op_sel_hi:[1,0,1]
	v_pk_fma_f32 v[164:165], v[148:149], v[128:129], v[164:165] op_sel_hi:[1,0,1]
	v_pk_fma_f32 v[166:167], v[150:151], v[128:129], v[166:167] op_sel_hi:[1,0,1]
	v_pk_fma_f32 v[168:169], v[152:153], v[128:129], v[168:169] op_sel_hi:[1,0,1]
	s_waitcnt lgkmcnt(0)
	v_pk_fma_f32 v[162:163], v[154:155], v[128:129], v[162:163] op_sel:[0,1,0] op_sel_hi:[1,1,1]
	v_pk_fma_f32 v[164:165], v[156:157], v[128:129], v[164:165] op_sel:[0,1,0] op_sel_hi:[1,1,1]
	v_pk_fma_f32 v[166:167], v[158:159], v[128:129], v[166:167] op_sel:[0,1,0] op_sel_hi:[1,1,1]
	v_pk_fma_f32 v[168:169], v[160:161], v[128:129], v[168:169] op_sel:[0,1,0] op_sel_hi:[1,1,1]
	s_nop 1
	v_add_f32_dpp v162, v162, v162 quad_perm:[1,0,3,2] row_mask:0xf bank_mask:0xf
	v_add_f32_dpp v163, v163, v163 quad_perm:[1,0,3,2] row_mask:0xf bank_mask:0xf
	v_add_f32_dpp v164, v164, v164 quad_perm:[1,0,3,2] row_mask:0xf bank_mask:0xf
	v_add_f32_dpp v165, v165, v165 quad_perm:[1,0,3,2] row_mask:0xf bank_mask:0xf
	v_add_f32_dpp v166, v166, v166 quad_perm:[1,0,3,2] row_mask:0xf bank_mask:0xf
	v_add_f32_dpp v167, v167, v167 quad_perm:[1,0,3,2] row_mask:0xf bank_mask:0xf
	v_add_f32_dpp v168, v168, v168 quad_perm:[1,0,3,2] row_mask:0xf bank_mask:0xf
	v_add_f32_dpp v169, v169, v169 quad_perm:[1,0,3,2] row_mask:0xf bank_mask:0xf
	v_add_f32_dpp v162, v162, v162 quad_perm:[2,3,0,1] row_mask:0xf bank_mask:0xf
	v_add_f32_dpp v163, v163, v163 quad_perm:[2,3,0,1] row_mask:0xf bank_mask:0xf
	v_add_f32_dpp v164, v164, v164 quad_perm:[2,3,0,1] row_mask:0xf bank_mask:0xf
	v_add_f32_dpp v165, v165, v165 quad_perm:[2,3,0,1] row_mask:0xf bank_mask:0xf
	v_add_f32_dpp v166, v166, v166 quad_perm:[2,3,0,1] row_mask:0xf bank_mask:0xf
	v_add_f32_dpp v167, v167, v167 quad_perm:[2,3,0,1] row_mask:0xf bank_mask:0xf
	v_add_f32_dpp v168, v168, v168 quad_perm:[2,3,0,1] row_mask:0xf bank_mask:0xf
	v_add_f32_dpp v169, v169, v169 quad_perm:[2,3,0,1] row_mask:0xf bank_mask:0xf
	v_add_f32_dpp v162, v162, v162 row_half_mirror row_mask:0xf bank_mask:0xf
	v_add_f32_dpp v163, v163, v163 row_half_mirror row_mask:0xf bank_mask:0xf
	v_add_f32_dpp v164, v164, v164 row_half_mirror row_mask:0xf bank_mask:0xf
	v_add_f32_dpp v165, v165, v165 row_half_mirror row_mask:0xf bank_mask:0xf
	v_add_f32_dpp v166, v166, v166 row_half_mirror row_mask:0xf bank_mask:0xf
	v_add_f32_dpp v167, v167, v167 row_half_mirror row_mask:0xf bank_mask:0xf
	v_add_f32_dpp v168, v168, v168 row_half_mirror row_mask:0xf bank_mask:0xf
	v_add_f32_dpp v169, v169, v169 row_half_mirror row_mask:0xf bank_mask:0xf
	v_add_f32_dpp v162, v162, v162 row_mirror row_mask:0xf bank_mask:0xf
	v_add_f32_dpp v163, v163, v163 row_mirror row_mask:0xf bank_mask:0xf
	v_add_f32_dpp v164, v164, v164 row_mirror row_mask:0xf bank_mask:0xf
	v_add_f32_dpp v165, v165, v165 row_mirror row_mask:0xf bank_mask:0xf
	v_add_f32_dpp v166, v166, v166 row_mirror row_mask:0xf bank_mask:0xf
	v_add_f32_dpp v167, v167, v167 row_mirror row_mask:0xf bank_mask:0xf
	v_add_f32_dpp v168, v168, v168 row_mirror row_mask:0xf bank_mask:0xf
	v_add_f32_dpp v169, v169, v169 row_mirror row_mask:0xf bank_mask:0xf
	v_mov_b32_e32 v170, v162
	v_mov_b32_e32 v171, v163
	v_mov_b32_e32 v172, v164
	v_mov_b32_e32 v173, v165
	v_mov_b32_e32 v174, v166
	v_mov_b32_e32 v175, v167
	v_mov_b32_e32 v176, v168
	v_mov_b32_e32 v177, v169
	v_permlane16_swap_b32 v170, v162
	v_permlane16_swap_b32 v171, v163
	v_permlane16_swap_b32 v172, v164
	v_permlane16_swap_b32 v173, v165
	v_permlane16_swap_b32 v174, v166
	v_permlane16_swap_b32 v175, v167
	v_permlane16_swap_b32 v176, v168
	v_permlane16_swap_b32 v177, v169
	v_add_f32_e32 v162, v162, v170
	v_add_f32_e32 v163, v163, v171
	v_add_f32_e32 v164, v164, v172
	v_add_f32_e32 v165, v165, v173
	v_add_f32_e32 v166, v166, v174
	v_add_f32_e32 v167, v167, v175
	v_add_f32_e32 v168, v168, v176
	v_add_f32_e32 v169, v169, v177
	v_mov_b32_e32 v170, v162
	v_mov_b32_e32 v171, v163
	v_mov_b32_e32 v172, v164
	v_mov_b32_e32 v173, v165
	v_mov_b32_e32 v174, v166
	v_mov_b32_e32 v175, v167
	v_mov_b32_e32 v176, v168
	v_mov_b32_e32 v177, v169
	v_permlane32_swap_b32 v170, v162
	v_permlane32_swap_b32 v171, v163
	v_permlane32_swap_b32 v172, v164
	v_permlane32_swap_b32 v173, v165
	v_permlane32_swap_b32 v174, v166
	v_permlane32_swap_b32 v175, v167
	v_permlane32_swap_b32 v176, v168
	v_permlane32_swap_b32 v177, v169
	v_add_f32_e32 v162, v162, v170
	v_add_f32_e32 v163, v163, v171
	v_add_f32_e32 v164, v164, v172
	v_add_f32_e32 v165, v165, v173
	v_add_f32_e32 v166, v166, v174
	v_add_f32_e32 v167, v167, v175
	v_add_f32_e32 v168, v168, v176
	v_add_f32_e32 v169, v169, v177
	v_readfirstlane_b32 s98, v162
	v_readfirstlane_b32 s99, v163
	v_readfirstlane_b32 s100, v164
	v_readfirstlane_b32 s101, v165
	v_writelane_b32 v230, s98, 48
	v_writelane_b32 v230, s99, 49
	v_writelane_b32 v230, s100, 50
	v_writelane_b32 v230, s101, 51
	v_readfirstlane_b32 s98, v166
	v_readfirstlane_b32 s99, v167
	v_readfirstlane_b32 s100, v168
	v_readfirstlane_b32 s101, v169
	v_writelane_b32 v230, s98, 52
	v_writelane_b32 v230, s99, 53
	v_writelane_b32 v230, s100, 54
	v_writelane_b32 v230, s101, 55
	s_waitcnt vmcnt(8)
	v_pk_mul_f32 v[198:199], v[66:67], v[66:67]
	v_pk_mul_f32 v[200:201], v[68:69], v[68:69]
	v_pk_fma_f32 v[198:199], v[70:71], v[70:71], v[198:199]
	v_pk_fma_f32 v[200:201], v[72:73], v[72:73], v[200:201]
	v_pk_fma_f32 v[198:199], v[74:75], v[74:75], v[198:199]
	v_pk_fma_f32 v[200:201], v[76:77], v[76:77], v[200:201]
	v_pk_fma_f32 v[198:199], v[78:79], v[78:79], v[198:199]
	v_pk_fma_f32 v[200:201], v[80:81], v[80:81], v[200:201]
	v_pk_fma_f32 v[198:199], v[82:83], v[82:83], v[198:199]
	v_pk_fma_f32 v[200:201], v[84:85], v[84:85], v[200:201]
	v_pk_fma_f32 v[198:199], v[86:87], v[86:87], v[198:199]
	v_pk_fma_f32 v[200:201], v[88:89], v[88:89], v[200:201]
	v_pk_fma_f32 v[198:199], v[90:91], v[90:91], v[198:199]
	v_pk_fma_f32 v[200:201], v[92:93], v[92:93], v[200:201]
	v_pk_fma_f32 v[198:199], v[94:95], v[94:95], v[198:199]
	v_pk_fma_f32 v[200:201], v[96:97], v[96:97], v[200:201]
	v_pk_add_f32 v[198:199], v[198:199], v[200:201]
	v_add_f32_e32 v198, v198, v199
	s_nop 1
	v_add_f32_dpp v198, v198, v198 quad_perm:[1,0,3,2] row_mask:0xf bank_mask:0xf
	s_nop 1
	v_add_f32_dpp v198, v198, v198 quad_perm:[2,3,0,1] row_mask:0xf bank_mask:0xf
	s_nop 1
	v_add_f32_dpp v198, v198, v198 row_half_mirror row_mask:0xf bank_mask:0xf
	s_nop 1
	v_add_f32_dpp v198, v198, v198 row_mirror row_mask:0xf bank_mask:0xf
	v_mov_b32_e32 v199, v198
	s_nop 1
	v_permlane16_swap_b32 v199, v198
	v_add_f32_e32 v198, v198, v199
	v_mov_b32_e32 v199, v198
	s_nop 1
	v_permlane32_swap_b32 v199, v198
	v_add_f32_e32 v198, v198, v199
	ds_read_b128 v[130:133], v192
	ds_read_b128 v[134:137], v192 offset:1024
	ds_read_b128 v[138:141], v192 offset:2048
	ds_read_b128 v[142:145], v192 offset:3072
	ds_read_b128 v[146:149], v192 offset:4096
	ds_read_b128 v[150:153], v192 offset:5120
	ds_read_b128 v[154:157], v192 offset:6144
	ds_read_b128 v[158:161], v192 offset:7168
	v_fmamk_f32 v198, v198, 0x3a000000, v241
	v_mul_f32_e32 v199, 0x4b800000, v198
	v_cmp_gt_f32_e32 vcc, s17, v198
	s_nop 1
	v_cndmask_b32_e32 v198, v198, v199, vcc
	v_rsq_f32_e32 v198, v198
	s_nop 0
	v_mul_f32_e32 v199, 0x45800000, v198
	v_cndmask_b32_e32 v202, v198, v199, vcc
	v_pk_mul_f32 v[98:99], v[66:67], v[202:203] op_sel_hi:[1,0]
	v_pk_mul_f32 v[98:99], v[2:3], v[98:99]
	v_pk_mul_f32 v[100:101], v[68:69], v[202:203] op_sel_hi:[1,0]
	v_pk_mul_f32 v[100:101], v[4:5], v[100:101]
	v_cvt_pk_bf16_f32 v206, v98, v99
	v_cvt_pk_bf16_f32 v207, v100, v101
	global_store_dwordx2 v194, v[206:207], s[52:53]
	v_pk_mul_f32 v[102:103], v[70:71], v[202:203] op_sel_hi:[1,0]
	v_pk_mul_f32 v[102:103], v[6:7], v[102:103]
	v_pk_mul_f32 v[104:105], v[72:73], v[202:203] op_sel_hi:[1,0]
	v_pk_mul_f32 v[104:105], v[8:9], v[104:105]
	v_cvt_pk_bf16_f32 v206, v102, v103
	v_cvt_pk_bf16_f32 v207, v104, v105
	global_store_dwordx2 v194, v[206:207], s[52:53] offset:512
	v_pk_mul_f32 v[106:107], v[74:75], v[202:203] op_sel_hi:[1,0]
	v_pk_mul_f32 v[106:107], v[10:11], v[106:107]
	v_pk_mul_f32 v[108:109], v[76:77], v[202:203] op_sel_hi:[1,0]
	v_pk_mul_f32 v[108:109], v[12:13], v[108:109]
	v_cvt_pk_bf16_f32 v206, v106, v107
	v_cvt_pk_bf16_f32 v207, v108, v109
	global_store_dwordx2 v194, v[206:207], s[52:53] offset:1024
	v_pk_mul_f32 v[110:111], v[78:79], v[202:203] op_sel_hi:[1,0]
	v_pk_mul_f32 v[110:111], v[14:15], v[110:111]
	v_pk_mul_f32 v[112:113], v[80:81], v[202:203] op_sel_hi:[1,0]
	v_pk_mul_f32 v[112:113], v[16:17], v[112:113]
	v_cvt_pk_bf16_f32 v206, v110, v111
	v_cvt_pk_bf16_f32 v207, v112, v113
	global_store_dwordx2 v194, v[206:207], s[52:53] offset:1536
	v_pk_mul_f32 v[114:115], v[82:83], v[202:203] op_sel_hi:[1,0]
	v_pk_mul_f32 v[114:115], v[18:19], v[114:115]
	v_pk_mul_f32 v[116:117], v[84:85], v[202:203] op_sel_hi:[1,0]
	v_pk_mul_f32 v[116:117], v[20:21], v[116:117]
	v_cvt_pk_bf16_f32 v206, v114, v115
	v_cvt_pk_bf16_f32 v207, v116, v117
	global_store_dwordx2 v194, v[206:207], s[52:53] offset:2048
	v_pk_mul_f32 v[118:119], v[86:87], v[202:203] op_sel_hi:[1,0]
	v_pk_mul_f32 v[118:119], v[22:23], v[118:119]
	v_pk_mul_f32 v[120:121], v[88:89], v[202:203] op_sel_hi:[1,0]
	v_pk_mul_f32 v[120:121], v[24:25], v[120:121]
	v_cvt_pk_bf16_f32 v206, v118, v119
	v_cvt_pk_bf16_f32 v207, v120, v121
	global_store_dwordx2 v194, v[206:207], s[52:53] offset:2560
	v_pk_mul_f32 v[122:123], v[90:91], v[202:203] op_sel_hi:[1,0]
	v_pk_mul_f32 v[122:123], v[26:27], v[122:123]
	v_pk_mul_f32 v[124:125], v[92:93], v[202:203] op_sel_hi:[1,0]
	v_pk_mul_f32 v[124:125], v[28:29], v[124:125]
	v_cvt_pk_bf16_f32 v206, v122, v123
	v_cvt_pk_bf16_f32 v207, v124, v125
	global_store_dwordx2 v194, v[206:207], s[52:53] offset:3072
	v_pk_mul_f32 v[126:127], v[94:95], v[202:203] op_sel_hi:[1,0]
	v_pk_mul_f32 v[126:127], v[30:31], v[126:127]
	v_pk_mul_f32 v[128:129], v[96:97], v[202:203] op_sel_hi:[1,0]
	v_pk_mul_f32 v[128:129], v[32:33], v[128:129]
	v_cvt_pk_bf16_f32 v206, v126, v127
	v_cvt_pk_bf16_f32 v207, v128, v129
	global_store_dwordx2 v194, v[206:207], s[52:53] offset:3584
	v_add_u32_e32 v194, 0x800000, v194
	s_waitcnt lgkmcnt(6)
	v_pk_mul_f32 v[162:163], v[130:131], v[98:99] op_sel_hi:[1,0]
	v_pk_mul_f32 v[164:165], v[132:133], v[98:99] op_sel_hi:[1,0]
	v_pk_mul_f32 v[166:167], v[134:135], v[98:99] op_sel_hi:[1,0]
	v_pk_mul_f32 v[168:169], v[136:137], v[98:99] op_sel_hi:[1,0]
	ds_read_b128 v[130:133], v192 offset:8192
	ds_read_b128 v[134:137], v192 offset:9216
	s_waitcnt lgkmcnt(6)
	v_pk_fma_f32 v[162:163], v[138:139], v[98:99], v[162:163] op_sel:[0,1,0] op_sel_hi:[1,1,1]
	v_pk_fma_f32 v[164:165], v[140:141], v[98:99], v[164:165] op_sel:[0,1,0] op_sel_hi:[1,1,1]
	v_pk_fma_f32 v[166:167], v[142:143], v[98:99], v[166:167] op_sel:[0,1,0] op_sel_hi:[1,1,1]
	v_pk_fma_f32 v[168:169], v[144:145], v[98:99], v[168:169] op_sel:[0,1,0] op_sel_hi:[1,1,1]
	ds_read_b128 v[138:141], v192 offset:10240
	ds_read_b128 v[142:145], v192 offset:11264
	s_waitcnt lgkmcnt(6)
	v_pk_fma_f32 v[162:163], v[146:147], v[100:101], v[162:163] op_sel_hi:[1,0,1]
	v_pk_fma_f32 v[164:165], v[148:149], v[100:101], v[164:165] op_sel_hi:[1,0,1]
	v_pk_fma_f32 v[166:167], v[150:151], v[100:101], v[166:167] op_sel_hi:[1,0,1]
	v_pk_fma_f32 v[168:169], v[152:153], v[100:101], v[168:169] op_sel_hi:[1,0,1]
	ds_read_b128 v[146:149], v192 offset:12288
	ds_read_b128 v[150:153], v192 offset:13312
	s_waitcnt lgkmcnt(6)
	v_pk_fma_f32 v[162:163], v[154:155], v[100:101], v[162:163] op_sel:[0,1,0] op_sel_hi:[1,1,1]
	v_pk_fma_f32 v[164:165], v[156:157], v[100:101], v[164:165] op_sel:[0,1,0] op_sel_hi:[1,1,1]
	v_pk_fma_f32 v[166:167], v[158:159], v[100:101], v[166:167] op_sel:[0,1,0] op_sel_hi:[1,1,1]
	v_pk_fma_f32 v[168:169], v[160:161], v[100:101], v[168:169] op_sel:[0,1,0] op_sel_hi:[1,1,1]
	ds_read_b128 v[154:157], v192 offset:14336
	ds_read_b128 v[158:161], v192 offset:15360
	s_waitcnt lgkmcnt(6)
	v_pk_fma_f32 v[162:163], v[130:131], v[102:103], v[162:163] op_sel_hi:[1,0,1]
	v_pk_fma_f32 v[164:165], v[132:133], v[102:103], v[164:165] op_sel_hi:[1,0,1]
	v_pk_fma_f32 v[166:167], v[134:135], v[102:103], v[166:167] op_sel_hi:[1,0,1]
	v_pk_fma_f32 v[168:169], v[136:137], v[102:103], v[168:169] op_sel_hi:[1,0,1]
	ds_read_b128 v[130:133], v192 offset:16384
	ds_read_b128 v[134:137], v192 offset:17408
	s_waitcnt lgkmcnt(6)
	v_pk_fma_f32 v[162:163], v[138:139], v[102:103], v[162:163] op_sel:[0,1,0] op_sel_hi:[1,1,1]
	v_pk_fma_f32 v[164:165], v[140:141], v[102:103], v[164:165] op_sel:[0,1,0] op_sel_hi:[1,1,1]
	v_pk_fma_f32 v[166:167], v[142:143], v[102:103], v[166:167] op_sel:[0,1,0] op_sel_hi:[1,1,1]
	v_pk_fma_f32 v[168:169], v[144:145], v[102:103], v[168:169] op_sel:[0,1,0] op_sel_hi:[1,1,1]
	ds_read_b128 v[138:141], v192 offset:18432
	ds_read_b128 v[142:145], v192 offset:19456
	s_waitcnt lgkmcnt(6)
	v_pk_fma_f32 v[162:163], v[146:147], v[104:105], v[162:163] op_sel_hi:[1,0,1]
	v_pk_fma_f32 v[164:165], v[148:149], v[104:105], v[164:165] op_sel_hi:[1,0,1]
	v_pk_fma_f32 v[166:167], v[150:151], v[104:105], v[166:167] op_sel_hi:[1,0,1]
	v_pk_fma_f32 v[168:169], v[152:153], v[104:105], v[168:169] op_sel_hi:[1,0,1]
	ds_read_b128 v[146:149], v192 offset:20480
	ds_read_b128 v[150:153], v192 offset:21504
	s_waitcnt lgkmcnt(6)
	v_pk_fma_f32 v[162:163], v[154:155], v[104:105], v[162:163] op_sel:[0,1,0] op_sel_hi:[1,1,1]
	v_pk_fma_f32 v[164:165], v[156:157], v[104:105], v[164:165] op_sel:[0,1,0] op_sel_hi:[1,1,1]
	v_pk_fma_f32 v[166:167], v[158:159], v[104:105], v[166:167] op_sel:[0,1,0] op_sel_hi:[1,1,1]
	v_pk_fma_f32 v[168:169], v[160:161], v[104:105], v[168:169] op_sel:[0,1,0] op_sel_hi:[1,1,1]
	ds_read_b128 v[154:157], v192 offset:22528
	ds_read_b128 v[158:161], v192 offset:23552
	s_waitcnt lgkmcnt(6)
	v_pk_fma_f32 v[162:163], v[130:131], v[106:107], v[162:163] op_sel_hi:[1,0,1]
	v_pk_fma_f32 v[164:165], v[132:133], v[106:107], v[164:165] op_sel_hi:[1,0,1]
	v_pk_fma_f32 v[166:167], v[134:135], v[106:107], v[166:167] op_sel_hi:[1,0,1]
	v_pk_fma_f32 v[168:169], v[136:137], v[106:107], v[168:169] op_sel_hi:[1,0,1]
	ds_read_b128 v[130:133], v192 offset:24576
	ds_read_b128 v[134:137], v192 offset:25600
	s_waitcnt lgkmcnt(6)
	v_pk_fma_f32 v[162:163], v[138:139], v[106:107], v[162:163] op_sel:[0,1,0] op_sel_hi:[1,1,1]
	v_pk_fma_f32 v[164:165], v[140:141], v[106:107], v[164:165] op_sel:[0,1,0] op_sel_hi:[1,1,1]
	v_pk_fma_f32 v[166:167], v[142:143], v[106:107], v[166:167] op_sel:[0,1,0] op_sel_hi:[1,1,1]
	v_pk_fma_f32 v[168:169], v[144:145], v[106:107], v[168:169] op_sel:[0,1,0] op_sel_hi:[1,1,1]
	ds_read_b128 v[138:141], v192 offset:26624
	ds_read_b128 v[142:145], v192 offset:27648
	s_waitcnt lgkmcnt(6)
	v_pk_fma_f32 v[162:163], v[146:147], v[108:109], v[162:163] op_sel_hi:[1,0,1]
	v_pk_fma_f32 v[164:165], v[148:149], v[108:109], v[164:165] op_sel_hi:[1,0,1]
	v_pk_fma_f32 v[166:167], v[150:151], v[108:109], v[166:167] op_sel_hi:[1,0,1]
	v_pk_fma_f32 v[168:169], v[152:153], v[108:109], v[168:169] op_sel_hi:[1,0,1]
	ds_read_b128 v[146:149], v192 offset:28672
	ds_read_b128 v[150:153], v192 offset:29696
	s_waitcnt lgkmcnt(6)
	v_pk_fma_f32 v[162:163], v[154:155], v[108:109], v[162:163] op_sel:[0,1,0] op_sel_hi:[1,1,1]
	v_pk_fma_f32 v[164:165], v[156:157], v[108:109], v[164:165] op_sel:[0,1,0] op_sel_hi:[1,1,1]
	v_pk_fma_f32 v[166:167], v[158:159], v[108:109], v[166:167] op_sel:[0,1,0] op_sel_hi:[1,1,1]
	v_pk_fma_f32 v[168:169], v[160:161], v[108:109], v[168:169] op_sel:[0,1,0] op_sel_hi:[1,1,1]
	ds_read_b128 v[154:157], v192 offset:30720
	ds_read_b128 v[158:161], v192 offset:31744
	s_waitcnt lgkmcnt(6)
	v_pk_fma_f32 v[162:163], v[130:131], v[110:111], v[162:163] op_sel_hi:[1,0,1]
	v_pk_fma_f32 v[164:165], v[132:133], v[110:111], v[164:165] op_sel_hi:[1,0,1]
	v_pk_fma_f32 v[166:167], v[134:135], v[110:111], v[166:167] op_sel_hi:[1,0,1]
	v_pk_fma_f32 v[168:169], v[136:137], v[110:111], v[168:169] op_sel_hi:[1,0,1]
	ds_read_b128 v[130:133], v192 offset:32768
	ds_read_b128 v[134:137], v192 offset:33792
	s_waitcnt lgkmcnt(6)
	v_pk_fma_f32 v[162:163], v[138:139], v[110:111], v[162:163] op_sel:[0,1,0] op_sel_hi:[1,1,1]
	v_pk_fma_f32 v[164:165], v[140:141], v[110:111], v[164:165] op_sel:[0,1,0] op_sel_hi:[1,1,1]
	v_pk_fma_f32 v[166:167], v[142:143], v[110:111], v[166:167] op_sel:[0,1,0] op_sel_hi:[1,1,1]
	v_pk_fma_f32 v[168:169], v[144:145], v[110:111], v[168:169] op_sel:[0,1,0] op_sel_hi:[1,1,1]
	ds_read_b128 v[138:141], v192 offset:34816
	ds_read_b128 v[142:145], v192 offset:35840
	s_waitcnt lgkmcnt(6)
	v_pk_fma_f32 v[162:163], v[146:147], v[112:113], v[162:163] op_sel_hi:[1,0,1]
	v_pk_fma_f32 v[164:165], v[148:149], v[112:113], v[164:165] op_sel_hi:[1,0,1]
	v_pk_fma_f32 v[166:167], v[150:151], v[112:113], v[166:167] op_sel_hi:[1,0,1]
	v_pk_fma_f32 v[168:169], v[152:153], v[112:113], v[168:169] op_sel_hi:[1,0,1]
	ds_read_b128 v[146:149], v192 offset:36864
	ds_read_b128 v[150:153], v192 offset:37888
	s_waitcnt lgkmcnt(6)
	v_pk_fma_f32 v[162:163], v[154:155], v[112:113], v[162:163] op_sel:[0,1,0] op_sel_hi:[1,1,1]
	v_pk_fma_f32 v[164:165], v[156:157], v[112:113], v[164:165] op_sel:[0,1,0] op_sel_hi:[1,1,1]
	v_pk_fma_f32 v[166:167], v[158:159], v[112:113], v[166:167] op_sel:[0,1,0] op_sel_hi:[1,1,1]
	v_pk_fma_f32 v[168:169], v[160:161], v[112:113], v[168:169] op_sel:[0,1,0] op_sel_hi:[1,1,1]
	ds_read_b128 v[154:157], v192 offset:38912
	ds_read_b128 v[158:161], v192 offset:39936
	s_waitcnt lgkmcnt(6)
	v_pk_fma_f32 v[162:163], v[130:131], v[114:115], v[162:163] op_sel_hi:[1,0,1]
	v_pk_fma_f32 v[164:165], v[132:133], v[114:115], v[164:165] op_sel_hi:[1,0,1]
	v_pk_fma_f32 v[166:167], v[134:135], v[114:115], v[166:167] op_sel_hi:[1,0,1]
	v_pk_fma_f32 v[168:169], v[136:137], v[114:115], v[168:169] op_sel_hi:[1,0,1]
	ds_read_b128 v[130:133], v192 offset:40960
	ds_read_b128 v[134:137], v192 offset:41984
	s_waitcnt lgkmcnt(6)
	v_pk_fma_f32 v[162:163], v[138:139], v[114:115], v[162:163] op_sel:[0,1,0] op_sel_hi:[1,1,1]
	v_pk_fma_f32 v[164:165], v[140:141], v[114:115], v[164:165] op_sel:[0,1,0] op_sel_hi:[1,1,1]
	v_pk_fma_f32 v[166:167], v[142:143], v[114:115], v[166:167] op_sel:[0,1,0] op_sel_hi:[1,1,1]
	v_pk_fma_f32 v[168:169], v[144:145], v[114:115], v[168:169] op_sel:[0,1,0] op_sel_hi:[1,1,1]
	ds_read_b128 v[138:141], v192 offset:43008
	ds_read_b128 v[142:145], v192 offset:44032
	s_waitcnt lgkmcnt(6)
	v_pk_fma_f32 v[162:163], v[146:147], v[116:117], v[162:163] op_sel_hi:[1,0,1]
	v_pk_fma_f32 v[164:165], v[148:149], v[116:117], v[164:165] op_sel_hi:[1,0,1]
	v_pk_fma_f32 v[166:167], v[150:151], v[116:117], v[166:167] op_sel_hi:[1,0,1]
	v_pk_fma_f32 v[168:169], v[152:153], v[116:117], v[168:169] op_sel_hi:[1,0,1]
	ds_read_b128 v[146:149], v192 offset:45056
	ds_read_b128 v[150:153], v192 offset:46080
	s_waitcnt lgkmcnt(6)
	v_pk_fma_f32 v[162:163], v[154:155], v[116:117], v[162:163] op_sel:[0,1,0] op_sel_hi:[1,1,1]
	v_pk_fma_f32 v[164:165], v[156:157], v[116:117], v[164:165] op_sel:[0,1,0] op_sel_hi:[1,1,1]
	v_pk_fma_f32 v[166:167], v[158:159], v[116:117], v[166:167] op_sel:[0,1,0] op_sel_hi:[1,1,1]
	v_pk_fma_f32 v[168:169], v[160:161], v[116:117], v[168:169] op_sel:[0,1,0] op_sel_hi:[1,1,1]
	ds_read_b128 v[154:157], v192 offset:47104
	ds_read_b128 v[158:161], v192 offset:48128
	s_waitcnt lgkmcnt(6)
	v_pk_fma_f32 v[162:163], v[130:131], v[118:119], v[162:163] op_sel_hi:[1,0,1]
	v_pk_fma_f32 v[164:165], v[132:133], v[118:119], v[164:165] op_sel_hi:[1,0,1]
	v_pk_fma_f32 v[166:167], v[134:135], v[118:119], v[166:167] op_sel_hi:[1,0,1]
	v_pk_fma_f32 v[168:169], v[136:137], v[118:119], v[168:169] op_sel_hi:[1,0,1]
	ds_read_b128 v[130:133], v192 offset:49152
	ds_read_b128 v[134:137], v192 offset:50176
	s_waitcnt lgkmcnt(6)
	v_pk_fma_f32 v[162:163], v[138:139], v[118:119], v[162:163] op_sel:[0,1,0] op_sel_hi:[1,1,1]
	v_pk_fma_f32 v[164:165], v[140:141], v[118:119], v[164:165] op_sel:[0,1,0] op_sel_hi:[1,1,1]
	v_pk_fma_f32 v[166:167], v[142:143], v[118:119], v[166:167] op_sel:[0,1,0] op_sel_hi:[1,1,1]
	v_pk_fma_f32 v[168:169], v[144:145], v[118:119], v[168:169] op_sel:[0,1,0] op_sel_hi:[1,1,1]
	ds_read_b128 v[138:141], v192 offset:51200
	ds_read_b128 v[142:145], v192 offset:52224
	s_waitcnt lgkmcnt(6)
	v_pk_fma_f32 v[162:163], v[146:147], v[120:121], v[162:163] op_sel_hi:[1,0,1]
	v_pk_fma_f32 v[164:165], v[148:149], v[120:121], v[164:165] op_sel_hi:[1,0,1]
	v_pk_fma_f32 v[166:167], v[150:151], v[120:121], v[166:167] op_sel_hi:[1,0,1]
	v_pk_fma_f32 v[168:169], v[152:153], v[120:121], v[168:169] op_sel_hi:[1,0,1]
	ds_read_b128 v[146:149], v192 offset:53248
	ds_read_b128 v[150:153], v192 offset:54272
	s_waitcnt lgkmcnt(6)
	v_pk_fma_f32 v[162:163], v[154:155], v[120:121], v[162:163] op_sel:[0,1,0] op_sel_hi:[1,1,1]
	v_pk_fma_f32 v[164:165], v[156:157], v[120:121], v[164:165] op_sel:[0,1,0] op_sel_hi:[1,1,1]
	v_pk_fma_f32 v[166:167], v[158:159], v[120:121], v[166:167] op_sel:[0,1,0] op_sel_hi:[1,1,1]
	v_pk_fma_f32 v[168:169], v[160:161], v[120:121], v[168:169] op_sel:[0,1,0] op_sel_hi:[1,1,1]
	ds_read_b128 v[154:157], v192 offset:55296
	ds_read_b128 v[158:161], v192 offset:56320
	s_waitcnt lgkmcnt(6)
	v_pk_fma_f32 v[162:163], v[130:131], v[122:123], v[162:163] op_sel_hi:[1,0,1]
	v_pk_fma_f32 v[164:165], v[132:133], v[122:123], v[164:165] op_sel_hi:[1,0,1]
	v_pk_fma_f32 v[166:167], v[134:135], v[122:123], v[166:167] op_sel_hi:[1,0,1]
	v_pk_fma_f32 v[168:169], v[136:137], v[122:123], v[168:169] op_sel_hi:[1,0,1]
	ds_read_b128 v[130:133], v192 offset:57344
	ds_read_b128 v[134:137], v192 offset:58368
	s_waitcnt lgkmcnt(6)
	v_pk_fma_f32 v[162:163], v[138:139], v[122:123], v[162:163] op_sel:[0,1,0] op_sel_hi:[1,1,1]
	v_pk_fma_f32 v[164:165], v[140:141], v[122:123], v[164:165] op_sel:[0,1,0] op_sel_hi:[1,1,1]
	v_pk_fma_f32 v[166:167], v[142:143], v[122:123], v[166:167] op_sel:[0,1,0] op_sel_hi:[1,1,1]
	v_pk_fma_f32 v[168:169], v[144:145], v[122:123], v[168:169] op_sel:[0,1,0] op_sel_hi:[1,1,1]
	ds_read_b128 v[138:141], v192 offset:59392
	ds_read_b128 v[142:145], v192 offset:60416
	s_waitcnt lgkmcnt(6)
	v_pk_fma_f32 v[162:163], v[146:147], v[124:125], v[162:163] op_sel_hi:[1,0,1]
	v_pk_fma_f32 v[164:165], v[148:149], v[124:125], v[164:165] op_sel_hi:[1,0,1]
	v_pk_fma_f32 v[166:167], v[150:151], v[124:125], v[166:167] op_sel_hi:[1,0,1]
	v_pk_fma_f32 v[168:169], v[152:153], v[124:125], v[168:169] op_sel_hi:[1,0,1]
	ds_read_b128 v[146:149], v192 offset:61440
	ds_read_b128 v[150:153], v192 offset:62464
	s_waitcnt lgkmcnt(6)
	v_pk_fma_f32 v[162:163], v[154:155], v[124:125], v[162:163] op_sel:[0,1,0] op_sel_hi:[1,1,1]
	v_pk_fma_f32 v[164:165], v[156:157], v[124:125], v[164:165] op_sel:[0,1,0] op_sel_hi:[1,1,1]
	v_pk_fma_f32 v[166:167], v[158:159], v[124:125], v[166:167] op_sel:[0,1,0] op_sel_hi:[1,1,1]
	v_pk_fma_f32 v[168:169], v[160:161], v[124:125], v[168:169] op_sel:[0,1,0] op_sel_hi:[1,1,1]
	ds_read_b128 v[154:157], v192 offset:63488
	ds_read_b128 v[158:161], v192 offset:64512
	s_waitcnt lgkmcnt(6)
	v_pk_fma_f32 v[162:163], v[130:131], v[126:127], v[162:163] op_sel_hi:[1,0,1]
	v_pk_fma_f32 v[164:165], v[132:133], v[126:127], v[164:165] op_sel_hi:[1,0,1]
	v_pk_fma_f32 v[166:167], v[134:135], v[126:127], v[166:167] op_sel_hi:[1,0,1]
	v_pk_fma_f32 v[168:169], v[136:137], v[126:127], v[168:169] op_sel_hi:[1,0,1]
	s_waitcnt lgkmcnt(4)
	v_pk_fma_f32 v[162:163], v[138:139], v[126:127], v[162:163] op_sel:[0,1,0] op_sel_hi:[1,1,1]
	v_pk_fma_f32 v[164:165], v[140:141], v[126:127], v[164:165] op_sel:[0,1,0] op_sel_hi:[1,1,1]
	v_pk_fma_f32 v[166:167], v[142:143], v[126:127], v[166:167] op_sel:[0,1,0] op_sel_hi:[1,1,1]
	v_pk_fma_f32 v[168:169], v[144:145], v[126:127], v[168:169] op_sel:[0,1,0] op_sel_hi:[1,1,1]
	s_waitcnt lgkmcnt(2)
	v_pk_fma_f32 v[162:163], v[146:147], v[128:129], v[162:163] op_sel_hi:[1,0,1]
	v_pk_fma_f32 v[164:165], v[148:149], v[128:129], v[164:165] op_sel_hi:[1,0,1]
	v_pk_fma_f32 v[166:167], v[150:151], v[128:129], v[166:167] op_sel_hi:[1,0,1]
	v_pk_fma_f32 v[168:169], v[152:153], v[128:129], v[168:169] op_sel_hi:[1,0,1]
	s_waitcnt lgkmcnt(0)
	v_pk_fma_f32 v[162:163], v[154:155], v[128:129], v[162:163] op_sel:[0,1,0] op_sel_hi:[1,1,1]
	v_pk_fma_f32 v[164:165], v[156:157], v[128:129], v[164:165] op_sel:[0,1,0] op_sel_hi:[1,1,1]
	v_pk_fma_f32 v[166:167], v[158:159], v[128:129], v[166:167] op_sel:[0,1,0] op_sel_hi:[1,1,1]
	v_pk_fma_f32 v[168:169], v[160:161], v[128:129], v[168:169] op_sel:[0,1,0] op_sel_hi:[1,1,1]
	s_nop 1
	v_add_f32_dpp v162, v162, v162 quad_perm:[1,0,3,2] row_mask:0xf bank_mask:0xf
	v_add_f32_dpp v163, v163, v163 quad_perm:[1,0,3,2] row_mask:0xf bank_mask:0xf
	v_add_f32_dpp v164, v164, v164 quad_perm:[1,0,3,2] row_mask:0xf bank_mask:0xf
	v_add_f32_dpp v165, v165, v165 quad_perm:[1,0,3,2] row_mask:0xf bank_mask:0xf
	v_add_f32_dpp v166, v166, v166 quad_perm:[1,0,3,2] row_mask:0xf bank_mask:0xf
	v_add_f32_dpp v167, v167, v167 quad_perm:[1,0,3,2] row_mask:0xf bank_mask:0xf
	v_add_f32_dpp v168, v168, v168 quad_perm:[1,0,3,2] row_mask:0xf bank_mask:0xf
	v_add_f32_dpp v169, v169, v169 quad_perm:[1,0,3,2] row_mask:0xf bank_mask:0xf
	v_add_f32_dpp v162, v162, v162 quad_perm:[2,3,0,1] row_mask:0xf bank_mask:0xf
	v_add_f32_dpp v163, v163, v163 quad_perm:[2,3,0,1] row_mask:0xf bank_mask:0xf
	v_add_f32_dpp v164, v164, v164 quad_perm:[2,3,0,1] row_mask:0xf bank_mask:0xf
	v_add_f32_dpp v165, v165, v165 quad_perm:[2,3,0,1] row_mask:0xf bank_mask:0xf
	v_add_f32_dpp v166, v166, v166 quad_perm:[2,3,0,1] row_mask:0xf bank_mask:0xf
	v_add_f32_dpp v167, v167, v167 quad_perm:[2,3,0,1] row_mask:0xf bank_mask:0xf
	v_add_f32_dpp v168, v168, v168 quad_perm:[2,3,0,1] row_mask:0xf bank_mask:0xf
	v_add_f32_dpp v169, v169, v169 quad_perm:[2,3,0,1] row_mask:0xf bank_mask:0xf
	v_add_f32_dpp v162, v162, v162 row_half_mirror row_mask:0xf bank_mask:0xf
	v_add_f32_dpp v163, v163, v163 row_half_mirror row_mask:0xf bank_mask:0xf
	v_add_f32_dpp v164, v164, v164 row_half_mirror row_mask:0xf bank_mask:0xf
	v_add_f32_dpp v165, v165, v165 row_half_mirror row_mask:0xf bank_mask:0xf
	v_add_f32_dpp v166, v166, v166 row_half_mirror row_mask:0xf bank_mask:0xf
	v_add_f32_dpp v167, v167, v167 row_half_mirror row_mask:0xf bank_mask:0xf
	v_add_f32_dpp v168, v168, v168 row_half_mirror row_mask:0xf bank_mask:0xf
	v_add_f32_dpp v169, v169, v169 row_half_mirror row_mask:0xf bank_mask:0xf
	v_add_f32_dpp v162, v162, v162 row_mirror row_mask:0xf bank_mask:0xf
	v_add_f32_dpp v163, v163, v163 row_mirror row_mask:0xf bank_mask:0xf
	v_add_f32_dpp v164, v164, v164 row_mirror row_mask:0xf bank_mask:0xf
	v_add_f32_dpp v165, v165, v165 row_mirror row_mask:0xf bank_mask:0xf
	v_add_f32_dpp v166, v166, v166 row_mirror row_mask:0xf bank_mask:0xf
	v_add_f32_dpp v167, v167, v167 row_mirror row_mask:0xf bank_mask:0xf
	v_add_f32_dpp v168, v168, v168 row_mirror row_mask:0xf bank_mask:0xf
	v_add_f32_dpp v169, v169, v169 row_mirror row_mask:0xf bank_mask:0xf
	v_mov_b32_e32 v170, v162
	v_mov_b32_e32 v171, v163
	v_mov_b32_e32 v172, v164
	v_mov_b32_e32 v173, v165
	v_mov_b32_e32 v174, v166
	v_mov_b32_e32 v175, v167
	v_mov_b32_e32 v176, v168
	v_mov_b32_e32 v177, v169
	v_permlane16_swap_b32 v170, v162
	v_permlane16_swap_b32 v171, v163
	v_permlane16_swap_b32 v172, v164
	v_permlane16_swap_b32 v173, v165
	v_permlane16_swap_b32 v174, v166
	v_permlane16_swap_b32 v175, v167
	v_permlane16_swap_b32 v176, v168
	v_permlane16_swap_b32 v177, v169
	v_add_f32_e32 v162, v162, v170
	v_add_f32_e32 v163, v163, v171
	v_add_f32_e32 v164, v164, v172
	v_add_f32_e32 v165, v165, v173
	v_add_f32_e32 v166, v166, v174
	v_add_f32_e32 v167, v167, v175
	v_add_f32_e32 v168, v168, v176
	v_add_f32_e32 v169, v169, v177
	v_mov_b32_e32 v170, v162
	v_mov_b32_e32 v171, v163
	v_mov_b32_e32 v172, v164
	v_mov_b32_e32 v173, v165
	v_mov_b32_e32 v174, v166
	v_mov_b32_e32 v175, v167
	v_mov_b32_e32 v176, v168
	v_mov_b32_e32 v177, v169
	v_permlane32_swap_b32 v170, v162
	v_permlane32_swap_b32 v171, v163
	v_permlane32_swap_b32 v172, v164
	v_permlane32_swap_b32 v173, v165
	v_permlane32_swap_b32 v174, v166
	v_permlane32_swap_b32 v175, v167
	v_permlane32_swap_b32 v176, v168
	v_permlane32_swap_b32 v177, v169
	v_add_f32_e32 v162, v162, v170
	v_add_f32_e32 v163, v163, v171
	v_add_f32_e32 v164, v164, v172
	v_add_f32_e32 v165, v165, v173
	v_add_f32_e32 v166, v166, v174
	v_add_f32_e32 v167, v167, v175
	v_add_f32_e32 v168, v168, v176
	v_add_f32_e32 v169, v169, v177
	v_readfirstlane_b32 s98, v162
	v_readfirstlane_b32 s99, v163
	v_readfirstlane_b32 s100, v164
	v_readfirstlane_b32 s101, v165
	v_writelane_b32 v230, s98, 56
	v_writelane_b32 v230, s99, 57
	v_writelane_b32 v230, s100, 58
	v_writelane_b32 v230, s101, 59
	v_readfirstlane_b32 s98, v166
	v_readfirstlane_b32 s99, v167
	v_readfirstlane_b32 s100, v168
	v_readfirstlane_b32 s101, v169
	v_writelane_b32 v230, s98, 60
	v_writelane_b32 v230, s99, 61
	v_writelane_b32 v230, s100, 62
	v_writelane_b32 v230, s101, 63
	v_add_f32_e32 v223, v230, v196
	v_mul_f32_e64 v225, |v223|, s24
	v_exp_f32_e32 v210, v225
	v_min_f32_e32 v225, 0, v223
	s_nop 0
	v_add_f32_e32 v211, 1.0, v210
	v_add_f32_e32 v212, -1.0, v211
	v_frexp_mant_f32_e32 v213, v211
	v_cvt_f64_f32_e32 v[208:209], v211
	v_sub_f32_e32 v214, v212, v211
	v_frexp_exp_i32_f64_e32 v208, v[208:209]
	v_cmp_gt_f32_e32 vcc, s25, v213
	v_sub_f32_e32 v212, v210, v212
	v_add_f32_e32 v209, 1.0, v214
	v_subbrev_co_u32_e32 v208, vcc, 0, v208, vcc
	v_add_f32_e32 v209, v212, v209
	v_sub_u32_e32 v212, 0, v208
	v_cvt_f32_i32_e32 v208, v208
	v_ldexp_f32 v211, v211, v212
	v_ldexp_f32 v209, v209, v212
	v_add_f32_e32 v212, -1.0, v211
	v_add_f32_e32 v213, 1.0, v211
	v_add_f32_e32 v214, 1.0, v212
	v_add_f32_e32 v215, -1.0, v213
	v_sub_f32_e32 v214, v211, v214
	v_sub_f32_e32 v211, v211, v215
	v_mul_f32_e32 v215, 0x3f317218, v208
	v_add_f32_e32 v214, v209, v214
	v_add_f32_e32 v209, v209, v211
	v_fma_f32 v211, v208, s28, -v215
	v_add_f32_e32 v216, v212, v214
	v_add_f32_e32 v217, v213, v209
	v_fmac_f32_e32 v211, 0xb102e308, v208
	v_sub_f32_e32 v208, v216, v212
	v_sub_f32_e32 v212, v217, v213
	v_rcp_f32_e32 v213, v217
	v_add_f32_e32 v218, v215, v211
	v_sub_f32_e32 v209, v209, v212
	v_sub_f32_e32 v212, v218, v215
	v_sub_f32_e32 v211, v211, v212
	v_mul_f32_e32 v212, v216, v213
	v_sub_f32_e32 v208, v214, v208
	v_mul_f32_e32 v214, v217, v212
	v_fma_f32 v215, v212, v217, -v214
	v_fmac_f32_e32 v215, v212, v209
	v_add_f32_e32 v219, v214, v215
	v_sub_f32_e32 v220, v216, v219
	v_sub_f32_e32 v214, v219, v214
	v_sub_f32_e32 v216, v216, v220
	v_sub_f32_e32 v214, v214, v215
	v_sub_f32_e32 v215, v216, v219
	v_add_f32_e32 v208, v208, v215
	v_add_f32_e32 v208, v214, v208
	v_add_f32_e32 v214, v220, v208
	v_mul_f32_e32 v215, v213, v214
	v_sub_f32_e32 v216, v220, v214
	v_mul_f32_e32 v219, v217, v215
	v_add_f32_e32 v208, v208, v216
	v_add_f32_e32 v216, v212, v215
	v_fma_f32 v217, v215, v217, -v219
	v_sub_f32_e32 v212, v216, v212
	v_fmac_f32_e32 v217, v215, v209
	v_sub_f32_e32 v209, v215, v212
	v_add_f32_e32 v212, v219, v217
	v_sub_f32_e32 v215, v212, v219
	v_sub_f32_e32 v219, v214, v212
	v_sub_f32_e32 v214, v214, v219
	v_sub_f32_e32 v212, v214, v212
	v_sub_f32_e32 v215, v215, v217
	v_add_f32_e32 v208, v208, v212
	v_add_f32_e32 v208, v215, v208
	v_add_f32_e32 v208, v219, v208
	v_mul_f32_e32 v208, v213, v208
	v_add_f32_e32 v208, v209, v208
	v_add_f32_e32 v209, v216, v208
	v_mul_f32_e32 v212, v209, v209
	v_fmamk_f32 v215, v212, 0x3e9b6dac, v242
	v_sub_f32_e32 v213, v209, v216
	v_ldexp_f32 v214, v209, 1
	v_mul_f32_e32 v209, v209, v212
	v_fmaak_f32 v212, v212, v215, 0x3f2aaada
	v_mul_f32_e32 v209, v209, v212
	v_add_f32_e32 v212, v214, v209
	v_sub_f32_e32 v208, v208, v213
	v_sub_f32_e32 v213, v212, v214
	v_ldexp_f32 v208, v208, 1
	v_sub_f32_e32 v209, v209, v213
	v_add_f32_e32 v208, v208, v209
	v_add_f32_e32 v209, v212, v208
	v_sub_f32_e32 v212, v209, v212
	v_add_f32_e32 v213, v218, v209
	v_sub_f32_e32 v208, v208, v212
	v_sub_f32_e32 v212, v213, v218
	v_sub_f32_e32 v214, v213, v212
	v_sub_f32_e32 v209, v209, v212
	v_add_f32_e32 v212, v211, v208
	v_sub_f32_e32 v214, v218, v214
	v_sub_f32_e32 v215, v212, v211
	v_add_f32_e32 v209, v209, v214
	v_sub_f32_e32 v214, v212, v215
	v_sub_f32_e32 v208, v208, v215
	v_sub_f32_e32 v211, v211, v214
	v_add_f32_e32 v209, v212, v209
	v_add_f32_e32 v208, v208, v211
	v_add_f32_e32 v211, v213, v209
	v_sub_f32_e32 v212, v211, v213
	v_sub_f32_e32 v209, v209, v212
	v_add_f32_e32 v208, v208, v209
	v_add_f32_e32 v208, v211, v208
	v_cmp_neq_f32_e32 vcc, s29, v210
	s_nop 0
	s_nop 0
	v_cndmask_b32_e32 v208, v243, v208, vcc
	v_cmp_ngt_f32_e32 vcc, -1.0, v210
	s_nop 1
	v_cndmask_b32_e32 v208, v244, v208, vcc
	v_cmp_neq_f32_e32 vcc, -1.0, v210
	s_nop 1
	v_cndmask_b32_e32 v208, v245, v208, vcc
	v_cmp_lt_f32_e64 vcc, |v210|, s30
	s_nop 1
	v_cndmask_b32_e32 v208, v208, v210, vcc
	v_sub_f32_e32 v225, v225, v208
	v_lshrrev_b32_e32 v231, 3, v251
	v_and_b32_e32 v232, 7, v251
	v_lshlrev_b32_e32 v233, 13, v231
	v_lshl_add_u32 v233, v232, 15, v233
	v_lshl_add_u32 v233, v250, 2, v233
	v_cmp_lt_u32_e32 vcc, 3, v231
	v_mov_b32_e32 v234, 0x38000
	s_nop 0
	v_cndmask_b32_e32 v234, 0, v234, vcc
	v_add_u32_e32 v233, v233, v234
	global_store_dword v233, v225, s[74:75]
